# K-loop counter/pointer updates moved in front of the loop-back barrier; ssq row reduction via permlane16/32 swaps instead of ds_bpermute (on top of saddr LDS-DMA + f32 store regrouping)
# baseline (speedup 1.0000x reference)
; #define PG8_STAGE(bufoff, gbase, voff) do { _Pragma("unroll") for (int _i = 0; _i < 2; ++_i) \
;         __builtin_amdgcn_global_load_lds((const unsigned*)((const char*)(gbase) + (voff)[_i]), (PG8_LAS unsigned*)(lds + (bufoff) + ldsw + _i * 8192), 16, 0, 0); } while (0)
; #define PG8_LDA(dst, b, h) do { _Pragma("unroll") for (int m = 0; m < 4; ++m) _Pragma("unroll") for (int k = 0; k < 2; ++k) dst[m][k] = *(const PG8_LAS bf16x8*)(lds + PG8_SA(b, h) + aoff + m * 2048 + k * 1024); } while (0)
; #define PG8_LDB(dst, b, h) do { _Pragma("unroll") for (int n = 0; n < 2; ++n) _Pragma("unroll") for (int k = 0; k < 2; ++k) dst[n][k] = *(const PG8_LAS bf16x8*)(lds + PG8_SB(b, h) + boff + n * 2048 + k * 1024); } while (0)
; #define PG8_MMA(ai, bj, At, Bt) do { __builtin_amdgcn_s_setprio(1); _Pragma("unroll") for (int m = 0; m < 4; ++m) _Pragma("unroll") for (int n = 0; n < 2; ++n) _Pragma("unroll") for (int k = 0; k < 2; ++k) \
;         acc[ai][bj][m][n] = __builtin_amdgcn_mfma_f32_16x16x32_bf16(Bt[n][k], At[m][k], acc[ai][bj][m][n], 0, 0, 0); __builtin_amdgcn_s_setprio(0); } while (0)
; #define PG8_WAIT_V(n) asm volatile("s_waitcnt vmcnt(" #n ")" ::: "memory")
; #define PG8_WAIT_L(n) asm volatile("s_waitcnt lgkmcnt(" #n ")" ::: "memory")
; #define PG8_BAR __builtin_amdgcn_s_barrier()
; #define PG8_SCHED __builtin_amdgcn_sched_barrier(0)
; template <class Epi, class Sched, bool ALIGN_EPI = false, bool SP2 = false>
; __device__ __forceinline__ void gemm_phase(PG8_LAS unsigned char* lds, const Gemm g, const Sched& S, const Epi& E) {
;     ...
;             PG8_LDB(B0, 0, 0); PG8_LDB(B1, 0, 1); PG8_SCHED; PG8_LDA(At, 0, 0); PG8_STAGE(PG8_SA(1, 1), a1 + hstep, voffA);
;             PG8_WAIT_V(8); PG8_WAIT_L(0); PG8_BAR; PG8_MMA(0, 0, At, B0); PG8_MMA(0, 1, At, B1); PG8_BAR; PG8_SCHED;
;             PG8_LDA(At, 0, 1); PG8_STAGE(PG8_SB(0, 0), b2, voffB); PG8_STAGE(PG8_SB(0, 1), b2 + hstep, voffB); PG8_STAGE(PG8_SA(0, 0), a2, voffA);
;             PG8_WAIT_V(8); PG8_WAIT_L(0); PG8_BAR; PG8_MMA(1, 0, At, B0); PG8_MMA(1, 1, At, B1); PG8_BAR; PG8_SCHED;
.LBB0_130:
	s_nop 0
	ds_read_b128 v[128:131], v171
	ds_read_b128 v[132:135], v171 offset:1024
	ds_read_b128 v[136:139], v171 offset:2048
	ds_read_b128 v[140:143], v171 offset:3072
	ds_read_b128 v[160:163], v172
	ds_read_b128 v[176:179], v172 offset:1024
	ds_read_b128 v[180:183], v172 offset:2048
	ds_read_b128 v[184:187], v172 offset:3072
	s_add_u32 s28, s26, 0xfffc0080
	s_addc_u32 s29, s27, -1
	s_cmp_eq_u32 s54, 12
	s_cselect_b32 s31, s17, s29
	s_cselect_b32 s30, s50, s28
	s_cselect_b32 s29, s15, s53
	s_cselect_b32 s28, s51, s52
	s_add_i32 m0, s25, 0xc000
	ds_read_b128 v[188:191], v173
	ds_read_b128 v[192:195], v173 offset:1024
	ds_read_b128 v[196:199], v173 offset:2048
	ds_read_b128 v[200:203], v173 offset:3072
	ds_read_b128 v[204:207], v173 offset:4096
	ds_read_b128 v[208:211], v173 offset:5120
	ds_read_b128 v[212:215], v173 offset:6144
	ds_read_b128 v[216:219], v173 offset:7168
	global_load_lds_dwordx4 v152, s[26:27]
	s_add_i32 m0, s25, 0xe000
	s_nop 0
	global_load_lds_dwordx4 v154, s[26:27]
	s_waitcnt vmcnt(8)
	s_waitcnt lgkmcnt(0)
	s_barrier
	s_setprio 1
	s_waitcnt lgkmcnt(0)
	v_mfma_f32_16x16x32_bf16 v[124:127], v[128:131], v[188:191], v[124:127]
	v_mfma_f32_16x16x32_bf16 v[120:123], v[136:139], v[188:191], v[120:123]
	v_mfma_f32_16x16x32_bf16 v[116:119], v[128:131], v[196:199], v[116:119]
	v_mfma_f32_16x16x32_bf16 v[108:111], v[136:139], v[196:199], v[108:111]
	v_mfma_f32_16x16x32_bf16 v[96:99], v[128:131], v[204:207], v[96:99]
	v_mfma_f32_16x16x32_bf16 v[88:91], v[136:139], v[204:207], v[88:91]
	v_mfma_f32_16x16x32_bf16 v[84:87], v[128:131], v[212:215], v[84:87]
	v_mfma_f32_16x16x32_bf16 v[76:79], v[136:139], v[212:215], v[76:79]
	v_mfma_f32_16x16x32_bf16 v[124:127], v[132:135], v[192:195], v[124:127]
	v_mfma_f32_16x16x32_bf16 v[120:123], v[140:143], v[192:195], v[120:123]
	v_mfma_f32_16x16x32_bf16 v[116:119], v[132:135], v[200:203], v[116:119]
	v_mfma_f32_16x16x32_bf16 v[108:111], v[140:143], v[200:203], v[108:111]
	v_mfma_f32_16x16x32_bf16 v[96:99], v[132:135], v[208:211], v[96:99]
	v_mfma_f32_16x16x32_bf16 v[88:91], v[140:143], v[208:211], v[88:91]
	v_mfma_f32_16x16x32_bf16 v[84:87], v[132:135], v[216:219], v[84:87]
	v_mfma_f32_16x16x32_bf16 v[76:79], v[140:143], v[216:219], v[76:79]
	s_setprio 0
	s_setprio 1
	v_mfma_f32_16x16x32_bf16 v[112:115], v[160:163], v[188:191], v[112:115]
	v_mfma_f32_16x16x32_bf16 v[104:107], v[180:183], v[188:191], v[104:107]
	v_mfma_f32_16x16x32_bf16 v[100:103], v[160:163], v[196:199], v[100:103]
	v_mfma_f32_16x16x32_bf16 v[92:95], v[180:183], v[196:199], v[92:95]
	v_mfma_f32_16x16x32_bf16 v[80:83], v[160:163], v[204:207], v[80:83]
	v_mfma_f32_16x16x32_bf16 v[72:75], v[180:183], v[204:207], v[72:75]
	v_mfma_f32_16x16x32_bf16 v[68:71], v[160:163], v[212:215], v[68:71]
	v_mfma_f32_16x16x32_bf16 v[64:67], v[180:183], v[212:215], v[64:67]
	v_mfma_f32_16x16x32_bf16 v[112:115], v[176:179], v[192:195], v[112:115]
	v_mfma_f32_16x16x32_bf16 v[104:107], v[184:187], v[192:195], v[104:107]
	v_mfma_f32_16x16x32_bf16 v[100:103], v[176:179], v[200:203], v[100:103]
	v_mfma_f32_16x16x32_bf16 v[92:95], v[184:187], v[200:203], v[92:95]
	v_mfma_f32_16x16x32_bf16 v[80:83], v[176:179], v[208:211], v[80:83]
	v_mfma_f32_16x16x32_bf16 v[72:75], v[184:187], v[208:211], v[72:75]
	v_mfma_f32_16x16x32_bf16 v[68:71], v[176:179], v[216:219], v[68:71]
	v_mfma_f32_16x16x32_bf16 v[64:67], v[184:187], v[216:219], v[64:67]
	s_setprio 0
	s_barrier
	s_add_i32 s55, s44, s22
	s_mov_b32 m0, s55
	ds_read_b128 v[188:191], v173 offset:16384
	ds_read_b128 v[192:195], v173 offset:17408
	ds_read_b128 v[196:199], v173 offset:18432
	ds_read_b128 v[200:203], v173 offset:19456
	ds_read_b128 v[204:207], v173 offset:20480
	ds_read_b128 v[208:211], v173 offset:21504
	ds_read_b128 v[212:215], v173 offset:22528
	ds_read_b128 v[216:219], v173 offset:23552
	global_load_lds_dwordx4 v146, s[28:29]
	s_add_i32 m0, s55, 0x2000
	s_add_u32 s56, s28, 0x40000
	s_addc_u32 s57, s29, 0
	s_add_i32 s55, s45, s22
	global_load_lds_dwordx4 v150, s[28:29]
	s_mov_b32 m0, s55
	s_nop 0
	global_load_lds_dwordx4 v146, s[56:57]
	s_add_i32 m0, s55, 0x2000
	s_nop 0
	global_load_lds_dwordx4 v150, s[56:57]
	s_mov_b32 m0, s25
	s_nop 0
	global_load_lds_dwordx4 v144, s[30:31]
	s_mov_b32 m0, s36
	s_nop 0
	global_load_lds_dwordx4 v148, s[30:31]
	s_waitcnt vmcnt(8)
	s_waitcnt lgkmcnt(0)
	s_barrier
	s_setprio 1
	s_waitcnt lgkmcnt(0)
	v_mfma_f32_16x16x32_bf16 v[60:63], v[128:131], v[188:191], v[60:63]
	v_mfma_f32_16x16x32_bf16 v[56:59], v[136:139], v[188:191], v[56:59]
	v_mfma_f32_16x16x32_bf16 v[52:55], v[128:131], v[196:199], v[52:55]
	v_mfma_f32_16x16x32_bf16 v[44:47], v[136:139], v[196:199], v[44:47]
	v_mfma_f32_16x16x32_bf16 v[32:35], v[128:131], v[204:207], v[32:35]
	v_mfma_f32_16x16x32_bf16 v[24:27], v[136:139], v[204:207], v[24:27]
	v_mfma_f32_16x16x32_bf16 v[20:23], v[128:131], v[212:215], v[20:23]
	v_mfma_f32_16x16x32_bf16 v[12:15], v[136:139], v[212:215], v[12:15]
	v_mfma_f32_16x16x32_bf16 v[60:63], v[132:135], v[192:195], v[60:63]
	v_mfma_f32_16x16x32_bf16 v[56:59], v[140:143], v[192:195], v[56:59]
	v_mfma_f32_16x16x32_bf16 v[52:55], v[132:135], v[200:203], v[52:55]
	v_mfma_f32_16x16x32_bf16 v[44:47], v[140:143], v[200:203], v[44:47]
	v_mfma_f32_16x16x32_bf16 v[32:35], v[132:135], v[208:211], v[32:35]
	v_mfma_f32_16x16x32_bf16 v[24:27], v[140:143], v[208:211], v[24:27]
	v_mfma_f32_16x16x32_bf16 v[20:23], v[132:135], v[216:219], v[20:23]
	v_mfma_f32_16x16x32_bf16 v[12:15], v[140:143], v[216:219], v[12:15]
	s_setprio 0
	s_setprio 1
	v_mfma_f32_16x16x32_bf16 v[48:51], v[160:163], v[188:191], v[48:51]
	v_mfma_f32_16x16x32_bf16 v[40:43], v[180:183], v[188:191], v[40:43]
	v_mfma_f32_16x16x32_bf16 v[36:39], v[160:163], v[196:199], v[36:39]
	v_mfma_f32_16x16x32_bf16 v[28:31], v[180:183], v[196:199], v[28:31]
	v_mfma_f32_16x16x32_bf16 v[16:19], v[160:163], v[204:207], v[16:19]
	v_mfma_f32_16x16x32_bf16 v[8:11], v[180:183], v[204:207], v[8:11]
	v_mfma_f32_16x16x32_bf16 v[4:7], v[160:163], v[212:215], v[4:7]
	v_mfma_f32_16x16x32_bf16 v[0:3], v[180:183], v[212:215], v[0:3]
	v_mfma_f32_16x16x32_bf16 v[48:51], v[176:179], v[192:195], v[48:51]
	v_mfma_f32_16x16x32_bf16 v[40:43], v[184:187], v[192:195], v[40:43]
	v_mfma_f32_16x16x32_bf16 v[36:39], v[176:179], v[200:203], v[36:39]
	v_mfma_f32_16x16x32_bf16 v[28:31], v[184:187], v[200:203], v[28:31]
	v_mfma_f32_16x16x32_bf16 v[16:19], v[176:179], v[208:211], v[16:19]
	v_mfma_f32_16x16x32_bf16 v[8:11], v[184:187], v[208:211], v[8:11]
	v_mfma_f32_16x16x32_bf16 v[4:7], v[176:179], v[216:219], v[4:7]
	v_mfma_f32_16x16x32_bf16 v[0:3], v[184:187], v[216:219], v[0:3]
	s_setprio 0
	s_barrier
; #define PG8_STAGE(bufoff, gbase, voff) do { _Pragma("unroll") for (int _i = 0; _i < 2; ++_i) \
;         __builtin_amdgcn_global_load_lds((const unsigned*)((const char*)(gbase) + (voff)[_i]), (PG8_LAS unsigned*)(lds + (bufoff) + ldsw + _i * 8192), 16, 0, 0); } while (0)
; #define PG8_LDA(dst, b, h) do { _Pragma("unroll") for (int m = 0; m < 4; ++m) _Pragma("unroll") for (int k = 0; k < 2; ++k) dst[m][k] = *(const PG8_LAS bf16x8*)(lds + PG8_SA(b, h) + aoff + m * 2048 + k * 1024); } while (0)
; #define PG8_LDB(dst, b, h) do { _Pragma("unroll") for (int n = 0; n < 2; ++n) _Pragma("unroll") for (int k = 0; k < 2; ++k) dst[n][k] = *(const PG8_LAS bf16x8*)(lds + PG8_SB(b, h) + boff + n * 2048 + k * 1024); } while (0)
; #define PG8_MMA(ai, bj, At, Bt) do { __builtin_amdgcn_s_setprio(1); _Pragma("unroll") for (int m = 0; m < 4; ++m) _Pragma("unroll") for (int n = 0; n < 2; ++n) _Pragma("unroll") for (int k = 0; k < 2; ++k) \
;         acc[ai][bj][m][n] = __builtin_amdgcn_mfma_f32_16x16x32_bf16(Bt[n][k], At[m][k], acc[ai][bj][m][n], 0, 0, 0); __builtin_amdgcn_s_setprio(0); } while (0)
; #define PG8_WAIT_V(n) asm volatile("s_waitcnt vmcnt(" #n ")" ::: "memory")
; #define PG8_WAIT_L(n) asm volatile("s_waitcnt lgkmcnt(" #n ")" ::: "memory")
; #define PG8_BAR __builtin_amdgcn_s_barrier()
; #define PG8_SCHED __builtin_amdgcn_sched_barrier(0)
; template <class Epi, class Sched, bool ALIGN_EPI = false, bool SP2 = false>
; __device__ __forceinline__ void gemm_phase(PG8_LAS unsigned char* lds, const Gemm g, const Sched& S, const Epi& E) {
;     ...
;         for (int t = 0; t < nt; t += 2) {
;             const bool last = (t == nt - 2);
;     ...
;             PG8_LDB(B0, 1, 0); PG8_LDB(B1, 1, 1); PG8_SCHED; PG8_LDA(At, 1, 0); PG8_STAGE(PG8_SA(0, 1), a2 + hstep, voffA);
;             PG8_WAIT_V(8); PG8_WAIT_L(0); PG8_BAR; PG8_MMA(0, 0, At, B0); PG8_MMA(0, 1, At, B1); PG8_BAR; PG8_SCHED;
;             PG8_LDA(At, 1, 1); PG8_STAGE(PG8_SB(1, 0), b3, voffB); PG8_STAGE(PG8_SB(1, 1), b3 + hstep, voffB); PG8_STAGE(PG8_SA(1, 0), a3, voffA);
;             PG8_WAIT_V(8); PG8_WAIT_L(0); PG8_BAR; PG8_MMA(1, 0, At, B0); PG8_MMA(1, 1, At, B1); PG8_BAR; PG8_SCHED;
	s_add_i32 s55, 0, 0x18000
	s_add_i32 s56, 0, 0x1c000
	v_add_u32_e32 v140, s55, v167
	v_add_u32_e32 v175, s56, v167
	ds_read_b128 v[128:131], v140
	ds_read_b128 v[132:135], v140 offset:1024
	ds_read_b128 v[136:139], v140 offset:2048
	ds_read_b128 v[140:143], v140 offset:3072
	ds_read_b128 v[160:163], v175
	ds_read_b128 v[176:179], v175 offset:1024
	ds_read_b128 v[180:183], v175 offset:2048
	ds_read_b128 v[184:187], v175 offset:3072
	s_add_u32 s30, s30, 0x40000
	s_addc_u32 s31, s31, 0
	s_mov_b32 m0, s37
	ds_read_b128 v[188:191], v173 offset:32768
	ds_read_b128 v[192:195], v173 offset:33792
	ds_read_b128 v[196:199], v173 offset:34816
	ds_read_b128 v[200:203], v173 offset:35840
	ds_read_b128 v[204:207], v173 offset:36864
	ds_read_b128 v[208:211], v173 offset:37888
	ds_read_b128 v[212:215], v173 offset:38912
	ds_read_b128 v[216:219], v173 offset:39936
	global_load_lds_dwordx4 v144, s[30:31]
	s_mov_b32 m0, s38
	s_nop 0
	global_load_lds_dwordx4 v148, s[30:31]
	s_waitcnt vmcnt(8)
	s_waitcnt lgkmcnt(0)
	s_barrier
	s_setprio 1
	s_waitcnt lgkmcnt(0)
	v_mfma_f32_16x16x32_bf16 v[124:127], v[128:131], v[188:191], v[124:127]
	v_mfma_f32_16x16x32_bf16 v[120:123], v[136:139], v[188:191], v[120:123]
	v_mfma_f32_16x16x32_bf16 v[116:119], v[128:131], v[196:199], v[116:119]
	v_mfma_f32_16x16x32_bf16 v[108:111], v[136:139], v[196:199], v[108:111]
	v_mfma_f32_16x16x32_bf16 v[96:99], v[128:131], v[204:207], v[96:99]
	v_mfma_f32_16x16x32_bf16 v[88:91], v[136:139], v[204:207], v[88:91]
	v_mfma_f32_16x16x32_bf16 v[84:87], v[128:131], v[212:215], v[84:87]
	v_mfma_f32_16x16x32_bf16 v[76:79], v[136:139], v[212:215], v[76:79]
	v_mfma_f32_16x16x32_bf16 v[124:127], v[132:135], v[192:195], v[124:127]
	v_mfma_f32_16x16x32_bf16 v[120:123], v[140:143], v[192:195], v[120:123]
	v_mfma_f32_16x16x32_bf16 v[116:119], v[132:135], v[200:203], v[116:119]
	v_mfma_f32_16x16x32_bf16 v[108:111], v[140:143], v[200:203], v[108:111]
	v_mfma_f32_16x16x32_bf16 v[96:99], v[132:135], v[208:211], v[96:99]
	v_mfma_f32_16x16x32_bf16 v[88:91], v[140:143], v[208:211], v[88:91]
	v_mfma_f32_16x16x32_bf16 v[84:87], v[132:135], v[216:219], v[84:87]
	v_mfma_f32_16x16x32_bf16 v[76:79], v[140:143], v[216:219], v[76:79]
	s_setprio 0
	s_setprio 1
	v_mfma_f32_16x16x32_bf16 v[112:115], v[160:163], v[188:191], v[112:115]
	v_mfma_f32_16x16x32_bf16 v[104:107], v[180:183], v[188:191], v[104:107]
	v_mfma_f32_16x16x32_bf16 v[100:103], v[160:163], v[196:199], v[100:103]
	v_mfma_f32_16x16x32_bf16 v[92:95], v[180:183], v[196:199], v[92:95]
	v_mfma_f32_16x16x32_bf16 v[80:83], v[160:163], v[204:207], v[80:83]
	v_mfma_f32_16x16x32_bf16 v[72:75], v[180:183], v[204:207], v[72:75]
	v_mfma_f32_16x16x32_bf16 v[68:71], v[160:163], v[212:215], v[68:71]
	v_mfma_f32_16x16x32_bf16 v[64:67], v[180:183], v[212:215], v[64:67]
	v_mfma_f32_16x16x32_bf16 v[112:115], v[176:179], v[192:195], v[112:115]
	v_mfma_f32_16x16x32_bf16 v[104:107], v[184:187], v[192:195], v[104:107]
	v_mfma_f32_16x16x32_bf16 v[100:103], v[176:179], v[200:203], v[100:103]
	v_mfma_f32_16x16x32_bf16 v[92:95], v[184:187], v[200:203], v[92:95]
	v_mfma_f32_16x16x32_bf16 v[80:83], v[176:179], v[208:211], v[80:83]
	v_mfma_f32_16x16x32_bf16 v[72:75], v[184:187], v[208:211], v[72:75]
	v_mfma_f32_16x16x32_bf16 v[68:71], v[176:179], v[216:219], v[68:71]
	v_mfma_f32_16x16x32_bf16 v[64:67], v[184:187], v[216:219], v[64:67]
	s_setprio 0
	s_barrier
	s_add_u32 s98, s30, 0xfffc0080
	s_addc_u32 s99, s31, -1
	s_add_u32 s100, s28, 0x80
	s_addc_u32 s101, s29, 0
	s_add_i32 s30, s55, s22
	s_mov_b32 m0, s30
	ds_read_b128 v[188:191], v173 offset:49152
	ds_read_b128 v[192:195], v173 offset:50176
	ds_read_b128 v[196:199], v173 offset:51200
	ds_read_b128 v[200:203], v173 offset:52224
	ds_read_b128 v[204:207], v173 offset:53248
	ds_read_b128 v[208:211], v173 offset:54272
	ds_read_b128 v[212:215], v173 offset:55296
	ds_read_b128 v[216:219], v173 offset:56320
	global_load_lds_dwordx4 v146, s[100:101]
	s_add_i32 m0, s30, 0x2000
	s_add_u32 s28, s28, 0x40080
	s_addc_u32 s29, s29, 0
	s_add_i32 s30, s56, s22
	global_load_lds_dwordx4 v150, s[100:101]
	s_mov_b32 m0, s30
	s_nop 0
	global_load_lds_dwordx4 v146, s[28:29]
	s_add_i32 m0, s30, 0x2000
	s_nop 0
	global_load_lds_dwordx4 v150, s[28:29]
	s_mov_b32 m0, s39
	s_nop 0
	global_load_lds_dwordx4 v144, s[98:99]
	s_mov_b32 m0, s40
	s_nop 0
	global_load_lds_dwordx4 v148, s[98:99]
	s_waitcnt vmcnt(8)
	s_waitcnt lgkmcnt(0)
	s_barrier
	s_setprio 1
	s_waitcnt lgkmcnt(0)
	v_mfma_f32_16x16x32_bf16 v[60:63], v[128:131], v[188:191], v[60:63]
	v_mfma_f32_16x16x32_bf16 v[56:59], v[136:139], v[188:191], v[56:59]
	v_mfma_f32_16x16x32_bf16 v[52:55], v[128:131], v[196:199], v[52:55]
	v_mfma_f32_16x16x32_bf16 v[44:47], v[136:139], v[196:199], v[44:47]
	v_mfma_f32_16x16x32_bf16 v[32:35], v[128:131], v[204:207], v[32:35]
	v_mfma_f32_16x16x32_bf16 v[24:27], v[136:139], v[204:207], v[24:27]
	v_mfma_f32_16x16x32_bf16 v[20:23], v[128:131], v[212:215], v[20:23]
	v_mfma_f32_16x16x32_bf16 v[12:15], v[136:139], v[212:215], v[12:15]
	v_mfma_f32_16x16x32_bf16 v[60:63], v[132:135], v[192:195], v[60:63]
	v_mfma_f32_16x16x32_bf16 v[56:59], v[140:143], v[192:195], v[56:59]
	v_mfma_f32_16x16x32_bf16 v[52:55], v[132:135], v[200:203], v[52:55]
	v_mfma_f32_16x16x32_bf16 v[44:47], v[140:143], v[200:203], v[44:47]
	v_mfma_f32_16x16x32_bf16 v[32:35], v[132:135], v[208:211], v[32:35]
	v_mfma_f32_16x16x32_bf16 v[24:27], v[140:143], v[208:211], v[24:27]
	v_mfma_f32_16x16x32_bf16 v[20:23], v[132:135], v[216:219], v[20:23]
	v_mfma_f32_16x16x32_bf16 v[12:15], v[140:143], v[216:219], v[12:15]
	s_setprio 0
	s_setprio 1
	v_mfma_f32_16x16x32_bf16 v[48:51], v[160:163], v[188:191], v[48:51]
	v_mfma_f32_16x16x32_bf16 v[40:43], v[180:183], v[188:191], v[40:43]
	v_mfma_f32_16x16x32_bf16 v[36:39], v[160:163], v[196:199], v[36:39]
	v_mfma_f32_16x16x32_bf16 v[28:31], v[180:183], v[196:199], v[28:31]
	v_mfma_f32_16x16x32_bf16 v[16:19], v[160:163], v[204:207], v[16:19]
	v_mfma_f32_16x16x32_bf16 v[8:11], v[180:183], v[204:207], v[8:11]
	v_mfma_f32_16x16x32_bf16 v[4:7], v[160:163], v[212:215], v[4:7]
	v_mfma_f32_16x16x32_bf16 v[0:3], v[180:183], v[212:215], v[0:3]
	v_mfma_f32_16x16x32_bf16 v[48:51], v[176:179], v[192:195], v[48:51]
	v_mfma_f32_16x16x32_bf16 v[40:43], v[184:187], v[192:195], v[40:43]
	v_mfma_f32_16x16x32_bf16 v[36:39], v[176:179], v[200:203], v[36:39]
	v_mfma_f32_16x16x32_bf16 v[28:31], v[184:187], v[200:203], v[28:31]
	v_mfma_f32_16x16x32_bf16 v[16:19], v[176:179], v[208:211], v[16:19]
	v_mfma_f32_16x16x32_bf16 v[8:11], v[184:187], v[208:211], v[8:11]
	v_mfma_f32_16x16x32_bf16 v[4:7], v[176:179], v[216:219], v[4:7]
	v_mfma_f32_16x16x32_bf16 v[0:3], v[184:187], v[216:219], v[0:3]
	s_setprio 0
	s_add_i32 s54, s54, 2
	s_add_u32 s26, s26, 0x100
	s_addc_u32 s27, s27, 0
	s_add_u32 s52, s52, 0x100
	s_addc_u32 s53, s53, 0
	s_cmp_gt_u32 s54, 13
	s_barrier
	s_cbranch_scc0 .LBB0_130
	s_and_b64 vcc, exec, s[12:13]
	s_cbranch_vccz .LBB0_133
	s_barrier

; #define PG8_STAGE(bufoff, gbase, voff) do { _Pragma("unroll") for (int _i = 0; _i < 2; ++_i) \
;         __builtin_amdgcn_global_load_lds((const unsigned*)((const char*)(gbase) + (voff)[_i]), (PG8_LAS unsigned*)(lds + (bufoff) + ldsw + _i * 8192), 16, 0, 0); } while (0)
; #define PG8_LDA(dst, b, h) do { _Pragma("unroll") for (int m = 0; m < 4; ++m) _Pragma("unroll") for (int k = 0; k < 2; ++k) dst[m][k] = *(const PG8_LAS bf16x8*)(lds + PG8_SA(b, h) + aoff + m * 2048 + k * 1024); } while (0)
; #define PG8_LDB(dst, b, h) do { _Pragma("unroll") for (int n = 0; n < 2; ++n) _Pragma("unroll") for (int k = 0; k < 2; ++k) dst[n][k] = *(const PG8_LAS bf16x8*)(lds + PG8_SB(b, h) + boff + n * 2048 + k * 1024); } while (0)
; #define PG8_MMA(ai, bj, At, Bt) do { __builtin_amdgcn_s_setprio(1); _Pragma("unroll") for (int m = 0; m < 4; ++m) _Pragma("unroll") for (int n = 0; n < 2; ++n) _Pragma("unroll") for (int k = 0; k < 2; ++k) \
;         acc[ai][bj][m][n] = __builtin_amdgcn_mfma_f32_16x16x32_bf16(Bt[n][k], At[m][k], acc[ai][bj][m][n], 0, 0, 0); __builtin_amdgcn_s_setprio(0); } while (0)
; #define PG8_WAIT_V(n) asm volatile("s_waitcnt vmcnt(" #n ")" ::: "memory")
; #define PG8_WAIT_L(n) asm volatile("s_waitcnt lgkmcnt(" #n ")" ::: "memory")
; #define PG8_BAR __builtin_amdgcn_s_barrier()
; #define PG8_SCHED __builtin_amdgcn_sched_barrier(0)
; template <class Epi, class Sched, bool ALIGN_EPI = false, bool SP2 = false>
; __device__ __forceinline__ void gemm_phase(PG8_LAS unsigned char* lds, const Gemm g, const Sched& S, const Epi& E) {
;     ...
;             PG8_LDB(B0, 0, 0); PG8_LDB(B1, 0, 1); PG8_SCHED; PG8_LDA(At, 0, 0); PG8_STAGE(PG8_SA(1, 1), a1 + hstep, voffA);
;             PG8_WAIT_V(8); PG8_WAIT_L(0); PG8_BAR; PG8_MMA(0, 0, At, B0); PG8_MMA(0, 1, At, B1); PG8_BAR; PG8_SCHED;
;             PG8_LDA(At, 0, 1); PG8_STAGE(PG8_SB(0, 0), b2, voffB); PG8_STAGE(PG8_SB(0, 1), b2 + hstep, voffB); PG8_STAGE(PG8_SA(0, 0), a2, voffA);
;             PG8_WAIT_V(8); PG8_WAIT_L(0); PG8_BAR; PG8_MMA(1, 0, At, B0); PG8_MMA(1, 1, At, B1); PG8_BAR; PG8_SCHED;
.LBB0_658:
	ds_read_b128 v[144:147], v151
	ds_read_b128 v[156:159], v151 offset:1024
	ds_read_b128 v[160:163], v151 offset:2048
	ds_read_b128 v[168:171], v151 offset:3072
	ds_read_b128 v[172:175], v152
	ds_read_b128 v[176:179], v152 offset:1024
	ds_read_b128 v[180:183], v152 offset:2048
	ds_read_b128 v[184:187], v152 offset:3072
	s_add_u32 s26, s24, 0xfffc0080
	s_addc_u32 s27, s25, -1
	s_cmp_eq_u32 s50, 12
	s_cselect_b32 s29, s17, s27
	s_cselect_b32 s28, s23, s26
	s_cselect_b32 s27, s15, s49
	s_cselect_b32 s26, s47, s48
	s_add_i32 m0, s34, 0xc000
	ds_read_b128 v[188:191], v153
	ds_read_b128 v[192:195], v153 offset:1024
	ds_read_b128 v[196:199], v153 offset:2048
	ds_read_b128 v[200:203], v153 offset:3072
	ds_read_b128 v[204:207], v153 offset:4096
	ds_read_b128 v[208:211], v153 offset:5120
	ds_read_b128 v[212:215], v153 offset:6144
	ds_read_b128 v[216:219], v153 offset:7168
	global_load_lds_dwordx4 v136, s[24:25]
	s_add_i32 m0, s34, 0xe000
	s_nop 0
	global_load_lds_dwordx4 v138, s[24:25]
	s_waitcnt vmcnt(8)
	s_waitcnt lgkmcnt(0)
	s_barrier
	s_setprio 1
	s_waitcnt lgkmcnt(0)
	v_mfma_f32_16x16x32_bf16 v[124:127], v[144:147], v[188:191], v[124:127]
	v_mfma_f32_16x16x32_bf16 v[120:123], v[160:163], v[188:191], v[120:123]
	v_mfma_f32_16x16x32_bf16 v[108:111], v[144:147], v[196:199], v[108:111]
	v_mfma_f32_16x16x32_bf16 v[104:107], v[160:163], v[196:199], v[104:107]
	v_mfma_f32_16x16x32_bf16 v[92:95], v[144:147], v[204:207], v[92:95]
	v_mfma_f32_16x16x32_bf16 v[88:91], v[160:163], v[204:207], v[88:91]
	v_mfma_f32_16x16x32_bf16 v[76:79], v[144:147], v[212:215], v[76:79]
	v_mfma_f32_16x16x32_bf16 v[72:75], v[160:163], v[212:215], v[72:75]
	v_mfma_f32_16x16x32_bf16 v[124:127], v[156:159], v[192:195], v[124:127]
	v_mfma_f32_16x16x32_bf16 v[120:123], v[168:171], v[192:195], v[120:123]
	v_mfma_f32_16x16x32_bf16 v[108:111], v[156:159], v[200:203], v[108:111]
	v_mfma_f32_16x16x32_bf16 v[104:107], v[168:171], v[200:203], v[104:107]
	v_mfma_f32_16x16x32_bf16 v[92:95], v[156:159], v[208:211], v[92:95]
	v_mfma_f32_16x16x32_bf16 v[88:91], v[168:171], v[208:211], v[88:91]
	v_mfma_f32_16x16x32_bf16 v[76:79], v[156:159], v[216:219], v[76:79]
	v_mfma_f32_16x16x32_bf16 v[72:75], v[168:171], v[216:219], v[72:75]
	s_setprio 0
	s_setprio 1
	v_mfma_f32_16x16x32_bf16 v[116:119], v[172:175], v[188:191], v[116:119]
	v_mfma_f32_16x16x32_bf16 v[112:115], v[180:183], v[188:191], v[112:115]
	v_mfma_f32_16x16x32_bf16 v[100:103], v[172:175], v[196:199], v[100:103]
	v_mfma_f32_16x16x32_bf16 v[96:99], v[180:183], v[196:199], v[96:99]
	v_mfma_f32_16x16x32_bf16 v[84:87], v[172:175], v[204:207], v[84:87]
	v_mfma_f32_16x16x32_bf16 v[80:83], v[180:183], v[204:207], v[80:83]
	v_mfma_f32_16x16x32_bf16 v[68:71], v[172:175], v[212:215], v[68:71]
	v_mfma_f32_16x16x32_bf16 v[64:67], v[180:183], v[212:215], v[64:67]
	v_mfma_f32_16x16x32_bf16 v[116:119], v[176:179], v[192:195], v[116:119]
	v_mfma_f32_16x16x32_bf16 v[112:115], v[184:187], v[192:195], v[112:115]
	v_mfma_f32_16x16x32_bf16 v[100:103], v[176:179], v[200:203], v[100:103]
	v_mfma_f32_16x16x32_bf16 v[96:99], v[184:187], v[200:203], v[96:99]
	v_mfma_f32_16x16x32_bf16 v[84:87], v[176:179], v[208:211], v[84:87]
	v_mfma_f32_16x16x32_bf16 v[80:83], v[184:187], v[208:211], v[80:83]
	v_mfma_f32_16x16x32_bf16 v[68:71], v[176:179], v[216:219], v[68:71]
	v_mfma_f32_16x16x32_bf16 v[64:67], v[184:187], v[216:219], v[64:67]
	s_setprio 0
	s_barrier
	s_add_i32 s51, s44, s33
	s_mov_b32 m0, s51
	ds_read_b128 v[188:191], v153 offset:16384
	ds_read_b128 v[192:195], v153 offset:17408
	ds_read_b128 v[196:199], v153 offset:18432
	ds_read_b128 v[200:203], v153 offset:19456
	ds_read_b128 v[204:207], v153 offset:20480
	ds_read_b128 v[208:211], v153 offset:21504
	ds_read_b128 v[212:215], v153 offset:22528
	ds_read_b128 v[216:219], v153 offset:23552
	global_load_lds_dwordx4 v130, s[26:27]
	s_add_i32 m0, s51, 0x2000
	s_add_u32 s52, s26, 0x40000
	s_addc_u32 s53, s27, 0
	s_add_i32 s51, s45, s33
	global_load_lds_dwordx4 v134, s[26:27]
	s_mov_b32 m0, s51
	s_nop 0
	global_load_lds_dwordx4 v130, s[52:53]
	s_add_i32 m0, s51, 0x2000
	s_nop 0
	global_load_lds_dwordx4 v134, s[52:53]
	s_mov_b32 m0, s34
	s_nop 0
	global_load_lds_dwordx4 v128, s[28:29]
	s_mov_b32 m0, s35
	s_nop 0
	global_load_lds_dwordx4 v132, s[28:29]
	s_waitcnt vmcnt(8)
	s_waitcnt lgkmcnt(0)
	s_barrier
	s_setprio 1
	s_waitcnt lgkmcnt(0)
	v_mfma_f32_16x16x32_bf16 v[60:63], v[144:147], v[188:191], v[60:63]
	v_mfma_f32_16x16x32_bf16 v[56:59], v[160:163], v[188:191], v[56:59]
	v_mfma_f32_16x16x32_bf16 v[44:47], v[144:147], v[196:199], v[44:47]
	v_mfma_f32_16x16x32_bf16 v[40:43], v[160:163], v[196:199], v[40:43]
	v_mfma_f32_16x16x32_bf16 v[28:31], v[144:147], v[204:207], v[28:31]
	v_mfma_f32_16x16x32_bf16 v[24:27], v[160:163], v[204:207], v[24:27]
	v_mfma_f32_16x16x32_bf16 v[12:15], v[144:147], v[212:215], v[12:15]
	v_mfma_f32_16x16x32_bf16 v[8:11], v[160:163], v[212:215], v[8:11]
	v_mfma_f32_16x16x32_bf16 v[60:63], v[156:159], v[192:195], v[60:63]
	v_mfma_f32_16x16x32_bf16 v[56:59], v[168:171], v[192:195], v[56:59]
	v_mfma_f32_16x16x32_bf16 v[44:47], v[156:159], v[200:203], v[44:47]
	v_mfma_f32_16x16x32_bf16 v[40:43], v[168:171], v[200:203], v[40:43]
	v_mfma_f32_16x16x32_bf16 v[28:31], v[156:159], v[208:211], v[28:31]
	v_mfma_f32_16x16x32_bf16 v[24:27], v[168:171], v[208:211], v[24:27]
	v_mfma_f32_16x16x32_bf16 v[12:15], v[156:159], v[216:219], v[12:15]
	v_mfma_f32_16x16x32_bf16 v[8:11], v[168:171], v[216:219], v[8:11]
	s_setprio 0
	s_setprio 1
	v_mfma_f32_16x16x32_bf16 v[52:55], v[172:175], v[188:191], v[52:55]
	v_mfma_f32_16x16x32_bf16 v[48:51], v[180:183], v[188:191], v[48:51]
	v_mfma_f32_16x16x32_bf16 v[36:39], v[172:175], v[196:199], v[36:39]
	v_mfma_f32_16x16x32_bf16 v[32:35], v[180:183], v[196:199], v[32:35]
	v_mfma_f32_16x16x32_bf16 v[20:23], v[172:175], v[204:207], v[20:23]
	v_mfma_f32_16x16x32_bf16 v[16:19], v[180:183], v[204:207], v[16:19]
	v_mfma_f32_16x16x32_bf16 v[4:7], v[172:175], v[212:215], v[4:7]
	v_mfma_f32_16x16x32_bf16 v[0:3], v[180:183], v[212:215], v[0:3]
	v_mfma_f32_16x16x32_bf16 v[52:55], v[176:179], v[192:195], v[52:55]
	v_mfma_f32_16x16x32_bf16 v[48:51], v[184:187], v[192:195], v[48:51]
	v_mfma_f32_16x16x32_bf16 v[36:39], v[176:179], v[200:203], v[36:39]
	v_mfma_f32_16x16x32_bf16 v[32:35], v[184:187], v[200:203], v[32:35]
	v_mfma_f32_16x16x32_bf16 v[20:23], v[176:179], v[208:211], v[20:23]
	v_mfma_f32_16x16x32_bf16 v[16:19], v[184:187], v[208:211], v[16:19]
	v_mfma_f32_16x16x32_bf16 v[4:7], v[176:179], v[216:219], v[4:7]
	v_mfma_f32_16x16x32_bf16 v[0:3], v[184:187], v[216:219], v[0:3]
	s_setprio 0
	s_barrier
; #define PG8_STAGE(bufoff, gbase, voff) do { _Pragma("unroll") for (int _i = 0; _i < 2; ++_i) \
;         __builtin_amdgcn_global_load_lds((const unsigned*)((const char*)(gbase) + (voff)[_i]), (PG8_LAS unsigned*)(lds + (bufoff) + ldsw + _i * 8192), 16, 0, 0); } while (0)
; #define PG8_LDA(dst, b, h) do { _Pragma("unroll") for (int m = 0; m < 4; ++m) _Pragma("unroll") for (int k = 0; k < 2; ++k) dst[m][k] = *(const PG8_LAS bf16x8*)(lds + PG8_SA(b, h) + aoff + m * 2048 + k * 1024); } while (0)
; #define PG8_LDB(dst, b, h) do { _Pragma("unroll") for (int n = 0; n < 2; ++n) _Pragma("unroll") for (int k = 0; k < 2; ++k) dst[n][k] = *(const PG8_LAS bf16x8*)(lds + PG8_SB(b, h) + boff + n * 2048 + k * 1024); } while (0)
; #define PG8_MMA(ai, bj, At, Bt) do { __builtin_amdgcn_s_setprio(1); _Pragma("unroll") for (int m = 0; m < 4; ++m) _Pragma("unroll") for (int n = 0; n < 2; ++n) _Pragma("unroll") for (int k = 0; k < 2; ++k) \
;         acc[ai][bj][m][n] = __builtin_amdgcn_mfma_f32_16x16x32_bf16(Bt[n][k], At[m][k], acc[ai][bj][m][n], 0, 0, 0); __builtin_amdgcn_s_setprio(0); } while (0)
; #define PG8_WAIT_V(n) asm volatile("s_waitcnt vmcnt(" #n ")" ::: "memory")
; #define PG8_WAIT_L(n) asm volatile("s_waitcnt lgkmcnt(" #n ")" ::: "memory")
; #define PG8_BAR __builtin_amdgcn_s_barrier()
; #define PG8_SCHED __builtin_amdgcn_sched_barrier(0)
; template <class Epi, class Sched, bool ALIGN_EPI = false, bool SP2 = false>
; __device__ __forceinline__ void gemm_phase(PG8_LAS unsigned char* lds, const Gemm g, const Sched& S, const Epi& E) {
;     ...
;         for (int t = 0; t < nt; t += 2) {
;     ...
;             PG8_LDB(B0, 1, 0); PG8_LDB(B1, 1, 1); PG8_SCHED; PG8_LDA(At, 1, 0); PG8_STAGE(PG8_SA(0, 1), a2 + hstep, voffA);
;             PG8_WAIT_V(8); PG8_WAIT_L(0); PG8_BAR; PG8_MMA(0, 0, At, B0); PG8_MMA(0, 1, At, B1); PG8_BAR; PG8_SCHED;
;             PG8_LDA(At, 1, 1); PG8_STAGE(PG8_SB(1, 0), b3, voffB); PG8_STAGE(PG8_SB(1, 1), b3 + hstep, voffB); PG8_STAGE(PG8_SA(1, 0), a3, voffA);
;             PG8_WAIT_V(8); PG8_WAIT_L(0); PG8_BAR; PG8_MMA(1, 0, At, B0); PG8_MMA(1, 1, At, B1); PG8_BAR; PG8_SCHED;
	s_add_i32 s51, 0, 0x18000
	v_add_u32_e32 v155, s51, v149
	s_add_i32 s52, 0, 0x1c000
	ds_read_b128 v[144:147], v155
	ds_read_b128 v[156:159], v155 offset:1024
	ds_read_b128 v[160:163], v155 offset:2048
	ds_read_b128 v[168:171], v155 offset:3072
	v_add_u32_e32 v155, s52, v149
	ds_read_b128 v[172:175], v155
	ds_read_b128 v[176:179], v155 offset:1024
	ds_read_b128 v[180:183], v155 offset:2048
	ds_read_b128 v[184:187], v155 offset:3072
	s_add_u32 s28, s28, 0x40000
	s_addc_u32 s29, s29, 0
	s_mov_b32 m0, s36
	ds_read_b128 v[188:191], v153 offset:32768
	ds_read_b128 v[192:195], v153 offset:33792
	ds_read_b128 v[196:199], v153 offset:34816
	ds_read_b128 v[200:203], v153 offset:35840
	ds_read_b128 v[204:207], v153 offset:36864
	ds_read_b128 v[208:211], v153 offset:37888
	ds_read_b128 v[212:215], v153 offset:38912
	ds_read_b128 v[216:219], v153 offset:39936
	global_load_lds_dwordx4 v128, s[28:29]
	s_mov_b32 m0, s37
	s_nop 0
	global_load_lds_dwordx4 v132, s[28:29]
	s_waitcnt vmcnt(8)
	s_waitcnt lgkmcnt(0)
	s_barrier
	s_setprio 1
	s_waitcnt lgkmcnt(0)
	v_mfma_f32_16x16x32_bf16 v[124:127], v[144:147], v[188:191], v[124:127]
	v_mfma_f32_16x16x32_bf16 v[120:123], v[160:163], v[188:191], v[120:123]
	v_mfma_f32_16x16x32_bf16 v[108:111], v[144:147], v[196:199], v[108:111]
	v_mfma_f32_16x16x32_bf16 v[104:107], v[160:163], v[196:199], v[104:107]
	v_mfma_f32_16x16x32_bf16 v[92:95], v[144:147], v[204:207], v[92:95]
	v_mfma_f32_16x16x32_bf16 v[88:91], v[160:163], v[204:207], v[88:91]
	v_mfma_f32_16x16x32_bf16 v[76:79], v[144:147], v[212:215], v[76:79]
	v_mfma_f32_16x16x32_bf16 v[72:75], v[160:163], v[212:215], v[72:75]
	v_mfma_f32_16x16x32_bf16 v[124:127], v[156:159], v[192:195], v[124:127]
	v_mfma_f32_16x16x32_bf16 v[120:123], v[168:171], v[192:195], v[120:123]
	v_mfma_f32_16x16x32_bf16 v[108:111], v[156:159], v[200:203], v[108:111]
	v_mfma_f32_16x16x32_bf16 v[104:107], v[168:171], v[200:203], v[104:107]
	v_mfma_f32_16x16x32_bf16 v[92:95], v[156:159], v[208:211], v[92:95]
	v_mfma_f32_16x16x32_bf16 v[88:91], v[168:171], v[208:211], v[88:91]
	v_mfma_f32_16x16x32_bf16 v[76:79], v[156:159], v[216:219], v[76:79]
	v_mfma_f32_16x16x32_bf16 v[72:75], v[168:171], v[216:219], v[72:75]
	s_setprio 0
	s_setprio 1
	v_mfma_f32_16x16x32_bf16 v[116:119], v[172:175], v[188:191], v[116:119]
	v_mfma_f32_16x16x32_bf16 v[112:115], v[180:183], v[188:191], v[112:115]
	v_mfma_f32_16x16x32_bf16 v[100:103], v[172:175], v[196:199], v[100:103]
	v_mfma_f32_16x16x32_bf16 v[96:99], v[180:183], v[196:199], v[96:99]
	v_mfma_f32_16x16x32_bf16 v[84:87], v[172:175], v[204:207], v[84:87]
	v_mfma_f32_16x16x32_bf16 v[80:83], v[180:183], v[204:207], v[80:83]
	v_mfma_f32_16x16x32_bf16 v[68:71], v[172:175], v[212:215], v[68:71]
	v_mfma_f32_16x16x32_bf16 v[64:67], v[180:183], v[212:215], v[64:67]
	v_mfma_f32_16x16x32_bf16 v[116:119], v[176:179], v[192:195], v[116:119]
	v_mfma_f32_16x16x32_bf16 v[112:115], v[184:187], v[192:195], v[112:115]
	v_mfma_f32_16x16x32_bf16 v[100:103], v[176:179], v[200:203], v[100:103]
	v_mfma_f32_16x16x32_bf16 v[96:99], v[184:187], v[200:203], v[96:99]
	v_mfma_f32_16x16x32_bf16 v[84:87], v[176:179], v[208:211], v[84:87]
	v_mfma_f32_16x16x32_bf16 v[80:83], v[184:187], v[208:211], v[80:83]
	v_mfma_f32_16x16x32_bf16 v[68:71], v[176:179], v[216:219], v[68:71]
	v_mfma_f32_16x16x32_bf16 v[64:67], v[184:187], v[216:219], v[64:67]
	s_setprio 0
	s_barrier
	s_add_u32 s98, s28, 0xfffc0080
	s_addc_u32 s99, s29, -1
	s_add_u32 s100, s26, 0x80
	s_addc_u32 s101, s27, 0
	s_add_i32 s28, s51, s33
	s_mov_b32 m0, s28
	ds_read_b128 v[188:191], v153 offset:49152
	ds_read_b128 v[192:195], v153 offset:50176
	ds_read_b128 v[196:199], v153 offset:51200
	ds_read_b128 v[200:203], v153 offset:52224
	ds_read_b128 v[204:207], v153 offset:53248
	ds_read_b128 v[208:211], v153 offset:54272
	ds_read_b128 v[212:215], v153 offset:55296
	ds_read_b128 v[216:219], v153 offset:56320
	global_load_lds_dwordx4 v130, s[100:101]
	s_add_i32 m0, s28, 0x2000
	s_add_u32 s26, s26, 0x40080
	s_addc_u32 s27, s27, 0
	s_add_i32 s28, s52, s33
	global_load_lds_dwordx4 v134, s[100:101]
	s_mov_b32 m0, s28
	s_nop 0
	global_load_lds_dwordx4 v130, s[26:27]
	s_add_i32 m0, s28, 0x2000
	s_nop 0
	global_load_lds_dwordx4 v134, s[26:27]
	s_mov_b32 m0, s39
	s_nop 0
	global_load_lds_dwordx4 v128, s[98:99]
	s_mov_b32 m0, s40
	s_nop 0
	global_load_lds_dwordx4 v132, s[98:99]
	s_waitcnt vmcnt(8)
	s_waitcnt lgkmcnt(0)
	s_barrier
	s_setprio 1
	s_waitcnt lgkmcnt(0)
	v_mfma_f32_16x16x32_bf16 v[60:63], v[144:147], v[188:191], v[60:63]
	v_mfma_f32_16x16x32_bf16 v[56:59], v[160:163], v[188:191], v[56:59]
	v_mfma_f32_16x16x32_bf16 v[44:47], v[144:147], v[196:199], v[44:47]
	v_mfma_f32_16x16x32_bf16 v[40:43], v[160:163], v[196:199], v[40:43]
	v_mfma_f32_16x16x32_bf16 v[28:31], v[144:147], v[204:207], v[28:31]
	v_mfma_f32_16x16x32_bf16 v[24:27], v[160:163], v[204:207], v[24:27]
	v_mfma_f32_16x16x32_bf16 v[12:15], v[144:147], v[212:215], v[12:15]
	v_mfma_f32_16x16x32_bf16 v[8:11], v[160:163], v[212:215], v[8:11]
	v_mfma_f32_16x16x32_bf16 v[60:63], v[156:159], v[192:195], v[60:63]
	v_mfma_f32_16x16x32_bf16 v[56:59], v[168:171], v[192:195], v[56:59]
	v_mfma_f32_16x16x32_bf16 v[44:47], v[156:159], v[200:203], v[44:47]
	v_mfma_f32_16x16x32_bf16 v[40:43], v[168:171], v[200:203], v[40:43]
	v_mfma_f32_16x16x32_bf16 v[28:31], v[156:159], v[208:211], v[28:31]
	v_mfma_f32_16x16x32_bf16 v[24:27], v[168:171], v[208:211], v[24:27]
	v_mfma_f32_16x16x32_bf16 v[12:15], v[156:159], v[216:219], v[12:15]
	v_mfma_f32_16x16x32_bf16 v[8:11], v[168:171], v[216:219], v[8:11]
	s_setprio 0
	s_setprio 1
	v_mfma_f32_16x16x32_bf16 v[52:55], v[172:175], v[188:191], v[52:55]
	v_mfma_f32_16x16x32_bf16 v[48:51], v[180:183], v[188:191], v[48:51]
	v_mfma_f32_16x16x32_bf16 v[36:39], v[172:175], v[196:199], v[36:39]
	v_mfma_f32_16x16x32_bf16 v[32:35], v[180:183], v[196:199], v[32:35]
	v_mfma_f32_16x16x32_bf16 v[20:23], v[172:175], v[204:207], v[20:23]
	v_mfma_f32_16x16x32_bf16 v[16:19], v[180:183], v[204:207], v[16:19]
	v_mfma_f32_16x16x32_bf16 v[4:7], v[172:175], v[212:215], v[4:7]
	v_mfma_f32_16x16x32_bf16 v[0:3], v[180:183], v[212:215], v[0:3]
	v_mfma_f32_16x16x32_bf16 v[52:55], v[176:179], v[192:195], v[52:55]
	v_mfma_f32_16x16x32_bf16 v[48:51], v[184:187], v[192:195], v[48:51]
	v_mfma_f32_16x16x32_bf16 v[36:39], v[176:179], v[200:203], v[36:39]
	v_mfma_f32_16x16x32_bf16 v[32:35], v[184:187], v[200:203], v[32:35]
	v_mfma_f32_16x16x32_bf16 v[20:23], v[176:179], v[208:211], v[20:23]
	v_mfma_f32_16x16x32_bf16 v[16:19], v[184:187], v[208:211], v[16:19]
	v_mfma_f32_16x16x32_bf16 v[4:7], v[176:179], v[216:219], v[4:7]
	v_mfma_f32_16x16x32_bf16 v[0:3], v[184:187], v[216:219], v[0:3]
	s_setprio 0
	s_add_i32 s50, s50, 2
	s_add_u32 s24, s24, 0x100
	s_addc_u32 s25, s25, 0
	s_add_u32 s48, s48, 0x100
	s_addc_u32 s49, s49, 0
	s_cmp_gt_u32 s50, 13
	s_barrier
; #define PG8_LAS __attribute__((address_space(3)))
; __device__ __forceinline__ unsigned cvt_pk_bf16(float lo, float hi) { const f32x2_t v = {lo, hi}; const bf16x2_t b = __builtin_convertvector(v, bf16x2_t); return __builtin_bit_cast(unsigned, b); }
; #define PG8_BAR __builtin_amdgcn_s_barrier()
;     __device__ __forceinline__ void operator()(const f32x4 (&acc)[2][2][4][2], const Unit& u, int wr, int wc, int fr, int fq, const PG8_LAS float*) const {
;         const int row0 = u.pm * BM + wr * 64 + fr; const int col0 = u.pn * BM + wc * 32 + 8 * fq;
; #pragma unroll
;         for (int ai = 0; ai < 2; ++ai)
; #pragma unroll
;             for (int m = 0; m < 4; ++m) { const int row = row0 + ai * HALF + m * 16; const size_t off = (size_t)row * ldc + col0; float ss = 0.f;
; #pragma unroll
;                 for (int bj = 0; bj < 2; ++bj) {
;                     const f32x4 b0 = *(const f32x4*)(base + off + bj * HALF), b1 = *(const f32x4*)(base + off + bj * HALF + 4);
;                     const f32x4 v0 = b0 + acc[ai][bj][m][0], v1 = b1 + acc[ai][bj][m][1];
;                     *(f32x4*)(out + off + bj * HALF) = v0; *(f32x4*)(out + off + bj * HALF + 4) = v1;
;                     if (xb) { u32x4 w; w.x = cvt_pk_bf16(v0[0], v0[1]); w.y = cvt_pk_bf16(v0[2], v0[3]); w.z = cvt_pk_bf16(v1[0], v1[1]); w.w = cvt_pk_bf16(v1[2], v1[3]);
;                         *(u32x4*)(xb + off + bj * HALF) = w;
;                         ss += ((v0[0] * v0[0] + v0[1] * v0[1]) + (v0[2] * v0[2] + v0[3] * v0[3])) + ((v1[0] * v1[0] + v1[1] * v1[1]) + (v1[2] * v1[2] + v1[3] * v1[3])); } }
;                 if (xb) { ss += __shfl_xor(ss, 16); ss += __shfl_xor(ss, 32); if (fq == 0) ssq[(size_t)row * 16 + u.pn * 4 + wc] = ss; } }
; template <class Epi, class Sched, bool ALIGN_EPI = false, bool SP2 = false>
; __device__ __forceinline__ void gemm_phase(PG8_LAS unsigned char* lds, const Gemm g, const Sched& S, const Epi& E) {
;     ...
;         if constexpr (ALIGN_EPI) { if (wr == 0) PG8_BAR; }
	s_cbranch_scc0 .LBB0_658
	v_mbcnt_lo_u32_b32 v234, -1, 0
	v_mbcnt_hi_u32_b32 v234, -1, v234
	v_bfe_u32 v234, v234, 3, 1
	v_sub_u32_e32 v231, 0, v234
	v_and_b32_e32 v230, 0xffff8010, v231
	v_and_b32_e32 v235, 0x7ff0, v231
	v_sub_u32_e32 v244, 0x8000, v235
	v_mov_b32_e32 v245, 0
	s_mov_b32 s98, 0xff00ff
	s_mov_b32 s99, 0xff00ff
	s_and_b64 vcc, exec, s[12:13]
	s_cbranch_vccz .LBB0_661
	s_barrier
.LBB0_661:
	v_lshl_add_u32 v146, s22, 8, v148
	v_lshl_or_b32 v144, s6, 8, v150
	v_ashrrev_i32_e32 v147, 31, v146
	v_ashrrev_i32_e32 v145, 31, v144
	v_lshlrev_b64 v[156:157], 10, v[146:147]
	v_lshl_add_u64 v[164:165], v[156:157], 0, v[144:145]
	v_readlane_b32 s48, v254, 3
	v_lshlrev_b64 v[168:169], 2, v[164:165]
	v_readlane_b32 s49, v254, 4
	v_readlane_b32 s22, v254, 39
	v_readlane_b32 s23, v254, 40
	v_lshl_add_u64 v[170:171], s[48:49], 0, v[168:169]
	global_load_dwordx4 v[156:159], v[170:171], off
	global_load_dwordx4 v[160:163], v[170:171], off offset:16
	v_lshl_add_u64 v[164:165], v[164:165], 1, s[22:23]
	v_lshl_add_u64 v[172:173], s[68:69], 0, v[168:169]
	v_xor_b32_e32 v155, 32, v154
	s_lshl_b32 s22, s6, 2
	s_ashr_i32 s23, s22, 31
	v_readlane_b32 s50, v254, 5
	v_readlane_b32 s51, v254, 6
	v_readlane_b32 s52, v254, 7
	v_readlane_b32 s53, v254, 8
	v_readlane_b32 s54, v254, 9
	v_readlane_b32 s55, v254, 10
	v_readlane_b32 s56, v254, 11
	v_readlane_b32 s57, v254, 12
	v_readlane_b32 s58, v254, 13
	v_readlane_b32 s59, v254, 14
	v_readlane_b32 s60, v254, 15
	v_readlane_b32 s61, v254, 16
	v_readlane_b32 s62, v254, 17
	v_readlane_b32 s63, v254, 18
	s_waitcnt vmcnt(0)
	v_pk_add_f32 v[126:127], v[126:127], v[158:159]
	v_pk_add_f32 v[124:125], v[124:125], v[156:157]
	v_pk_add_f32 v[158:159], v[122:123], v[162:163]
	v_pk_add_f32 v[156:157], v[120:121], v[160:161]
	v_cvt_pk_bf16_f32 v120, v124, v125
	v_cvt_pk_bf16_f32 v121, v126, v127
	v_cvt_pk_bf16_f32 v122, v156, v157
	v_cvt_pk_bf16_f32 v123, v158, v159
	v_lshl_add_u64 v[228:229], v[172:173], 0, v[230:231]
	v_lshl_add_u64 v[232:233], v[172:173], 0, v[244:245]
	s_nop 1
	v_mov_b32_dpp v236, v156 row_ror:8 row_mask:0xf bank_mask:0xf
	v_mov_b32_dpp v237, v157 row_ror:8 row_mask:0xf bank_mask:0xf
	v_mov_b32_dpp v238, v158 row_ror:8 row_mask:0xf bank_mask:0xf
	v_mov_b32_dpp v239, v159 row_ror:8 row_mask:0xf bank_mask:0xf
	v_mov_b32_dpp v240, v124 row_ror:8 row_mask:0xf bank_mask:0xf
	v_mov_b32_dpp v241, v125 row_ror:8 row_mask:0xf bank_mask:0xf
	v_mov_b32_dpp v242, v126 row_ror:8 row_mask:0xf bank_mask:0xf
	v_mov_b32_dpp v243, v127 row_ror:8 row_mask:0xf bank_mask:0xf
	s_nop 0
	v_cndmask_b32_e64 v236, v236, v124, s[98:99]
	v_cndmask_b32_e64 v237, v237, v125, s[98:99]
	v_cndmask_b32_e64 v238, v238, v126, s[98:99]
	v_cndmask_b32_e64 v239, v239, v127, s[98:99]
	v_cndmask_b32_e64 v240, v156, v240, s[98:99]
	v_cndmask_b32_e64 v241, v157, v241, s[98:99]
	v_cndmask_b32_e64 v242, v158, v242, s[98:99]
	v_cndmask_b32_e64 v243, v159, v243, s[98:99]
	global_store_dwordx4 v[228:229], v[236:239], off
	global_store_dwordx4 v[232:233], v[240:243], off
	global_store_dwordx4 v[164:165], v[120:123], off
	global_load_dwordx4 v[160:163], v[170:171], off offset:512
	s_nop 0
	global_load_dwordx4 v[168:171], v[170:171], off offset:528
	v_mul_f32_e32 v122, v125, v125
	v_mul_f32_e32 v123, v127, v127
	v_mul_f32_e32 v125, v157, v157
	v_mul_f32_e32 v127, v159, v159
	v_fmac_f32_e32 v122, v124, v124
	v_fmac_f32_e32 v123, v126, v126
	v_fmac_f32_e32 v125, v156, v156
	v_fmac_f32_e32 v127, v158, v158
	v_add_f32_e32 v122, v122, v123
	v_add_f32_e32 v123, v125, v127
	v_add_f32_e32 v126, v122, v123
	v_and_b32_e32 v121, 64, v154
	v_xor_b32_e32 v120, 16, v154
	v_add_u32_e32 v121, 64, v121
	v_cmp_lt_i32_e32 vcc, v120, v121
	s_waitcnt vmcnt(1)
	v_pk_add_f32 v[118:119], v[118:119], v[162:163]
	v_pk_add_f32 v[116:117], v[116:117], v[160:161]
	s_waitcnt vmcnt(0)
	v_pk_add_f32 v[124:125], v[114:115], v[170:171]
	v_pk_add_f32 v[122:123], v[112:113], v[168:169]
	v_mul_f32_e32 v112, v117, v117
	v_mul_f32_e32 v113, v119, v119
	v_mul_f32_e32 v114, v123, v123
	v_mul_f32_e32 v115, v125, v125
	v_fmac_f32_e32 v112, v116, v116
	v_fmac_f32_e32 v113, v118, v118
	v_fmac_f32_e32 v114, v122, v122
	v_fmac_f32_e32 v115, v124, v124
	v_add_f32_e32 v112, v112, v113
	v_add_f32_e32 v113, v114, v115
	v_cndmask_b32_e32 v120, v154, v120, vcc
	v_add_f32_e32 v112, v112, v113
	v_lshlrev_b32_e32 v120, 2, v120
	v_add_f32_e32 v112, v126, v112
	v_mov_b32_e32 v113, v112
	s_nop 1
	v_permlane16_swap_b32_e32 v113, v112
	v_cmp_lt_i32_e32 vcc, v155, v121
	v_lshl_add_u64 v[228:229], v[172:173], 0, v[230:231]
	v_lshl_add_u64 v[232:233], v[172:173], 0, v[244:245]
	s_nop 1
	v_mov_b32_dpp v236, v122 row_ror:8 row_mask:0xf bank_mask:0xf
	v_mov_b32_dpp v237, v123 row_ror:8 row_mask:0xf bank_mask:0xf
	v_mov_b32_dpp v238, v124 row_ror:8 row_mask:0xf bank_mask:0xf
	v_mov_b32_dpp v239, v125 row_ror:8 row_mask:0xf bank_mask:0xf
	v_mov_b32_dpp v240, v116 row_ror:8 row_mask:0xf bank_mask:0xf
	v_mov_b32_dpp v241, v117 row_ror:8 row_mask:0xf bank_mask:0xf
	v_mov_b32_dpp v242, v118 row_ror:8 row_mask:0xf bank_mask:0xf
	v_mov_b32_dpp v243, v119 row_ror:8 row_mask:0xf bank_mask:0xf
	s_nop 0
	v_cndmask_b32_e64 v236, v236, v116, s[98:99]
	v_cndmask_b32_e64 v237, v237, v117, s[98:99]
	v_cndmask_b32_e64 v238, v238, v118, s[98:99]
	v_cndmask_b32_e64 v239, v239, v119, s[98:99]
	v_cndmask_b32_e64 v240, v122, v240, s[98:99]
	v_cndmask_b32_e64 v241, v123, v241, s[98:99]
	v_cndmask_b32_e64 v242, v124, v242, s[98:99]
	v_cndmask_b32_e64 v243, v125, v243, s[98:99]
	global_store_dwordx4 v[228:229], v[236:239], off offset:512
	global_store_dwordx4 v[232:233], v[240:243], off offset:512
	v_cndmask_b32_e32 v114, v154, v155, vcc
	v_lshlrev_b32_e32 v114, 2, v114
	s_waitcnt lgkmcnt(0)
	v_add_f32_e32 v112, v112, v113
	v_mov_b32_e32 v113, v112
	s_nop 1
	v_permlane32_swap_b32_e32 v113, v112
	v_cvt_pk_bf16_f32 v116, v116, v117
	v_cvt_pk_bf16_f32 v117, v118, v119
	v_cvt_pk_bf16_f32 v118, v122, v123
	v_cvt_pk_bf16_f32 v119, v124, v125
	global_store_dwordx4 v[164:165], v[116:119], off offset:256
	s_and_saveexec_b64 s[24:25], s[2:3]
	s_cbranch_execz .LBB0_663
	v_readlane_b32 s26, v254, 41
	s_waitcnt lgkmcnt(0)
	v_add_f32_e32 v115, v112, v113
	v_lshlrev_b64 v[112:113], 6, v[146:147]
	v_readlane_b32 s27, v254, 42
	s_lshl_b32 s6, s38, 2
	s_nop 0
	v_lshl_add_u64 v[112:113], s[26:27], 0, v[112:113]
	v_lshl_add_u64 v[112:113], s[22:23], 2, v[112:113]
	v_lshl_add_u64 v[112:113], v[112:113], 0, s[6:7]
	global_store_dword v[112:113], v115, off
; __device__ __forceinline__ unsigned cvt_pk_bf16(float lo, float hi) { const f32x2_t v = {lo, hi}; const bf16x2_t b = __builtin_convertvector(v, bf16x2_t); return __builtin_bit_cast(unsigned, b); }
;     __device__ __forceinline__ void operator()(const f32x4 (&acc)[2][2][4][2], const Unit& u, int wr, int wc, int fr, int fq, const PG8_LAS float*) const {
;     ...
;             for (int m = 0; m < 4; ++m) { const int row = row0 + ai * HALF + m * 16; const size_t off = (size_t)row * ldc + col0; float ss = 0.f;
; #pragma unroll
;                 for (int bj = 0; bj < 2; ++bj) {
;                     const f32x4 b0 = *(const f32x4*)(base + off + bj * HALF), b1 = *(const f32x4*)(base + off + bj * HALF + 4);
;                     const f32x4 v0 = b0 + acc[ai][bj][m][0], v1 = b1 + acc[ai][bj][m][1];
;                     *(f32x4*)(out + off + bj * HALF) = v0; *(f32x4*)(out + off + bj * HALF + 4) = v1;
;                     if (xb) { u32x4 w; w.x = cvt_pk_bf16(v0[0], v0[1]); w.y = cvt_pk_bf16(v0[2], v0[3]); w.z = cvt_pk_bf16(v1[0], v1[1]); w.w = cvt_pk_bf16(v1[2], v1[3]);
;                         *(u32x4*)(xb + off + bj * HALF) = w;
;                         ss += ((v0[0] * v0[0] + v0[1] * v0[1]) + (v0[2] * v0[2] + v0[3] * v0[3])) + ((v1[0] * v1[0] + v1[1] * v1[1]) + (v1[2] * v1[2] + v1[3] * v1[3])); } }
;                 if (xb) { ss += __shfl_xor(ss, 16); ss += __shfl_xor(ss, 32); if (fq == 0) ssq[(size_t)row * 16 + u.pn * 4 + wc] = ss; } }
.LBB0_663:
	s_or_b64 exec, exec, s[24:25]
	v_or_b32_e32 v112, 16, v146
	s_waitcnt lgkmcnt(0)
	v_ashrrev_i32_e32 v113, 31, v112
	v_lshlrev_b64 v[116:117], 10, v[112:113]
	v_lshl_add_u64 v[126:127], v[116:117], 0, v[144:145]
	v_readlane_b32 s48, v254, 3
	v_lshlrev_b64 v[156:157], 2, v[126:127]
	v_readlane_b32 s49, v254, 4
	v_readlane_b32 s24, v254, 39
	v_readlane_b32 s25, v254, 40
	v_lshl_add_u64 v[158:159], s[48:49], 0, v[156:157]
	global_load_dwordx4 v[116:119], v[158:159], off
	global_load_dwordx4 v[122:125], v[158:159], off offset:16
	v_lshl_add_u64 v[126:127], v[126:127], 1, s[24:25]
	v_lshl_add_u64 v[156:157], s[68:69], 0, v[156:157]
	v_readlane_b32 s50, v254, 5
	v_readlane_b32 s51, v254, 6
	v_readlane_b32 s52, v254, 7
	v_readlane_b32 s53, v254, 8
	v_readlane_b32 s54, v254, 9
	v_readlane_b32 s55, v254, 10
	v_readlane_b32 s56, v254, 11
	v_readlane_b32 s57, v254, 12
	v_readlane_b32 s58, v254, 13
	v_readlane_b32 s59, v254, 14
	v_readlane_b32 s60, v254, 15
	v_readlane_b32 s61, v254, 16
	v_readlane_b32 s62, v254, 17
	v_readlane_b32 s63, v254, 18
	s_waitcnt vmcnt(1)
	v_pk_add_f32 v[110:111], v[110:111], v[118:119]
	v_pk_add_f32 v[108:109], v[108:109], v[116:117]
	s_waitcnt vmcnt(0)
	v_pk_add_f32 v[106:107], v[106:107], v[124:125]
	v_pk_add_f32 v[104:105], v[104:105], v[122:123]
	v_cvt_pk_bf16_f32 v116, v108, v109
	v_cvt_pk_bf16_f32 v117, v110, v111
	v_cvt_pk_bf16_f32 v118, v104, v105
	v_cvt_pk_bf16_f32 v119, v106, v107
	v_lshl_add_u64 v[228:229], v[156:157], 0, v[230:231]
	v_lshl_add_u64 v[232:233], v[156:157], 0, v[244:245]
	s_nop 1
	v_mov_b32_dpp v236, v104 row_ror:8 row_mask:0xf bank_mask:0xf
	v_mov_b32_dpp v237, v105 row_ror:8 row_mask:0xf bank_mask:0xf
	v_mov_b32_dpp v238, v106 row_ror:8 row_mask:0xf bank_mask:0xf
	v_mov_b32_dpp v239, v107 row_ror:8 row_mask:0xf bank_mask:0xf
	v_mov_b32_dpp v240, v108 row_ror:8 row_mask:0xf bank_mask:0xf
	v_mov_b32_dpp v241, v109 row_ror:8 row_mask:0xf bank_mask:0xf
	v_mov_b32_dpp v242, v110 row_ror:8 row_mask:0xf bank_mask:0xf
	v_mov_b32_dpp v243, v111 row_ror:8 row_mask:0xf bank_mask:0xf
	s_nop 0
	v_cndmask_b32_e64 v236, v236, v108, s[98:99]
	v_cndmask_b32_e64 v237, v237, v109, s[98:99]
	v_cndmask_b32_e64 v238, v238, v110, s[98:99]
	v_cndmask_b32_e64 v239, v239, v111, s[98:99]
	v_cndmask_b32_e64 v240, v104, v240, s[98:99]
	v_cndmask_b32_e64 v241, v105, v241, s[98:99]
	v_cndmask_b32_e64 v242, v106, v242, s[98:99]
	v_cndmask_b32_e64 v243, v107, v243, s[98:99]
	global_store_dwordx4 v[228:229], v[236:239], off
	global_store_dwordx4 v[232:233], v[240:243], off
	global_store_dwordx4 v[126:127], v[116:119], off
	global_load_dwordx4 v[116:119], v[158:159], off offset:512
	s_nop 0
	global_load_dwordx4 v[122:125], v[158:159], off offset:528
	v_mul_f32_e32 v109, v109, v109
	v_mul_f32_e32 v111, v111, v111
	v_mul_f32_e32 v105, v105, v105
	v_mul_f32_e32 v107, v107, v107
	v_fmac_f32_e32 v109, v108, v108
	v_fmac_f32_e32 v111, v110, v110
	v_fmac_f32_e32 v105, v104, v104
	v_fmac_f32_e32 v107, v106, v106
	v_add_f32_e32 v104, v109, v111
	v_add_f32_e32 v105, v105, v107
	v_add_f32_e32 v108, v104, v105
	s_waitcnt vmcnt(1)
	v_pk_add_f32 v[102:103], v[102:103], v[118:119]
	v_pk_add_f32 v[100:101], v[100:101], v[116:117]
	s_waitcnt vmcnt(0)
	v_pk_add_f32 v[106:107], v[98:99], v[124:125]
	v_pk_add_f32 v[104:105], v[96:97], v[122:123]
	v_mul_f32_e32 v96, v101, v101
	v_mul_f32_e32 v97, v103, v103
	v_mul_f32_e32 v98, v105, v105
	v_mul_f32_e32 v99, v107, v107
	v_fmac_f32_e32 v96, v100, v100
	v_fmac_f32_e32 v97, v102, v102
	v_fmac_f32_e32 v98, v104, v104
	v_fmac_f32_e32 v99, v106, v106
	v_add_f32_e32 v96, v96, v97
	v_add_f32_e32 v97, v98, v99
	v_add_f32_e32 v96, v96, v97
	v_add_f32_e32 v96, v108, v96
	v_mov_b32_e32 v97, v96
	s_nop 1
	v_permlane16_swap_b32_e32 v97, v96
	v_lshl_add_u64 v[228:229], v[156:157], 0, v[230:231]
	v_lshl_add_u64 v[232:233], v[156:157], 0, v[244:245]
	s_nop 1
	v_mov_b32_dpp v236, v104 row_ror:8 row_mask:0xf bank_mask:0xf
	v_mov_b32_dpp v237, v105 row_ror:8 row_mask:0xf bank_mask:0xf
	v_mov_b32_dpp v238, v106 row_ror:8 row_mask:0xf bank_mask:0xf
	v_mov_b32_dpp v239, v107 row_ror:8 row_mask:0xf bank_mask:0xf
	v_mov_b32_dpp v240, v100 row_ror:8 row_mask:0xf bank_mask:0xf
	v_mov_b32_dpp v241, v101 row_ror:8 row_mask:0xf bank_mask:0xf
	v_mov_b32_dpp v242, v102 row_ror:8 row_mask:0xf bank_mask:0xf
	v_mov_b32_dpp v243, v103 row_ror:8 row_mask:0xf bank_mask:0xf
	s_nop 0
	v_cndmask_b32_e64 v236, v236, v100, s[98:99]
	v_cndmask_b32_e64 v237, v237, v101, s[98:99]
	v_cndmask_b32_e64 v238, v238, v102, s[98:99]
	v_cndmask_b32_e64 v239, v239, v103, s[98:99]
	v_cndmask_b32_e64 v240, v104, v240, s[98:99]
	v_cndmask_b32_e64 v241, v105, v241, s[98:99]
	v_cndmask_b32_e64 v242, v106, v242, s[98:99]
	v_cndmask_b32_e64 v243, v107, v243, s[98:99]
	global_store_dwordx4 v[228:229], v[236:239], off offset:512
	global_store_dwordx4 v[232:233], v[240:243], off offset:512
	v_cvt_pk_bf16_f32 v98, v100, v101
	v_cvt_pk_bf16_f32 v99, v102, v103
	v_cvt_pk_bf16_f32 v100, v104, v105
	s_waitcnt lgkmcnt(0)
	v_add_f32_e32 v96, v96, v97
	v_mov_b32_e32 v97, v96
	s_nop 1
	v_permlane32_swap_b32_e32 v97, v96
	v_cvt_pk_bf16_f32 v101, v106, v107
	global_store_dwordx4 v[126:127], v[98:101], off offset:256
	s_and_saveexec_b64 s[24:25], s[2:3]
	s_cbranch_execz .LBB0_665
	v_readlane_b32 s26, v254, 41
	s_waitcnt lgkmcnt(0)
	v_add_f32_e32 v98, v96, v97
	v_lshlrev_b64 v[96:97], 6, v[112:113]
	v_readlane_b32 s27, v254, 42
	s_lshl_b32 s6, s38, 2
	s_nop 0
	v_lshl_add_u64 v[96:97], s[26:27], 0, v[96:97]
	v_lshl_add_u64 v[96:97], s[22:23], 2, v[96:97]
	v_lshl_add_u64 v[96:97], v[96:97], 0, s[6:7]
	global_store_dword v[96:97], v98, off
; __device__ __forceinline__ unsigned cvt_pk_bf16(float lo, float hi) { const f32x2_t v = {lo, hi}; const bf16x2_t b = __builtin_convertvector(v, bf16x2_t); return __builtin_bit_cast(unsigned, b); }
;     __device__ __forceinline__ void operator()(const f32x4 (&acc)[2][2][4][2], const Unit& u, int wr, int wc, int fr, int fq, const PG8_LAS float*) const {
;     ...
;             for (int m = 0; m < 4; ++m) { const int row = row0 + ai * HALF + m * 16; const size_t off = (size_t)row * ldc + col0; float ss = 0.f;
; #pragma unroll
;                 for (int bj = 0; bj < 2; ++bj) {
;                     const f32x4 b0 = *(const f32x4*)(base + off + bj * HALF), b1 = *(const f32x4*)(base + off + bj * HALF + 4);
;                     const f32x4 v0 = b0 + acc[ai][bj][m][0], v1 = b1 + acc[ai][bj][m][1];
;                     *(f32x4*)(out + off + bj * HALF) = v0; *(f32x4*)(out + off + bj * HALF + 4) = v1;
;                     if (xb) { u32x4 w; w.x = cvt_pk_bf16(v0[0], v0[1]); w.y = cvt_pk_bf16(v0[2], v0[3]); w.z = cvt_pk_bf16(v1[0], v1[1]); w.w = cvt_pk_bf16(v1[2], v1[3]);
;                         *(u32x4*)(xb + off + bj * HALF) = w;
;                         ss += ((v0[0] * v0[0] + v0[1] * v0[1]) + (v0[2] * v0[2] + v0[3] * v0[3])) + ((v1[0] * v1[0] + v1[1] * v1[1]) + (v1[2] * v1[2] + v1[3] * v1[3])); } }
;                 if (xb) { ss += __shfl_xor(ss, 16); ss += __shfl_xor(ss, 32); if (fq == 0) ssq[(size_t)row * 16 + u.pn * 4 + wc] = ss; } }
.LBB0_665:
	s_or_b64 exec, exec, s[24:25]
	v_or_b32_e32 v96, 32, v146
	s_waitcnt lgkmcnt(0)
	v_ashrrev_i32_e32 v97, 31, v96
	v_lshlrev_b64 v[98:99], 10, v[96:97]
	v_lshl_add_u64 v[106:107], v[98:99], 0, v[144:145]
	v_readlane_b32 s48, v254, 3
	v_lshlrev_b64 v[108:109], 2, v[106:107]
	v_readlane_b32 s49, v254, 4
	v_readlane_b32 s24, v254, 39
	v_readlane_b32 s25, v254, 40
	v_lshl_add_u64 v[110:111], s[48:49], 0, v[108:109]
	global_load_dwordx4 v[98:101], v[110:111], off
	global_load_dwordx4 v[102:105], v[110:111], off offset:16
	v_lshl_add_u64 v[106:107], v[106:107], 1, s[24:25]
	v_lshl_add_u64 v[108:109], s[68:69], 0, v[108:109]
	v_readlane_b32 s50, v254, 5
	v_readlane_b32 s51, v254, 6
	v_readlane_b32 s52, v254, 7
	v_readlane_b32 s53, v254, 8
	v_readlane_b32 s54, v254, 9
	v_readlane_b32 s55, v254, 10
	v_readlane_b32 s56, v254, 11
	v_readlane_b32 s57, v254, 12
	v_readlane_b32 s58, v254, 13
	v_readlane_b32 s59, v254, 14
	v_readlane_b32 s60, v254, 15
	v_readlane_b32 s61, v254, 16
	v_readlane_b32 s62, v254, 17
	v_readlane_b32 s63, v254, 18
	s_waitcnt vmcnt(1)
	v_pk_add_f32 v[94:95], v[94:95], v[100:101]
	v_pk_add_f32 v[92:93], v[92:93], v[98:99]
	s_waitcnt vmcnt(0)
	v_pk_add_f32 v[90:91], v[90:91], v[104:105]
	v_pk_add_f32 v[88:89], v[88:89], v[102:103]
	v_cvt_pk_bf16_f32 v98, v92, v93
	v_cvt_pk_bf16_f32 v99, v94, v95
	v_cvt_pk_bf16_f32 v100, v88, v89
	v_cvt_pk_bf16_f32 v101, v90, v91
	v_lshl_add_u64 v[228:229], v[108:109], 0, v[230:231]
	v_lshl_add_u64 v[232:233], v[108:109], 0, v[244:245]
	s_nop 1
	v_mov_b32_dpp v236, v88 row_ror:8 row_mask:0xf bank_mask:0xf
	v_mov_b32_dpp v237, v89 row_ror:8 row_mask:0xf bank_mask:0xf
	v_mov_b32_dpp v238, v90 row_ror:8 row_mask:0xf bank_mask:0xf
	v_mov_b32_dpp v239, v91 row_ror:8 row_mask:0xf bank_mask:0xf
	v_mov_b32_dpp v240, v92 row_ror:8 row_mask:0xf bank_mask:0xf
	v_mov_b32_dpp v241, v93 row_ror:8 row_mask:0xf bank_mask:0xf
	v_mov_b32_dpp v242, v94 row_ror:8 row_mask:0xf bank_mask:0xf
	v_mov_b32_dpp v243, v95 row_ror:8 row_mask:0xf bank_mask:0xf
	s_nop 0
	v_cndmask_b32_e64 v236, v236, v92, s[98:99]
	v_cndmask_b32_e64 v237, v237, v93, s[98:99]
	v_cndmask_b32_e64 v238, v238, v94, s[98:99]
	v_cndmask_b32_e64 v239, v239, v95, s[98:99]
	v_cndmask_b32_e64 v240, v88, v240, s[98:99]
	v_cndmask_b32_e64 v241, v89, v241, s[98:99]
	v_cndmask_b32_e64 v242, v90, v242, s[98:99]
	v_cndmask_b32_e64 v243, v91, v243, s[98:99]
	global_store_dwordx4 v[228:229], v[236:239], off
	global_store_dwordx4 v[232:233], v[240:243], off
	global_store_dwordx4 v[106:107], v[98:101], off
	global_load_dwordx4 v[98:101], v[110:111], off offset:512
	s_nop 0
	global_load_dwordx4 v[102:105], v[110:111], off offset:528
	v_mul_f32_e32 v93, v93, v93
	v_mul_f32_e32 v95, v95, v95
	v_mul_f32_e32 v89, v89, v89
	v_mul_f32_e32 v91, v91, v91
	v_fmac_f32_e32 v93, v92, v92
	v_fmac_f32_e32 v95, v94, v94
	v_fmac_f32_e32 v89, v88, v88
	v_fmac_f32_e32 v91, v90, v90
	v_add_f32_e32 v88, v93, v95
	v_add_f32_e32 v89, v89, v91
	v_add_f32_e32 v92, v88, v89
	s_waitcnt vmcnt(1)
	v_pk_add_f32 v[86:87], v[86:87], v[100:101]
	v_pk_add_f32 v[84:85], v[84:85], v[98:99]
	s_waitcnt vmcnt(0)
	v_pk_add_f32 v[90:91], v[82:83], v[104:105]
	v_pk_add_f32 v[88:89], v[80:81], v[102:103]
	v_mul_f32_e32 v80, v85, v85
	v_mul_f32_e32 v81, v87, v87
	v_mul_f32_e32 v82, v89, v89
	v_mul_f32_e32 v83, v91, v91
	v_fmac_f32_e32 v80, v84, v84
	v_fmac_f32_e32 v81, v86, v86
	v_fmac_f32_e32 v82, v88, v88
	v_fmac_f32_e32 v83, v90, v90
	v_add_f32_e32 v80, v80, v81
	v_add_f32_e32 v81, v82, v83
	v_add_f32_e32 v80, v80, v81
	v_add_f32_e32 v80, v92, v80
	v_mov_b32_e32 v81, v80
	s_nop 1
	v_permlane16_swap_b32_e32 v81, v80
	v_lshl_add_u64 v[228:229], v[108:109], 0, v[230:231]
	v_lshl_add_u64 v[232:233], v[108:109], 0, v[244:245]
	s_nop 1
	v_mov_b32_dpp v236, v88 row_ror:8 row_mask:0xf bank_mask:0xf
	v_mov_b32_dpp v237, v89 row_ror:8 row_mask:0xf bank_mask:0xf
	v_mov_b32_dpp v238, v90 row_ror:8 row_mask:0xf bank_mask:0xf
	v_mov_b32_dpp v239, v91 row_ror:8 row_mask:0xf bank_mask:0xf
	v_mov_b32_dpp v240, v84 row_ror:8 row_mask:0xf bank_mask:0xf
	v_mov_b32_dpp v241, v85 row_ror:8 row_mask:0xf bank_mask:0xf
	v_mov_b32_dpp v242, v86 row_ror:8 row_mask:0xf bank_mask:0xf
	v_mov_b32_dpp v243, v87 row_ror:8 row_mask:0xf bank_mask:0xf
	s_nop 0
	v_cndmask_b32_e64 v236, v236, v84, s[98:99]
	v_cndmask_b32_e64 v237, v237, v85, s[98:99]
	v_cndmask_b32_e64 v238, v238, v86, s[98:99]
	v_cndmask_b32_e64 v239, v239, v87, s[98:99]
	v_cndmask_b32_e64 v240, v88, v240, s[98:99]
	v_cndmask_b32_e64 v241, v89, v241, s[98:99]
	v_cndmask_b32_e64 v242, v90, v242, s[98:99]
	v_cndmask_b32_e64 v243, v91, v243, s[98:99]
	global_store_dwordx4 v[228:229], v[236:239], off offset:512
	global_store_dwordx4 v[232:233], v[240:243], off offset:512
	v_cvt_pk_bf16_f32 v82, v84, v85
	v_cvt_pk_bf16_f32 v83, v86, v87
	v_cvt_pk_bf16_f32 v84, v88, v89
	s_waitcnt lgkmcnt(0)
	v_add_f32_e32 v80, v80, v81
	v_mov_b32_e32 v81, v80
	s_nop 1
	v_permlane32_swap_b32_e32 v81, v80
	v_cvt_pk_bf16_f32 v85, v90, v91
	global_store_dwordx4 v[106:107], v[82:85], off offset:256
	s_and_saveexec_b64 s[24:25], s[2:3]
	s_cbranch_execz .LBB0_667
	v_readlane_b32 s26, v254, 41
	s_waitcnt lgkmcnt(0)
	v_add_f32_e32 v82, v80, v81
	v_lshlrev_b64 v[80:81], 6, v[96:97]
	v_readlane_b32 s27, v254, 42
	s_lshl_b32 s6, s38, 2
	s_nop 0
	v_lshl_add_u64 v[80:81], s[26:27], 0, v[80:81]
	v_lshl_add_u64 v[80:81], s[22:23], 2, v[80:81]
	v_lshl_add_u64 v[80:81], v[80:81], 0, s[6:7]
	global_store_dword v[80:81], v82, off
; __device__ __forceinline__ unsigned cvt_pk_bf16(float lo, float hi) { const f32x2_t v = {lo, hi}; const bf16x2_t b = __builtin_convertvector(v, bf16x2_t); return __builtin_bit_cast(unsigned, b); }
;     __device__ __forceinline__ void operator()(const f32x4 (&acc)[2][2][4][2], const Unit& u, int wr, int wc, int fr, int fq, const PG8_LAS float*) const {
;     ...
;             for (int m = 0; m < 4; ++m) { const int row = row0 + ai * HALF + m * 16; const size_t off = (size_t)row * ldc + col0; float ss = 0.f;
; #pragma unroll
;                 for (int bj = 0; bj < 2; ++bj) {
;                     const f32x4 b0 = *(const f32x4*)(base + off + bj * HALF), b1 = *(const f32x4*)(base + off + bj * HALF + 4);
;                     const f32x4 v0 = b0 + acc[ai][bj][m][0], v1 = b1 + acc[ai][bj][m][1];
;                     *(f32x4*)(out + off + bj * HALF) = v0; *(f32x4*)(out + off + bj * HALF + 4) = v1;
;                     if (xb) { u32x4 w; w.x = cvt_pk_bf16(v0[0], v0[1]); w.y = cvt_pk_bf16(v0[2], v0[3]); w.z = cvt_pk_bf16(v1[0], v1[1]); w.w = cvt_pk_bf16(v1[2], v1[3]);
;                         *(u32x4*)(xb + off + bj * HALF) = w;
;                         ss += ((v0[0] * v0[0] + v0[1] * v0[1]) + (v0[2] * v0[2] + v0[3] * v0[3])) + ((v1[0] * v1[0] + v1[1] * v1[1]) + (v1[2] * v1[2] + v1[3] * v1[3])); } }
;                 if (xb) { ss += __shfl_xor(ss, 16); ss += __shfl_xor(ss, 32); if (fq == 0) ssq[(size_t)row * 16 + u.pn * 4 + wc] = ss; } }
.LBB0_667:
	s_or_b64 exec, exec, s[24:25]
	v_or_b32_e32 v80, 48, v146
	s_waitcnt lgkmcnt(0)
	v_ashrrev_i32_e32 v81, 31, v80
	v_lshlrev_b64 v[82:83], 10, v[80:81]
	v_lshl_add_u64 v[90:91], v[82:83], 0, v[144:145]
	v_readlane_b32 s48, v254, 3
	v_lshlrev_b64 v[92:93], 2, v[90:91]
	v_readlane_b32 s49, v254, 4
	v_readlane_b32 s24, v254, 39
	v_readlane_b32 s25, v254, 40
	v_lshl_add_u64 v[94:95], s[48:49], 0, v[92:93]
	global_load_dwordx4 v[82:85], v[94:95], off
	global_load_dwordx4 v[86:89], v[94:95], off offset:16
	v_lshl_add_u64 v[90:91], v[90:91], 1, s[24:25]
	v_lshl_add_u64 v[92:93], s[68:69], 0, v[92:93]
	v_readlane_b32 s50, v254, 5
	v_readlane_b32 s51, v254, 6
	v_readlane_b32 s52, v254, 7
	v_readlane_b32 s53, v254, 8
	v_readlane_b32 s54, v254, 9
	v_readlane_b32 s55, v254, 10
	v_readlane_b32 s56, v254, 11
	v_readlane_b32 s57, v254, 12
	v_readlane_b32 s58, v254, 13
	v_readlane_b32 s59, v254, 14
	v_readlane_b32 s60, v254, 15
	v_readlane_b32 s61, v254, 16
	v_readlane_b32 s62, v254, 17
	v_readlane_b32 s63, v254, 18
	s_waitcnt vmcnt(1)
	v_pk_add_f32 v[78:79], v[78:79], v[84:85]
	v_pk_add_f32 v[76:77], v[76:77], v[82:83]
	s_waitcnt vmcnt(0)
	v_pk_add_f32 v[74:75], v[74:75], v[88:89]
	v_pk_add_f32 v[72:73], v[72:73], v[86:87]
	v_cvt_pk_bf16_f32 v82, v76, v77
	v_cvt_pk_bf16_f32 v83, v78, v79
	v_cvt_pk_bf16_f32 v84, v72, v73
	v_cvt_pk_bf16_f32 v85, v74, v75
	v_lshl_add_u64 v[228:229], v[92:93], 0, v[230:231]
	v_lshl_add_u64 v[232:233], v[92:93], 0, v[244:245]
	s_nop 1
	v_mov_b32_dpp v236, v72 row_ror:8 row_mask:0xf bank_mask:0xf
	v_mov_b32_dpp v237, v73 row_ror:8 row_mask:0xf bank_mask:0xf
	v_mov_b32_dpp v238, v74 row_ror:8 row_mask:0xf bank_mask:0xf
	v_mov_b32_dpp v239, v75 row_ror:8 row_mask:0xf bank_mask:0xf
	v_mov_b32_dpp v240, v76 row_ror:8 row_mask:0xf bank_mask:0xf
	v_mov_b32_dpp v241, v77 row_ror:8 row_mask:0xf bank_mask:0xf
	v_mov_b32_dpp v242, v78 row_ror:8 row_mask:0xf bank_mask:0xf
	v_mov_b32_dpp v243, v79 row_ror:8 row_mask:0xf bank_mask:0xf
	s_nop 0
	v_cndmask_b32_e64 v236, v236, v76, s[98:99]
	v_cndmask_b32_e64 v237, v237, v77, s[98:99]
	v_cndmask_b32_e64 v238, v238, v78, s[98:99]
	v_cndmask_b32_e64 v239, v239, v79, s[98:99]
	v_cndmask_b32_e64 v240, v72, v240, s[98:99]
	v_cndmask_b32_e64 v241, v73, v241, s[98:99]
	v_cndmask_b32_e64 v242, v74, v242, s[98:99]
	v_cndmask_b32_e64 v243, v75, v243, s[98:99]
	global_store_dwordx4 v[228:229], v[236:239], off
	global_store_dwordx4 v[232:233], v[240:243], off
	global_store_dwordx4 v[90:91], v[82:85], off
	global_load_dwordx4 v[82:85], v[94:95], off offset:512
	s_nop 0
	global_load_dwordx4 v[86:89], v[94:95], off offset:528
	v_mul_f32_e32 v77, v77, v77
	v_mul_f32_e32 v79, v79, v79
	v_mul_f32_e32 v73, v73, v73
	v_mul_f32_e32 v75, v75, v75
	v_fmac_f32_e32 v77, v76, v76
	v_fmac_f32_e32 v79, v78, v78
	v_fmac_f32_e32 v73, v72, v72
	v_fmac_f32_e32 v75, v74, v74
	v_add_f32_e32 v72, v77, v79
	v_add_f32_e32 v73, v73, v75
	v_add_f32_e32 v76, v72, v73
	s_waitcnt vmcnt(1)
	v_pk_add_f32 v[70:71], v[70:71], v[84:85]
	v_pk_add_f32 v[68:69], v[68:69], v[82:83]
	s_waitcnt vmcnt(0)
	v_pk_add_f32 v[74:75], v[66:67], v[88:89]
	v_pk_add_f32 v[72:73], v[64:65], v[86:87]
	v_mul_f32_e32 v64, v69, v69
	v_mul_f32_e32 v65, v71, v71
	v_mul_f32_e32 v66, v73, v73
	v_mul_f32_e32 v67, v75, v75
	v_fmac_f32_e32 v64, v68, v68
	v_fmac_f32_e32 v65, v70, v70
	v_fmac_f32_e32 v66, v72, v72
	v_fmac_f32_e32 v67, v74, v74
	v_add_f32_e32 v64, v64, v65
	v_add_f32_e32 v65, v66, v67
	v_add_f32_e32 v64, v64, v65
	v_add_f32_e32 v64, v76, v64
	v_mov_b32_e32 v65, v64
	s_nop 1
	v_permlane16_swap_b32_e32 v65, v64
	v_lshl_add_u64 v[228:229], v[92:93], 0, v[230:231]
	v_lshl_add_u64 v[232:233], v[92:93], 0, v[244:245]
	s_nop 1
	v_mov_b32_dpp v236, v72 row_ror:8 row_mask:0xf bank_mask:0xf
	v_mov_b32_dpp v237, v73 row_ror:8 row_mask:0xf bank_mask:0xf
	v_mov_b32_dpp v238, v74 row_ror:8 row_mask:0xf bank_mask:0xf
	v_mov_b32_dpp v239, v75 row_ror:8 row_mask:0xf bank_mask:0xf
	v_mov_b32_dpp v240, v68 row_ror:8 row_mask:0xf bank_mask:0xf
	v_mov_b32_dpp v241, v69 row_ror:8 row_mask:0xf bank_mask:0xf
	v_mov_b32_dpp v242, v70 row_ror:8 row_mask:0xf bank_mask:0xf
	v_mov_b32_dpp v243, v71 row_ror:8 row_mask:0xf bank_mask:0xf
	s_nop 0
	v_cndmask_b32_e64 v236, v236, v68, s[98:99]
	v_cndmask_b32_e64 v237, v237, v69, s[98:99]
	v_cndmask_b32_e64 v238, v238, v70, s[98:99]
	v_cndmask_b32_e64 v239, v239, v71, s[98:99]
	v_cndmask_b32_e64 v240, v72, v240, s[98:99]
	v_cndmask_b32_e64 v241, v73, v241, s[98:99]
	v_cndmask_b32_e64 v242, v74, v242, s[98:99]
	v_cndmask_b32_e64 v243, v75, v243, s[98:99]
	global_store_dwordx4 v[228:229], v[236:239], off offset:512
	global_store_dwordx4 v[232:233], v[240:243], off offset:512
	v_cvt_pk_bf16_f32 v66, v68, v69
	v_cvt_pk_bf16_f32 v67, v70, v71
	v_cvt_pk_bf16_f32 v68, v72, v73
	s_waitcnt lgkmcnt(0)
	v_add_f32_e32 v64, v64, v65
	v_mov_b32_e32 v65, v64
	s_nop 1
	v_permlane32_swap_b32_e32 v65, v64
	v_cvt_pk_bf16_f32 v69, v74, v75
	global_store_dwordx4 v[90:91], v[66:69], off offset:256
	s_and_saveexec_b64 s[24:25], s[2:3]
	s_cbranch_execz .LBB0_669
	v_readlane_b32 s26, v254, 41
	s_waitcnt lgkmcnt(0)
	v_add_f32_e32 v66, v64, v65
	v_lshlrev_b64 v[64:65], 6, v[80:81]
	v_readlane_b32 s27, v254, 42
	s_lshl_b32 s6, s38, 2
	s_nop 0
	v_lshl_add_u64 v[64:65], s[26:27], 0, v[64:65]
	v_lshl_add_u64 v[64:65], s[22:23], 2, v[64:65]
	v_lshl_add_u64 v[64:65], v[64:65], 0, s[6:7]
	global_store_dword v[64:65], v66, off
; __device__ __forceinline__ unsigned cvt_pk_bf16(float lo, float hi) { const f32x2_t v = {lo, hi}; const bf16x2_t b = __builtin_convertvector(v, bf16x2_t); return __builtin_bit_cast(unsigned, b); }
;     __device__ __forceinline__ void operator()(const f32x4 (&acc)[2][2][4][2], const Unit& u, int wr, int wc, int fr, int fq, const PG8_LAS float*) const {
;     ...
;             for (int m = 0; m < 4; ++m) { const int row = row0 + ai * HALF + m * 16; const size_t off = (size_t)row * ldc + col0; float ss = 0.f;
; #pragma unroll
;                 for (int bj = 0; bj < 2; ++bj) {
;                     const f32x4 b0 = *(const f32x4*)(base + off + bj * HALF), b1 = *(const f32x4*)(base + off + bj * HALF + 4);
;                     const f32x4 v0 = b0 + acc[ai][bj][m][0], v1 = b1 + acc[ai][bj][m][1];
;                     *(f32x4*)(out + off + bj * HALF) = v0; *(f32x4*)(out + off + bj * HALF + 4) = v1;
;                     if (xb) { u32x4 w; w.x = cvt_pk_bf16(v0[0], v0[1]); w.y = cvt_pk_bf16(v0[2], v0[3]); w.z = cvt_pk_bf16(v1[0], v1[1]); w.w = cvt_pk_bf16(v1[2], v1[3]);
;                         *(u32x4*)(xb + off + bj * HALF) = w;
;                         ss += ((v0[0] * v0[0] + v0[1] * v0[1]) + (v0[2] * v0[2] + v0[3] * v0[3])) + ((v1[0] * v1[0] + v1[1] * v1[1]) + (v1[2] * v1[2] + v1[3] * v1[3])); } }
;                 if (xb) { ss += __shfl_xor(ss, 16); ss += __shfl_xor(ss, 32); if (fq == 0) ssq[(size_t)row * 16 + u.pn * 4 + wc] = ss; } }
.LBB0_669:
	s_or_b64 exec, exec, s[24:25]
	v_add_u32_e32 v64, 0x80, v146
	s_waitcnt lgkmcnt(0)
	v_ashrrev_i32_e32 v65, 31, v64
	v_lshlrev_b64 v[66:67], 10, v[64:65]
	v_lshl_add_u64 v[74:75], v[66:67], 0, v[144:145]
	v_readlane_b32 s48, v254, 3
	v_lshlrev_b64 v[76:77], 2, v[74:75]
	v_readlane_b32 s49, v254, 4
	v_readlane_b32 s24, v254, 39
	v_readlane_b32 s25, v254, 40
	v_lshl_add_u64 v[78:79], s[48:49], 0, v[76:77]
	global_load_dwordx4 v[66:69], v[78:79], off
	global_load_dwordx4 v[70:73], v[78:79], off offset:16
	v_lshl_add_u64 v[74:75], v[74:75], 1, s[24:25]
	v_lshl_add_u64 v[76:77], s[68:69], 0, v[76:77]
	v_readlane_b32 s50, v254, 5
	v_readlane_b32 s51, v254, 6
	v_readlane_b32 s52, v254, 7
	v_readlane_b32 s53, v254, 8
	v_readlane_b32 s54, v254, 9
	v_readlane_b32 s55, v254, 10
	v_readlane_b32 s56, v254, 11
	v_readlane_b32 s57, v254, 12
	v_readlane_b32 s58, v254, 13
	v_readlane_b32 s59, v254, 14
	v_readlane_b32 s60, v254, 15
	v_readlane_b32 s61, v254, 16
	v_readlane_b32 s62, v254, 17
	v_readlane_b32 s63, v254, 18
	s_waitcnt vmcnt(1)
	v_pk_add_f32 v[62:63], v[62:63], v[68:69]
	v_pk_add_f32 v[60:61], v[60:61], v[66:67]
	s_waitcnt vmcnt(0)
	v_pk_add_f32 v[58:59], v[58:59], v[72:73]
	v_pk_add_f32 v[56:57], v[56:57], v[70:71]
	v_cvt_pk_bf16_f32 v66, v60, v61
	v_cvt_pk_bf16_f32 v67, v62, v63
	v_cvt_pk_bf16_f32 v68, v56, v57
	v_cvt_pk_bf16_f32 v69, v58, v59
	v_lshl_add_u64 v[228:229], v[76:77], 0, v[230:231]
	v_lshl_add_u64 v[232:233], v[76:77], 0, v[244:245]
	s_nop 1
	v_mov_b32_dpp v236, v56 row_ror:8 row_mask:0xf bank_mask:0xf
	v_mov_b32_dpp v237, v57 row_ror:8 row_mask:0xf bank_mask:0xf
	v_mov_b32_dpp v238, v58 row_ror:8 row_mask:0xf bank_mask:0xf
	v_mov_b32_dpp v239, v59 row_ror:8 row_mask:0xf bank_mask:0xf
	v_mov_b32_dpp v240, v60 row_ror:8 row_mask:0xf bank_mask:0xf
	v_mov_b32_dpp v241, v61 row_ror:8 row_mask:0xf bank_mask:0xf
	v_mov_b32_dpp v242, v62 row_ror:8 row_mask:0xf bank_mask:0xf
	v_mov_b32_dpp v243, v63 row_ror:8 row_mask:0xf bank_mask:0xf
	s_nop 0
	v_cndmask_b32_e64 v236, v236, v60, s[98:99]
	v_cndmask_b32_e64 v237, v237, v61, s[98:99]
	v_cndmask_b32_e64 v238, v238, v62, s[98:99]
	v_cndmask_b32_e64 v239, v239, v63, s[98:99]
	v_cndmask_b32_e64 v240, v56, v240, s[98:99]
	v_cndmask_b32_e64 v241, v57, v241, s[98:99]
	v_cndmask_b32_e64 v242, v58, v242, s[98:99]
	v_cndmask_b32_e64 v243, v59, v243, s[98:99]
	global_store_dwordx4 v[228:229], v[236:239], off
	global_store_dwordx4 v[232:233], v[240:243], off
	global_store_dwordx4 v[74:75], v[66:69], off
	global_load_dwordx4 v[66:69], v[78:79], off offset:512
	s_nop 0
	global_load_dwordx4 v[70:73], v[78:79], off offset:528
	v_mul_f32_e32 v61, v61, v61
	v_mul_f32_e32 v63, v63, v63
	v_mul_f32_e32 v57, v57, v57
	v_mul_f32_e32 v59, v59, v59
	v_fmac_f32_e32 v61, v60, v60
	v_fmac_f32_e32 v63, v62, v62
	v_fmac_f32_e32 v57, v56, v56
	v_fmac_f32_e32 v59, v58, v58
	v_add_f32_e32 v56, v61, v63
	v_add_f32_e32 v57, v57, v59
	v_add_f32_e32 v60, v56, v57
	s_waitcnt vmcnt(1)
	v_pk_add_f32 v[54:55], v[54:55], v[68:69]
	v_pk_add_f32 v[52:53], v[52:53], v[66:67]
	s_waitcnt vmcnt(0)
	v_pk_add_f32 v[58:59], v[50:51], v[72:73]
	v_pk_add_f32 v[56:57], v[48:49], v[70:71]
	v_mul_f32_e32 v48, v53, v53
	v_mul_f32_e32 v49, v55, v55
	v_mul_f32_e32 v50, v57, v57
	v_mul_f32_e32 v51, v59, v59
	v_fmac_f32_e32 v48, v52, v52
	v_fmac_f32_e32 v49, v54, v54
	v_fmac_f32_e32 v50, v56, v56
	v_fmac_f32_e32 v51, v58, v58
	v_add_f32_e32 v48, v48, v49
	v_add_f32_e32 v49, v50, v51
	v_add_f32_e32 v48, v48, v49
	v_add_f32_e32 v48, v60, v48
	v_mov_b32_e32 v49, v48
	s_nop 1
	v_permlane16_swap_b32_e32 v49, v48
	v_lshl_add_u64 v[228:229], v[76:77], 0, v[230:231]
	v_lshl_add_u64 v[232:233], v[76:77], 0, v[244:245]
	s_nop 1
	v_mov_b32_dpp v236, v56 row_ror:8 row_mask:0xf bank_mask:0xf
	v_mov_b32_dpp v237, v57 row_ror:8 row_mask:0xf bank_mask:0xf
	v_mov_b32_dpp v238, v58 row_ror:8 row_mask:0xf bank_mask:0xf
	v_mov_b32_dpp v239, v59 row_ror:8 row_mask:0xf bank_mask:0xf
	v_mov_b32_dpp v240, v52 row_ror:8 row_mask:0xf bank_mask:0xf
	v_mov_b32_dpp v241, v53 row_ror:8 row_mask:0xf bank_mask:0xf
	v_mov_b32_dpp v242, v54 row_ror:8 row_mask:0xf bank_mask:0xf
	v_mov_b32_dpp v243, v55 row_ror:8 row_mask:0xf bank_mask:0xf
	s_nop 0
	v_cndmask_b32_e64 v236, v236, v52, s[98:99]
	v_cndmask_b32_e64 v237, v237, v53, s[98:99]
	v_cndmask_b32_e64 v238, v238, v54, s[98:99]
	v_cndmask_b32_e64 v239, v239, v55, s[98:99]
	v_cndmask_b32_e64 v240, v56, v240, s[98:99]
	v_cndmask_b32_e64 v241, v57, v241, s[98:99]
	v_cndmask_b32_e64 v242, v58, v242, s[98:99]
	v_cndmask_b32_e64 v243, v59, v243, s[98:99]
	global_store_dwordx4 v[228:229], v[236:239], off offset:512
	global_store_dwordx4 v[232:233], v[240:243], off offset:512
	v_cvt_pk_bf16_f32 v50, v52, v53
	v_cvt_pk_bf16_f32 v51, v54, v55
	v_cvt_pk_bf16_f32 v52, v56, v57
	s_waitcnt lgkmcnt(0)
	v_add_f32_e32 v48, v48, v49
	v_mov_b32_e32 v49, v48
	s_nop 1
	v_permlane32_swap_b32_e32 v49, v48
	v_cvt_pk_bf16_f32 v53, v58, v59
	global_store_dwordx4 v[74:75], v[50:53], off offset:256
	s_and_saveexec_b64 s[24:25], s[2:3]
	s_cbranch_execz .LBB0_671
	v_readlane_b32 s26, v254, 41
	s_waitcnt lgkmcnt(0)
	v_add_f32_e32 v50, v48, v49
	v_lshlrev_b64 v[48:49], 6, v[64:65]
	v_readlane_b32 s27, v254, 42
	s_lshl_b32 s6, s38, 2
	s_nop 0
	v_lshl_add_u64 v[48:49], s[26:27], 0, v[48:49]
	v_lshl_add_u64 v[48:49], s[22:23], 2, v[48:49]
	v_lshl_add_u64 v[48:49], v[48:49], 0, s[6:7]
	global_store_dword v[48:49], v50, off
; __device__ __forceinline__ unsigned cvt_pk_bf16(float lo, float hi) { const f32x2_t v = {lo, hi}; const bf16x2_t b = __builtin_convertvector(v, bf16x2_t); return __builtin_bit_cast(unsigned, b); }
;     __device__ __forceinline__ void operator()(const f32x4 (&acc)[2][2][4][2], const Unit& u, int wr, int wc, int fr, int fq, const PG8_LAS float*) const {
;     ...
;             for (int m = 0; m < 4; ++m) { const int row = row0 + ai * HALF + m * 16; const size_t off = (size_t)row * ldc + col0; float ss = 0.f;
; #pragma unroll
;                 for (int bj = 0; bj < 2; ++bj) {
;                     const f32x4 b0 = *(const f32x4*)(base + off + bj * HALF), b1 = *(const f32x4*)(base + off + bj * HALF + 4);
;                     const f32x4 v0 = b0 + acc[ai][bj][m][0], v1 = b1 + acc[ai][bj][m][1];
;                     *(f32x4*)(out + off + bj * HALF) = v0; *(f32x4*)(out + off + bj * HALF + 4) = v1;
;                     if (xb) { u32x4 w; w.x = cvt_pk_bf16(v0[0], v0[1]); w.y = cvt_pk_bf16(v0[2], v0[3]); w.z = cvt_pk_bf16(v1[0], v1[1]); w.w = cvt_pk_bf16(v1[2], v1[3]);
;                         *(u32x4*)(xb + off + bj * HALF) = w;
;                         ss += ((v0[0] * v0[0] + v0[1] * v0[1]) + (v0[2] * v0[2] + v0[3] * v0[3])) + ((v1[0] * v1[0] + v1[1] * v1[1]) + (v1[2] * v1[2] + v1[3] * v1[3])); } }
;                 if (xb) { ss += __shfl_xor(ss, 16); ss += __shfl_xor(ss, 32); if (fq == 0) ssq[(size_t)row * 16 + u.pn * 4 + wc] = ss; } }
.LBB0_671:
	s_or_b64 exec, exec, s[24:25]
	v_add_u32_e32 v48, 0x90, v146
	s_waitcnt lgkmcnt(0)
	v_ashrrev_i32_e32 v49, 31, v48
	v_lshlrev_b64 v[50:51], 10, v[48:49]
	v_lshl_add_u64 v[58:59], v[50:51], 0, v[144:145]
	v_readlane_b32 s48, v254, 3
	v_lshlrev_b64 v[60:61], 2, v[58:59]
	v_readlane_b32 s49, v254, 4
	v_readlane_b32 s24, v254, 39
	v_readlane_b32 s25, v254, 40
	v_lshl_add_u64 v[62:63], s[48:49], 0, v[60:61]
	global_load_dwordx4 v[50:53], v[62:63], off
	global_load_dwordx4 v[54:57], v[62:63], off offset:16
	v_lshl_add_u64 v[58:59], v[58:59], 1, s[24:25]
	v_lshl_add_u64 v[60:61], s[68:69], 0, v[60:61]
	v_readlane_b32 s50, v254, 5
	v_readlane_b32 s51, v254, 6
	v_readlane_b32 s52, v254, 7
	v_readlane_b32 s53, v254, 8
	v_readlane_b32 s54, v254, 9
	v_readlane_b32 s55, v254, 10
	v_readlane_b32 s56, v254, 11
	v_readlane_b32 s57, v254, 12
	v_readlane_b32 s58, v254, 13
	v_readlane_b32 s59, v254, 14
	v_readlane_b32 s60, v254, 15
	v_readlane_b32 s61, v254, 16
	v_readlane_b32 s62, v254, 17
	v_readlane_b32 s63, v254, 18
	s_waitcnt vmcnt(1)
	v_pk_add_f32 v[46:47], v[46:47], v[52:53]
	v_pk_add_f32 v[44:45], v[44:45], v[50:51]
	s_waitcnt vmcnt(0)
	v_pk_add_f32 v[42:43], v[42:43], v[56:57]
	v_pk_add_f32 v[40:41], v[40:41], v[54:55]
	v_cvt_pk_bf16_f32 v50, v44, v45
	v_cvt_pk_bf16_f32 v51, v46, v47
	v_cvt_pk_bf16_f32 v52, v40, v41
	v_cvt_pk_bf16_f32 v53, v42, v43
	v_lshl_add_u64 v[228:229], v[60:61], 0, v[230:231]
	v_lshl_add_u64 v[232:233], v[60:61], 0, v[244:245]
	s_nop 1
	v_mov_b32_dpp v236, v40 row_ror:8 row_mask:0xf bank_mask:0xf
	v_mov_b32_dpp v237, v41 row_ror:8 row_mask:0xf bank_mask:0xf
	v_mov_b32_dpp v238, v42 row_ror:8 row_mask:0xf bank_mask:0xf
	v_mov_b32_dpp v239, v43 row_ror:8 row_mask:0xf bank_mask:0xf
	v_mov_b32_dpp v240, v44 row_ror:8 row_mask:0xf bank_mask:0xf
	v_mov_b32_dpp v241, v45 row_ror:8 row_mask:0xf bank_mask:0xf
	v_mov_b32_dpp v242, v46 row_ror:8 row_mask:0xf bank_mask:0xf
	v_mov_b32_dpp v243, v47 row_ror:8 row_mask:0xf bank_mask:0xf
	s_nop 0
	v_cndmask_b32_e64 v236, v236, v44, s[98:99]
	v_cndmask_b32_e64 v237, v237, v45, s[98:99]
	v_cndmask_b32_e64 v238, v238, v46, s[98:99]
	v_cndmask_b32_e64 v239, v239, v47, s[98:99]
	v_cndmask_b32_e64 v240, v40, v240, s[98:99]
	v_cndmask_b32_e64 v241, v41, v241, s[98:99]
	v_cndmask_b32_e64 v242, v42, v242, s[98:99]
	v_cndmask_b32_e64 v243, v43, v243, s[98:99]
	global_store_dwordx4 v[228:229], v[236:239], off
	global_store_dwordx4 v[232:233], v[240:243], off
	global_store_dwordx4 v[58:59], v[50:53], off
	global_load_dwordx4 v[50:53], v[62:63], off offset:512
	s_nop 0
	global_load_dwordx4 v[54:57], v[62:63], off offset:528
	v_mul_f32_e32 v45, v45, v45
	v_mul_f32_e32 v47, v47, v47
	v_mul_f32_e32 v41, v41, v41
	v_mul_f32_e32 v43, v43, v43
	v_fmac_f32_e32 v45, v44, v44
	v_fmac_f32_e32 v47, v46, v46
	v_fmac_f32_e32 v41, v40, v40
	v_fmac_f32_e32 v43, v42, v42
	v_add_f32_e32 v40, v45, v47
	v_add_f32_e32 v41, v41, v43
	v_add_f32_e32 v44, v40, v41
	s_waitcnt vmcnt(1)
	v_pk_add_f32 v[38:39], v[38:39], v[52:53]
	v_pk_add_f32 v[36:37], v[36:37], v[50:51]
	s_waitcnt vmcnt(0)
	v_pk_add_f32 v[42:43], v[34:35], v[56:57]
	v_pk_add_f32 v[40:41], v[32:33], v[54:55]
	v_mul_f32_e32 v32, v37, v37
	v_mul_f32_e32 v33, v39, v39
	v_mul_f32_e32 v34, v41, v41
	v_mul_f32_e32 v35, v43, v43
	v_fmac_f32_e32 v32, v36, v36
	v_fmac_f32_e32 v33, v38, v38
	v_fmac_f32_e32 v34, v40, v40
	v_fmac_f32_e32 v35, v42, v42
	v_add_f32_e32 v32, v32, v33
	v_add_f32_e32 v33, v34, v35
	v_add_f32_e32 v32, v32, v33
	v_add_f32_e32 v32, v44, v32
	v_mov_b32_e32 v33, v32
	s_nop 1
	v_permlane16_swap_b32_e32 v33, v32
	v_lshl_add_u64 v[228:229], v[60:61], 0, v[230:231]
	v_lshl_add_u64 v[232:233], v[60:61], 0, v[244:245]
	s_nop 1
	v_mov_b32_dpp v236, v40 row_ror:8 row_mask:0xf bank_mask:0xf
	v_mov_b32_dpp v237, v41 row_ror:8 row_mask:0xf bank_mask:0xf
	v_mov_b32_dpp v238, v42 row_ror:8 row_mask:0xf bank_mask:0xf
	v_mov_b32_dpp v239, v43 row_ror:8 row_mask:0xf bank_mask:0xf
	v_mov_b32_dpp v240, v36 row_ror:8 row_mask:0xf bank_mask:0xf
	v_mov_b32_dpp v241, v37 row_ror:8 row_mask:0xf bank_mask:0xf
	v_mov_b32_dpp v242, v38 row_ror:8 row_mask:0xf bank_mask:0xf
	v_mov_b32_dpp v243, v39 row_ror:8 row_mask:0xf bank_mask:0xf
	s_nop 0
	v_cndmask_b32_e64 v236, v236, v36, s[98:99]
	v_cndmask_b32_e64 v237, v237, v37, s[98:99]
	v_cndmask_b32_e64 v238, v238, v38, s[98:99]
	v_cndmask_b32_e64 v239, v239, v39, s[98:99]
	v_cndmask_b32_e64 v240, v40, v240, s[98:99]
	v_cndmask_b32_e64 v241, v41, v241, s[98:99]
	v_cndmask_b32_e64 v242, v42, v242, s[98:99]
	v_cndmask_b32_e64 v243, v43, v243, s[98:99]
	global_store_dwordx4 v[228:229], v[236:239], off offset:512
	global_store_dwordx4 v[232:233], v[240:243], off offset:512
	v_cvt_pk_bf16_f32 v34, v36, v37
	v_cvt_pk_bf16_f32 v35, v38, v39
	v_cvt_pk_bf16_f32 v36, v40, v41
	s_waitcnt lgkmcnt(0)
	v_add_f32_e32 v32, v32, v33
	v_mov_b32_e32 v33, v32
	s_nop 1
	v_permlane32_swap_b32_e32 v33, v32
	v_cvt_pk_bf16_f32 v37, v42, v43
	global_store_dwordx4 v[58:59], v[34:37], off offset:256
	s_and_saveexec_b64 s[24:25], s[2:3]
	s_cbranch_execz .LBB0_673
	v_readlane_b32 s26, v254, 41
	s_waitcnt lgkmcnt(0)
	v_add_f32_e32 v34, v32, v33
	v_lshlrev_b64 v[32:33], 6, v[48:49]
	v_readlane_b32 s27, v254, 42
	s_lshl_b32 s6, s38, 2
	s_nop 0
	v_lshl_add_u64 v[32:33], s[26:27], 0, v[32:33]
	v_lshl_add_u64 v[32:33], s[22:23], 2, v[32:33]
	v_lshl_add_u64 v[32:33], v[32:33], 0, s[6:7]
	global_store_dword v[32:33], v34, off
; __device__ __forceinline__ unsigned cvt_pk_bf16(float lo, float hi) { const f32x2_t v = {lo, hi}; const bf16x2_t b = __builtin_convertvector(v, bf16x2_t); return __builtin_bit_cast(unsigned, b); }
;     __device__ __forceinline__ void operator()(const f32x4 (&acc)[2][2][4][2], const Unit& u, int wr, int wc, int fr, int fq, const PG8_LAS float*) const {
;     ...
;             for (int m = 0; m < 4; ++m) { const int row = row0 + ai * HALF + m * 16; const size_t off = (size_t)row * ldc + col0; float ss = 0.f;
; #pragma unroll
;                 for (int bj = 0; bj < 2; ++bj) {
;                     const f32x4 b0 = *(const f32x4*)(base + off + bj * HALF), b1 = *(const f32x4*)(base + off + bj * HALF + 4);
;                     const f32x4 v0 = b0 + acc[ai][bj][m][0], v1 = b1 + acc[ai][bj][m][1];
;                     *(f32x4*)(out + off + bj * HALF) = v0; *(f32x4*)(out + off + bj * HALF + 4) = v1;
;                     if (xb) { u32x4 w; w.x = cvt_pk_bf16(v0[0], v0[1]); w.y = cvt_pk_bf16(v0[2], v0[3]); w.z = cvt_pk_bf16(v1[0], v1[1]); w.w = cvt_pk_bf16(v1[2], v1[3]);
;                         *(u32x4*)(xb + off + bj * HALF) = w;
;                         ss += ((v0[0] * v0[0] + v0[1] * v0[1]) + (v0[2] * v0[2] + v0[3] * v0[3])) + ((v1[0] * v1[0] + v1[1] * v1[1]) + (v1[2] * v1[2] + v1[3] * v1[3])); } }
;                 if (xb) { ss += __shfl_xor(ss, 16); ss += __shfl_xor(ss, 32); if (fq == 0) ssq[(size_t)row * 16 + u.pn * 4 + wc] = ss; } }
.LBB0_673:
	s_or_b64 exec, exec, s[24:25]
	v_add_u32_e32 v32, 0xa0, v146
	s_waitcnt lgkmcnt(0)
	v_ashrrev_i32_e32 v33, 31, v32
	v_lshlrev_b64 v[34:35], 10, v[32:33]
	v_lshl_add_u64 v[42:43], v[34:35], 0, v[144:145]
	v_readlane_b32 s48, v254, 3
	v_lshlrev_b64 v[44:45], 2, v[42:43]
	v_readlane_b32 s49, v254, 4
	v_readlane_b32 s24, v254, 39
	v_readlane_b32 s25, v254, 40
	v_lshl_add_u64 v[46:47], s[48:49], 0, v[44:45]
	global_load_dwordx4 v[34:37], v[46:47], off
	global_load_dwordx4 v[38:41], v[46:47], off offset:16
	v_lshl_add_u64 v[42:43], v[42:43], 1, s[24:25]
	v_lshl_add_u64 v[44:45], s[68:69], 0, v[44:45]
	v_readlane_b32 s50, v254, 5
	v_readlane_b32 s51, v254, 6
	v_readlane_b32 s52, v254, 7
	v_readlane_b32 s53, v254, 8
	v_readlane_b32 s54, v254, 9
	v_readlane_b32 s55, v254, 10
	v_readlane_b32 s56, v254, 11
	v_readlane_b32 s57, v254, 12
	v_readlane_b32 s58, v254, 13
	v_readlane_b32 s59, v254, 14
	v_readlane_b32 s60, v254, 15
	v_readlane_b32 s61, v254, 16
	v_readlane_b32 s62, v254, 17
	v_readlane_b32 s63, v254, 18
	s_waitcnt vmcnt(1)
	v_pk_add_f32 v[30:31], v[30:31], v[36:37]
	v_pk_add_f32 v[28:29], v[28:29], v[34:35]
	s_waitcnt vmcnt(0)
	v_pk_add_f32 v[26:27], v[26:27], v[40:41]
	v_pk_add_f32 v[24:25], v[24:25], v[38:39]
	v_cvt_pk_bf16_f32 v34, v28, v29
	v_cvt_pk_bf16_f32 v35, v30, v31
	v_cvt_pk_bf16_f32 v36, v24, v25
	v_cvt_pk_bf16_f32 v37, v26, v27
	v_lshl_add_u64 v[228:229], v[44:45], 0, v[230:231]
	v_lshl_add_u64 v[232:233], v[44:45], 0, v[244:245]
	s_nop 1
	v_mov_b32_dpp v236, v24 row_ror:8 row_mask:0xf bank_mask:0xf
	v_mov_b32_dpp v237, v25 row_ror:8 row_mask:0xf bank_mask:0xf
	v_mov_b32_dpp v238, v26 row_ror:8 row_mask:0xf bank_mask:0xf
	v_mov_b32_dpp v239, v27 row_ror:8 row_mask:0xf bank_mask:0xf
	v_mov_b32_dpp v240, v28 row_ror:8 row_mask:0xf bank_mask:0xf
	v_mov_b32_dpp v241, v29 row_ror:8 row_mask:0xf bank_mask:0xf
	v_mov_b32_dpp v242, v30 row_ror:8 row_mask:0xf bank_mask:0xf
	v_mov_b32_dpp v243, v31 row_ror:8 row_mask:0xf bank_mask:0xf
	s_nop 0
	v_cndmask_b32_e64 v236, v236, v28, s[98:99]
	v_cndmask_b32_e64 v237, v237, v29, s[98:99]
	v_cndmask_b32_e64 v238, v238, v30, s[98:99]
	v_cndmask_b32_e64 v239, v239, v31, s[98:99]
	v_cndmask_b32_e64 v240, v24, v240, s[98:99]
	v_cndmask_b32_e64 v241, v25, v241, s[98:99]
	v_cndmask_b32_e64 v242, v26, v242, s[98:99]
	v_cndmask_b32_e64 v243, v27, v243, s[98:99]
	global_store_dwordx4 v[228:229], v[236:239], off
	global_store_dwordx4 v[232:233], v[240:243], off
	global_store_dwordx4 v[42:43], v[34:37], off
	global_load_dwordx4 v[34:37], v[46:47], off offset:512
	s_nop 0
	global_load_dwordx4 v[38:41], v[46:47], off offset:528
	v_mul_f32_e32 v29, v29, v29
	v_mul_f32_e32 v31, v31, v31
	v_mul_f32_e32 v25, v25, v25
	v_mul_f32_e32 v27, v27, v27
	v_fmac_f32_e32 v29, v28, v28
	v_fmac_f32_e32 v31, v30, v30
	v_fmac_f32_e32 v25, v24, v24
	v_fmac_f32_e32 v27, v26, v26
	v_add_f32_e32 v24, v29, v31
	v_add_f32_e32 v25, v25, v27
	v_add_f32_e32 v28, v24, v25
	s_waitcnt vmcnt(1)
	v_pk_add_f32 v[22:23], v[22:23], v[36:37]
	v_pk_add_f32 v[20:21], v[20:21], v[34:35]
	s_waitcnt vmcnt(0)
	v_pk_add_f32 v[26:27], v[18:19], v[40:41]
	v_pk_add_f32 v[24:25], v[16:17], v[38:39]
	v_mul_f32_e32 v16, v21, v21
	v_mul_f32_e32 v17, v23, v23
	v_mul_f32_e32 v18, v25, v25
	v_mul_f32_e32 v19, v27, v27
	v_fmac_f32_e32 v16, v20, v20
	v_fmac_f32_e32 v17, v22, v22
	v_fmac_f32_e32 v18, v24, v24
	v_fmac_f32_e32 v19, v26, v26
	v_add_f32_e32 v16, v16, v17
	v_add_f32_e32 v17, v18, v19
	v_add_f32_e32 v16, v16, v17
	v_add_f32_e32 v16, v28, v16
	v_mov_b32_e32 v17, v16
	s_nop 1
	v_permlane16_swap_b32_e32 v17, v16
	v_lshl_add_u64 v[228:229], v[44:45], 0, v[230:231]
	v_lshl_add_u64 v[232:233], v[44:45], 0, v[244:245]
	s_nop 1
	v_mov_b32_dpp v236, v24 row_ror:8 row_mask:0xf bank_mask:0xf
	v_mov_b32_dpp v237, v25 row_ror:8 row_mask:0xf bank_mask:0xf
	v_mov_b32_dpp v238, v26 row_ror:8 row_mask:0xf bank_mask:0xf
	v_mov_b32_dpp v239, v27 row_ror:8 row_mask:0xf bank_mask:0xf
	v_mov_b32_dpp v240, v20 row_ror:8 row_mask:0xf bank_mask:0xf
	v_mov_b32_dpp v241, v21 row_ror:8 row_mask:0xf bank_mask:0xf
	v_mov_b32_dpp v242, v22 row_ror:8 row_mask:0xf bank_mask:0xf
	v_mov_b32_dpp v243, v23 row_ror:8 row_mask:0xf bank_mask:0xf
	s_nop 0
	v_cndmask_b32_e64 v236, v236, v20, s[98:99]
	v_cndmask_b32_e64 v237, v237, v21, s[98:99]
	v_cndmask_b32_e64 v238, v238, v22, s[98:99]
	v_cndmask_b32_e64 v239, v239, v23, s[98:99]
	v_cndmask_b32_e64 v240, v24, v240, s[98:99]
	v_cndmask_b32_e64 v241, v25, v241, s[98:99]
	v_cndmask_b32_e64 v242, v26, v242, s[98:99]
	v_cndmask_b32_e64 v243, v27, v243, s[98:99]
	global_store_dwordx4 v[228:229], v[236:239], off offset:512
	global_store_dwordx4 v[232:233], v[240:243], off offset:512
	v_cvt_pk_bf16_f32 v18, v20, v21
	v_cvt_pk_bf16_f32 v19, v22, v23
	v_cvt_pk_bf16_f32 v20, v24, v25
	s_waitcnt lgkmcnt(0)
	v_add_f32_e32 v16, v16, v17
	v_mov_b32_e32 v17, v16
	s_nop 1
	v_permlane32_swap_b32_e32 v17, v16
	v_cvt_pk_bf16_f32 v21, v26, v27
	global_store_dwordx4 v[42:43], v[18:21], off offset:256
	s_and_saveexec_b64 s[24:25], s[2:3]
	s_cbranch_execz .LBB0_675
	v_readlane_b32 s26, v254, 41
	s_waitcnt lgkmcnt(0)
	v_add_f32_e32 v18, v16, v17
	v_lshlrev_b64 v[16:17], 6, v[32:33]
	v_readlane_b32 s27, v254, 42
	s_lshl_b32 s6, s38, 2
	s_nop 0
	v_lshl_add_u64 v[16:17], s[26:27], 0, v[16:17]
	v_lshl_add_u64 v[16:17], s[22:23], 2, v[16:17]
	v_lshl_add_u64 v[16:17], v[16:17], 0, s[6:7]
	global_store_dword v[16:17], v18, off
; __device__ __forceinline__ unsigned cvt_pk_bf16(float lo, float hi) { const f32x2_t v = {lo, hi}; const bf16x2_t b = __builtin_convertvector(v, bf16x2_t); return __builtin_bit_cast(unsigned, b); }
;     __device__ __forceinline__ void operator()(const f32x4 (&acc)[2][2][4][2], const Unit& u, int wr, int wc, int fr, int fq, const PG8_LAS float*) const {
;     ...
;             for (int m = 0; m < 4; ++m) { const int row = row0 + ai * HALF + m * 16; const size_t off = (size_t)row * ldc + col0; float ss = 0.f;
; #pragma unroll
;                 for (int bj = 0; bj < 2; ++bj) {
;                     const f32x4 b0 = *(const f32x4*)(base + off + bj * HALF), b1 = *(const f32x4*)(base + off + bj * HALF + 4);
;                     const f32x4 v0 = b0 + acc[ai][bj][m][0], v1 = b1 + acc[ai][bj][m][1];
;                     *(f32x4*)(out + off + bj * HALF) = v0; *(f32x4*)(out + off + bj * HALF + 4) = v1;
;                     if (xb) { u32x4 w; w.x = cvt_pk_bf16(v0[0], v0[1]); w.y = cvt_pk_bf16(v0[2], v0[3]); w.z = cvt_pk_bf16(v1[0], v1[1]); w.w = cvt_pk_bf16(v1[2], v1[3]);
;                         *(u32x4*)(xb + off + bj * HALF) = w;
;                         ss += ((v0[0] * v0[0] + v0[1] * v0[1]) + (v0[2] * v0[2] + v0[3] * v0[3])) + ((v1[0] * v1[0] + v1[1] * v1[1]) + (v1[2] * v1[2] + v1[3] * v1[3])); } }
;                 if (xb) { ss += __shfl_xor(ss, 16); ss += __shfl_xor(ss, 32); if (fq == 0) ssq[(size_t)row * 16 + u.pn * 4 + wc] = ss; } }
.LBB0_675:
	s_or_b64 exec, exec, s[24:25]
	v_add_u32_e32 v16, 0xb0, v146
	s_waitcnt lgkmcnt(0)
	v_ashrrev_i32_e32 v17, 31, v16
	v_lshlrev_b64 v[18:19], 10, v[16:17]
	v_lshl_add_u64 v[26:27], v[18:19], 0, v[144:145]
	v_readlane_b32 s48, v254, 3
	v_lshlrev_b64 v[28:29], 2, v[26:27]
	v_readlane_b32 s49, v254, 4
	v_readlane_b32 s24, v254, 39
	v_readlane_b32 s25, v254, 40
	v_lshl_add_u64 v[30:31], s[48:49], 0, v[28:29]
	global_load_dwordx4 v[18:21], v[30:31], off
	global_load_dwordx4 v[22:25], v[30:31], off offset:16
	v_lshl_add_u64 v[26:27], v[26:27], 1, s[24:25]
	v_lshl_add_u64 v[28:29], s[68:69], 0, v[28:29]
	v_readlane_b32 s50, v254, 5
	v_readlane_b32 s51, v254, 6
	v_readlane_b32 s52, v254, 7
	v_readlane_b32 s53, v254, 8
	v_readlane_b32 s54, v254, 9
	v_readlane_b32 s55, v254, 10
	v_readlane_b32 s56, v254, 11
	v_readlane_b32 s57, v254, 12
	v_readlane_b32 s58, v254, 13
	v_readlane_b32 s59, v254, 14
	v_readlane_b32 s60, v254, 15
	v_readlane_b32 s61, v254, 16
	v_readlane_b32 s62, v254, 17
	v_readlane_b32 s63, v254, 18
	s_waitcnt vmcnt(1)
	v_pk_add_f32 v[14:15], v[14:15], v[20:21]
	v_pk_add_f32 v[12:13], v[12:13], v[18:19]
	s_waitcnt vmcnt(0)
	v_pk_add_f32 v[10:11], v[10:11], v[24:25]
	v_pk_add_f32 v[8:9], v[8:9], v[22:23]
	v_cvt_pk_bf16_f32 v18, v12, v13
	v_cvt_pk_bf16_f32 v19, v14, v15
	v_cvt_pk_bf16_f32 v20, v8, v9
	v_cvt_pk_bf16_f32 v21, v10, v11
	v_lshl_add_u64 v[228:229], v[28:29], 0, v[230:231]
	v_lshl_add_u64 v[232:233], v[28:29], 0, v[244:245]
	s_nop 1
	v_mov_b32_dpp v236, v8 row_ror:8 row_mask:0xf bank_mask:0xf
	v_mov_b32_dpp v237, v9 row_ror:8 row_mask:0xf bank_mask:0xf
	v_mov_b32_dpp v238, v10 row_ror:8 row_mask:0xf bank_mask:0xf
	v_mov_b32_dpp v239, v11 row_ror:8 row_mask:0xf bank_mask:0xf
	v_mov_b32_dpp v240, v12 row_ror:8 row_mask:0xf bank_mask:0xf
	v_mov_b32_dpp v241, v13 row_ror:8 row_mask:0xf bank_mask:0xf
	v_mov_b32_dpp v242, v14 row_ror:8 row_mask:0xf bank_mask:0xf
	v_mov_b32_dpp v243, v15 row_ror:8 row_mask:0xf bank_mask:0xf
	s_nop 0
	v_cndmask_b32_e64 v236, v236, v12, s[98:99]
	v_cndmask_b32_e64 v237, v237, v13, s[98:99]
	v_cndmask_b32_e64 v238, v238, v14, s[98:99]
	v_cndmask_b32_e64 v239, v239, v15, s[98:99]
	v_cndmask_b32_e64 v240, v8, v240, s[98:99]
	v_cndmask_b32_e64 v241, v9, v241, s[98:99]
	v_cndmask_b32_e64 v242, v10, v242, s[98:99]
	v_cndmask_b32_e64 v243, v11, v243, s[98:99]
	global_store_dwordx4 v[228:229], v[236:239], off
	global_store_dwordx4 v[232:233], v[240:243], off
	global_store_dwordx4 v[26:27], v[18:21], off
	global_load_dwordx4 v[18:21], v[30:31], off offset:512
	s_nop 0
	global_load_dwordx4 v[22:25], v[30:31], off offset:528
	v_mul_f32_e32 v13, v13, v13
	v_mul_f32_e32 v15, v15, v15
	v_mul_f32_e32 v9, v9, v9
	v_mul_f32_e32 v11, v11, v11
	v_fmac_f32_e32 v13, v12, v12
	v_fmac_f32_e32 v15, v14, v14
	v_fmac_f32_e32 v9, v8, v8
	v_fmac_f32_e32 v11, v10, v10
	v_add_f32_e32 v8, v13, v15
	v_add_f32_e32 v9, v9, v11
	v_add_f32_e32 v12, v8, v9
	s_waitcnt vmcnt(1)
	v_pk_add_f32 v[6:7], v[6:7], v[20:21]
	v_pk_add_f32 v[4:5], v[4:5], v[18:19]
	s_waitcnt vmcnt(0)
	v_pk_add_f32 v[10:11], v[2:3], v[24:25]
	v_pk_add_f32 v[8:9], v[0:1], v[22:23]
	v_mul_f32_e32 v0, v5, v5
	v_mul_f32_e32 v1, v7, v7
	v_mul_f32_e32 v2, v9, v9
	v_mul_f32_e32 v3, v11, v11
	v_fmac_f32_e32 v0, v4, v4
	v_fmac_f32_e32 v1, v6, v6
	v_fmac_f32_e32 v2, v8, v8
	v_fmac_f32_e32 v3, v10, v10
	v_add_f32_e32 v0, v0, v1
	v_add_f32_e32 v1, v2, v3
	v_add_f32_e32 v0, v0, v1
	v_add_f32_e32 v0, v12, v0
	v_mov_b32_e32 v1, v0
	s_nop 1
	v_permlane16_swap_b32_e32 v1, v0
	v_lshl_add_u64 v[228:229], v[28:29], 0, v[230:231]
	v_lshl_add_u64 v[232:233], v[28:29], 0, v[244:245]
	s_nop 1
	v_mov_b32_dpp v236, v8 row_ror:8 row_mask:0xf bank_mask:0xf
	v_mov_b32_dpp v237, v9 row_ror:8 row_mask:0xf bank_mask:0xf
	v_mov_b32_dpp v238, v10 row_ror:8 row_mask:0xf bank_mask:0xf
	v_mov_b32_dpp v239, v11 row_ror:8 row_mask:0xf bank_mask:0xf
	v_mov_b32_dpp v240, v4 row_ror:8 row_mask:0xf bank_mask:0xf
	v_mov_b32_dpp v241, v5 row_ror:8 row_mask:0xf bank_mask:0xf
	v_mov_b32_dpp v242, v6 row_ror:8 row_mask:0xf bank_mask:0xf
	v_mov_b32_dpp v243, v7 row_ror:8 row_mask:0xf bank_mask:0xf
	s_nop 0
	v_cndmask_b32_e64 v236, v236, v4, s[98:99]
	v_cndmask_b32_e64 v237, v237, v5, s[98:99]
	v_cndmask_b32_e64 v238, v238, v6, s[98:99]
	v_cndmask_b32_e64 v239, v239, v7, s[98:99]
	v_cndmask_b32_e64 v240, v8, v240, s[98:99]
	v_cndmask_b32_e64 v241, v9, v241, s[98:99]
	v_cndmask_b32_e64 v242, v10, v242, s[98:99]
	v_cndmask_b32_e64 v243, v11, v243, s[98:99]
	global_store_dwordx4 v[228:229], v[236:239], off offset:512
	global_store_dwordx4 v[232:233], v[240:243], off offset:512
	v_cvt_pk_bf16_f32 v2, v4, v5
	v_cvt_pk_bf16_f32 v3, v6, v7
	v_cvt_pk_bf16_f32 v4, v8, v9
	s_waitcnt lgkmcnt(0)
	v_add_f32_e32 v0, v0, v1
	v_mov_b32_e32 v1, v0
	s_nop 1
	v_permlane32_swap_b32_e32 v1, v0
	v_cvt_pk_bf16_f32 v5, v10, v11
	global_store_dwordx4 v[26:27], v[2:5], off offset:256
	s_and_saveexec_b64 s[24:25], s[2:3]
	s_cbranch_execz .LBB0_677
	v_readlane_b32 s26, v254, 41
	s_waitcnt lgkmcnt(0)
	v_add_f32_e32 v2, v0, v1
	v_lshlrev_b64 v[0:1], 6, v[16:17]
	v_readlane_b32 s27, v254, 42
	s_lshl_b32 s6, s38, 2
	s_nop 0
	v_lshl_add_u64 v[0:1], s[26:27], 0, v[0:1]
	v_lshl_add_u64 v[0:1], s[22:23], 2, v[0:1]
	v_lshl_add_u64 v[0:1], v[0:1], 0, s[6:7]
	global_store_dword v[0:1], v2, off

; #define PG8_STAGE(bufoff, gbase, voff) do { _Pragma("unroll") for (int _i = 0; _i < 2; ++_i) \
;         __builtin_amdgcn_global_load_lds((const unsigned*)((const char*)(gbase) + (voff)[_i]), (PG8_LAS unsigned*)(lds + (bufoff) + ldsw + _i * 8192), 16, 0, 0); } while (0)
; #define PG8_LDA(dst, b, h) do { _Pragma("unroll") for (int m = 0; m < 4; ++m) _Pragma("unroll") for (int k = 0; k < 2; ++k) dst[m][k] = *(const PG8_LAS bf16x8*)(lds + PG8_SA(b, h) + aoff + m * 2048 + k * 1024); } while (0)
; #define PG8_LDB(dst, b, h) do { _Pragma("unroll") for (int n = 0; n < 2; ++n) _Pragma("unroll") for (int k = 0; k < 2; ++k) dst[n][k] = *(const PG8_LAS bf16x8*)(lds + PG8_SB(b, h) + boff + n * 2048 + k * 1024); } while (0)
; #define PG8_MMA(ai, bj, At, Bt) do { __builtin_amdgcn_s_setprio(1); _Pragma("unroll") for (int m = 0; m < 4; ++m) _Pragma("unroll") for (int n = 0; n < 2; ++n) _Pragma("unroll") for (int k = 0; k < 2; ++k) \
;         acc[ai][bj][m][n] = __builtin_amdgcn_mfma_f32_16x16x32_bf16(Bt[n][k], At[m][k], acc[ai][bj][m][n], 0, 0, 0); __builtin_amdgcn_s_setprio(0); } while (0)
; #define PG8_WAIT_V(n) asm volatile("s_waitcnt vmcnt(" #n ")" ::: "memory")
; #define PG8_WAIT_L(n) asm volatile("s_waitcnt lgkmcnt(" #n ")" ::: "memory")
; #define PG8_BAR __builtin_amdgcn_s_barrier()
; #define PG8_SCHED __builtin_amdgcn_sched_barrier(0)
; template <class Epi, class Sched, bool ALIGN_EPI = false, bool SP2 = false>
; __device__ __forceinline__ void gemm_phase(PG8_LAS unsigned char* lds, const Gemm g, const Sched& S, const Epi& E) {
;     ...
;             const char* a2 = last ? nA : cA + (size_t)(t + 2) * kstep; const char* b2 = last ? nB : cB + (size_t)(t + 2) * kstep;
;     ...
;             PG8_LDB(B0, 0, 0); PG8_LDB(B1, 0, 1); PG8_SCHED; PG8_LDA(At, 0, 0); PG8_STAGE(PG8_SA(1, 1), a1 + hstep, voffA);
;             PG8_WAIT_V(8); PG8_WAIT_L(0); PG8_BAR; PG8_MMA(0, 0, At, B0); PG8_MMA(0, 1, At, B1); PG8_BAR; PG8_SCHED;
;             PG8_LDA(At, 0, 1); PG8_STAGE(PG8_SB(0, 0), b2, voffB); PG8_STAGE(PG8_SB(0, 1), b2 + hstep, voffB); PG8_STAGE(PG8_SA(0, 0), a2, voffA);
;             PG8_WAIT_V(8); PG8_WAIT_L(0); PG8_BAR; PG8_MMA(1, 0, At, B0); PG8_MMA(1, 1, At, B1); PG8_BAR; PG8_SCHED;
.LBB0_755:
	ds_read_b128 v[128:131], v173
	ds_read_b128 v[132:135], v173 offset:1024
	ds_read_b128 v[136:139], v173 offset:2048
	ds_read_b128 v[140:143], v173 offset:3072
	ds_read_b128 v[160:163], v174
	ds_read_b128 v[178:181], v174 offset:1024
	ds_read_b128 v[182:185], v174 offset:2048
	ds_read_b128 v[186:189], v174 offset:3072
	s_add_u32 s38, s36, 0xfffc0080
	s_addc_u32 s39, s37, -1
	s_cmp_eq_u32 s63, 12
	s_cselect_b32 s41, s25, s39
	s_cselect_b32 s40, s59, s38
	s_cselect_b32 s39, s23, s62
	s_cselect_b32 s38, s60, s61
	s_add_i32 m0, s35, 0xc000
	ds_read_b128 v[190:193], v175
	ds_read_b128 v[194:197], v175 offset:1024
	ds_read_b128 v[198:201], v175 offset:2048
	ds_read_b128 v[202:205], v175 offset:3072
	ds_read_b128 v[206:209], v175 offset:4096
	ds_read_b128 v[210:213], v175 offset:5120
	ds_read_b128 v[214:217], v175 offset:6144
	ds_read_b128 v[218:221], v175 offset:7168
	global_load_lds_dwordx4 v152, s[36:37]
	s_add_i32 m0, s35, 0xe000
	s_nop 0
	global_load_lds_dwordx4 v154, s[36:37]
	s_waitcnt vmcnt(8)
	s_waitcnt lgkmcnt(0)
	s_barrier
	s_setprio 1
	s_waitcnt lgkmcnt(0)
	v_mfma_f32_16x16x32_bf16 v[124:127], v[128:131], v[190:193], v[124:127]
	v_mfma_f32_16x16x32_bf16 v[120:123], v[136:139], v[190:193], v[120:123]
	v_mfma_f32_16x16x32_bf16 v[108:111], v[128:131], v[198:201], v[108:111]
	v_mfma_f32_16x16x32_bf16 v[104:107], v[136:139], v[198:201], v[104:107]
	v_mfma_f32_16x16x32_bf16 v[92:95], v[128:131], v[206:209], v[92:95]
	v_mfma_f32_16x16x32_bf16 v[88:91], v[136:139], v[206:209], v[88:91]
	v_mfma_f32_16x16x32_bf16 v[76:79], v[128:131], v[214:217], v[76:79]
	v_mfma_f32_16x16x32_bf16 v[72:75], v[136:139], v[214:217], v[72:75]
	v_mfma_f32_16x16x32_bf16 v[124:127], v[132:135], v[194:197], v[124:127]
	v_mfma_f32_16x16x32_bf16 v[120:123], v[140:143], v[194:197], v[120:123]
	v_mfma_f32_16x16x32_bf16 v[108:111], v[132:135], v[202:205], v[108:111]
	v_mfma_f32_16x16x32_bf16 v[104:107], v[140:143], v[202:205], v[104:107]
	v_mfma_f32_16x16x32_bf16 v[92:95], v[132:135], v[210:213], v[92:95]
	v_mfma_f32_16x16x32_bf16 v[88:91], v[140:143], v[210:213], v[88:91]
	v_mfma_f32_16x16x32_bf16 v[76:79], v[132:135], v[218:221], v[76:79]
	v_mfma_f32_16x16x32_bf16 v[72:75], v[140:143], v[218:221], v[72:75]
	s_setprio 0
	s_setprio 1
	v_mfma_f32_16x16x32_bf16 v[116:119], v[160:163], v[190:193], v[116:119]
	v_mfma_f32_16x16x32_bf16 v[112:115], v[182:185], v[190:193], v[112:115]
	v_mfma_f32_16x16x32_bf16 v[100:103], v[160:163], v[198:201], v[100:103]
	v_mfma_f32_16x16x32_bf16 v[96:99], v[182:185], v[198:201], v[96:99]
	v_mfma_f32_16x16x32_bf16 v[84:87], v[160:163], v[206:209], v[84:87]
	v_mfma_f32_16x16x32_bf16 v[80:83], v[182:185], v[206:209], v[80:83]
	v_mfma_f32_16x16x32_bf16 v[68:71], v[160:163], v[214:217], v[68:71]
	v_mfma_f32_16x16x32_bf16 v[64:67], v[182:185], v[214:217], v[64:67]
	v_mfma_f32_16x16x32_bf16 v[116:119], v[178:181], v[194:197], v[116:119]
	v_mfma_f32_16x16x32_bf16 v[112:115], v[186:189], v[194:197], v[112:115]
	v_mfma_f32_16x16x32_bf16 v[100:103], v[178:181], v[202:205], v[100:103]
	v_mfma_f32_16x16x32_bf16 v[96:99], v[186:189], v[202:205], v[96:99]
	v_mfma_f32_16x16x32_bf16 v[84:87], v[178:181], v[210:213], v[84:87]
	v_mfma_f32_16x16x32_bf16 v[80:83], v[186:189], v[210:213], v[80:83]
	v_mfma_f32_16x16x32_bf16 v[68:71], v[178:181], v[218:221], v[68:71]
	v_mfma_f32_16x16x32_bf16 v[64:67], v[186:189], v[218:221], v[64:67]
	s_setprio 0
	s_barrier
	s_add_i32 s64, s51, s30
	s_mov_b32 m0, s64
	ds_read_b128 v[190:193], v175 offset:16384
	ds_read_b128 v[194:197], v175 offset:17408
	ds_read_b128 v[198:201], v175 offset:18432
	ds_read_b128 v[202:205], v175 offset:19456
	ds_read_b128 v[206:209], v175 offset:20480
	ds_read_b128 v[210:213], v175 offset:21504
	ds_read_b128 v[214:217], v175 offset:22528
	ds_read_b128 v[218:221], v175 offset:23552
	global_load_lds_dwordx4 v146, s[38:39]
	s_add_i32 m0, s64, 0x2000
	s_add_u32 s64, s38, 0x40000
	s_addc_u32 s65, s39, 0
	s_add_i32 s66, s52, s30
	global_load_lds_dwordx4 v150, s[38:39]
	s_mov_b32 m0, s66
	s_nop 0
	global_load_lds_dwordx4 v146, s[64:65]
	s_add_i32 m0, s66, 0x2000
	s_nop 0
	global_load_lds_dwordx4 v150, s[64:65]
	s_mov_b32 m0, s35
	s_nop 0
	global_load_lds_dwordx4 v144, s[40:41]
	s_mov_b32 m0, s44
	s_nop 0
	global_load_lds_dwordx4 v148, s[40:41]
	s_waitcnt vmcnt(8)
	s_waitcnt lgkmcnt(0)
	s_barrier
	s_setprio 1
	s_waitcnt lgkmcnt(0)
	v_mfma_f32_16x16x32_bf16 v[60:63], v[128:131], v[190:193], v[60:63]
	v_mfma_f32_16x16x32_bf16 v[56:59], v[136:139], v[190:193], v[56:59]
	v_mfma_f32_16x16x32_bf16 v[44:47], v[128:131], v[198:201], v[44:47]
	v_mfma_f32_16x16x32_bf16 v[40:43], v[136:139], v[198:201], v[40:43]
	v_mfma_f32_16x16x32_bf16 v[28:31], v[128:131], v[206:209], v[28:31]
	v_mfma_f32_16x16x32_bf16 v[24:27], v[136:139], v[206:209], v[24:27]
	v_mfma_f32_16x16x32_bf16 v[12:15], v[128:131], v[214:217], v[12:15]
	v_mfma_f32_16x16x32_bf16 v[8:11], v[136:139], v[214:217], v[8:11]
	v_mfma_f32_16x16x32_bf16 v[60:63], v[132:135], v[194:197], v[60:63]
	v_mfma_f32_16x16x32_bf16 v[56:59], v[140:143], v[194:197], v[56:59]
	v_mfma_f32_16x16x32_bf16 v[44:47], v[132:135], v[202:205], v[44:47]
	v_mfma_f32_16x16x32_bf16 v[40:43], v[140:143], v[202:205], v[40:43]
	v_mfma_f32_16x16x32_bf16 v[28:31], v[132:135], v[210:213], v[28:31]
	v_mfma_f32_16x16x32_bf16 v[24:27], v[140:143], v[210:213], v[24:27]
	v_mfma_f32_16x16x32_bf16 v[12:15], v[132:135], v[218:221], v[12:15]
	v_mfma_f32_16x16x32_bf16 v[8:11], v[140:143], v[218:221], v[8:11]
	s_setprio 0
	s_setprio 1
	v_mfma_f32_16x16x32_bf16 v[52:55], v[160:163], v[190:193], v[52:55]
	v_mfma_f32_16x16x32_bf16 v[48:51], v[182:185], v[190:193], v[48:51]
	v_mfma_f32_16x16x32_bf16 v[36:39], v[160:163], v[198:201], v[36:39]
	v_mfma_f32_16x16x32_bf16 v[32:35], v[182:185], v[198:201], v[32:35]
	v_mfma_f32_16x16x32_bf16 v[20:23], v[160:163], v[206:209], v[20:23]
	v_mfma_f32_16x16x32_bf16 v[16:19], v[182:185], v[206:209], v[16:19]
	v_mfma_f32_16x16x32_bf16 v[4:7], v[160:163], v[214:217], v[4:7]
	v_mfma_f32_16x16x32_bf16 v[0:3], v[182:185], v[214:217], v[0:3]
	v_mfma_f32_16x16x32_bf16 v[52:55], v[178:181], v[194:197], v[52:55]
	v_mfma_f32_16x16x32_bf16 v[48:51], v[186:189], v[194:197], v[48:51]
	v_mfma_f32_16x16x32_bf16 v[36:39], v[178:181], v[202:205], v[36:39]
	v_mfma_f32_16x16x32_bf16 v[32:35], v[186:189], v[202:205], v[32:35]
	v_mfma_f32_16x16x32_bf16 v[20:23], v[178:181], v[210:213], v[20:23]
	v_mfma_f32_16x16x32_bf16 v[16:19], v[186:189], v[210:213], v[16:19]
	v_mfma_f32_16x16x32_bf16 v[4:7], v[178:181], v[218:221], v[4:7]
	v_mfma_f32_16x16x32_bf16 v[0:3], v[186:189], v[218:221], v[0:3]
	s_setprio 0
	s_barrier
; #define PG8_STAGE(bufoff, gbase, voff) do { _Pragma("unroll") for (int _i = 0; _i < 2; ++_i) \
;         __builtin_amdgcn_global_load_lds((const unsigned*)((const char*)(gbase) + (voff)[_i]), (PG8_LAS unsigned*)(lds + (bufoff) + ldsw + _i * 8192), 16, 0, 0); } while (0)
; #define PG8_LDA(dst, b, h) do { _Pragma("unroll") for (int m = 0; m < 4; ++m) _Pragma("unroll") for (int k = 0; k < 2; ++k) dst[m][k] = *(const PG8_LAS bf16x8*)(lds + PG8_SA(b, h) + aoff + m * 2048 + k * 1024); } while (0)
; #define PG8_LDB(dst, b, h) do { _Pragma("unroll") for (int n = 0; n < 2; ++n) _Pragma("unroll") for (int k = 0; k < 2; ++k) dst[n][k] = *(const PG8_LAS bf16x8*)(lds + PG8_SB(b, h) + boff + n * 2048 + k * 1024); } while (0)
; #define PG8_MMA(ai, bj, At, Bt) do { __builtin_amdgcn_s_setprio(1); _Pragma("unroll") for (int m = 0; m < 4; ++m) _Pragma("unroll") for (int n = 0; n < 2; ++n) _Pragma("unroll") for (int k = 0; k < 2; ++k) \
;         acc[ai][bj][m][n] = __builtin_amdgcn_mfma_f32_16x16x32_bf16(Bt[n][k], At[m][k], acc[ai][bj][m][n], 0, 0, 0); __builtin_amdgcn_s_setprio(0); } while (0)
; #define PG8_WAIT_V(n) asm volatile("s_waitcnt vmcnt(" #n ")" ::: "memory")
; #define PG8_WAIT_L(n) asm volatile("s_waitcnt lgkmcnt(" #n ")" ::: "memory")
; #define PG8_BAR __builtin_amdgcn_s_barrier()
; #define PG8_SCHED __builtin_amdgcn_sched_barrier(0)
; template <class Epi, class Sched, bool ALIGN_EPI = false, bool SP2 = false>
; __device__ __forceinline__ void gemm_phase(PG8_LAS unsigned char* lds, const Gemm g, const Sched& S, const Epi& E) {
;     ...
;             PG8_LDB(B0, 1, 0); PG8_LDB(B1, 1, 1); PG8_SCHED; PG8_LDA(At, 1, 0); PG8_STAGE(PG8_SA(0, 1), a2 + hstep, voffA);
;             PG8_WAIT_V(8); PG8_WAIT_L(0); PG8_BAR; PG8_MMA(0, 0, At, B0); PG8_MMA(0, 1, At, B1); PG8_BAR; PG8_SCHED;
;             PG8_LDA(At, 1, 1); PG8_STAGE(PG8_SB(1, 0), b3, voffB); PG8_STAGE(PG8_SB(1, 1), b3 + hstep, voffB); PG8_STAGE(PG8_SA(1, 0), a3, voffA);
;             PG8_WAIT_V(8); PG8_WAIT_L(0); PG8_BAR; PG8_MMA(1, 0, At, B0); PG8_MMA(1, 1, At, B1); PG8_BAR; PG8_SCHED;
;     ...
;         if constexpr (ALIGN_EPI) { if (wr == 0) PG8_BAR; }
	s_add_i32 s64, 0, 0x18000
	s_add_i32 s65, 0, 0x1c000
	v_add_u32_e32 v140, s64, v169
	v_add_u32_e32 v177, s65, v169
	ds_read_b128 v[128:131], v140
	ds_read_b128 v[132:135], v140 offset:1024
	ds_read_b128 v[136:139], v140 offset:2048
	ds_read_b128 v[140:143], v140 offset:3072
	ds_read_b128 v[160:163], v177
	ds_read_b128 v[178:181], v177 offset:1024
	ds_read_b128 v[182:185], v177 offset:2048
	ds_read_b128 v[186:189], v177 offset:3072
	s_add_u32 s40, s40, 0x40000
	s_addc_u32 s41, s41, 0
	s_mov_b32 m0, s45
	ds_read_b128 v[190:193], v175 offset:32768
	ds_read_b128 v[194:197], v175 offset:33792
	ds_read_b128 v[198:201], v175 offset:34816
	ds_read_b128 v[202:205], v175 offset:35840
	ds_read_b128 v[206:209], v175 offset:36864
	ds_read_b128 v[210:213], v175 offset:37888
	ds_read_b128 v[214:217], v175 offset:38912
	ds_read_b128 v[218:221], v175 offset:39936
	global_load_lds_dwordx4 v144, s[40:41]
	s_mov_b32 m0, s46
	s_nop 0
	global_load_lds_dwordx4 v148, s[40:41]
	s_waitcnt vmcnt(8)
	s_waitcnt lgkmcnt(0)
	s_barrier
	s_setprio 1
	s_waitcnt lgkmcnt(0)
	v_mfma_f32_16x16x32_bf16 v[124:127], v[128:131], v[190:193], v[124:127]
	v_mfma_f32_16x16x32_bf16 v[120:123], v[136:139], v[190:193], v[120:123]
	v_mfma_f32_16x16x32_bf16 v[108:111], v[128:131], v[198:201], v[108:111]
	v_mfma_f32_16x16x32_bf16 v[104:107], v[136:139], v[198:201], v[104:107]
	v_mfma_f32_16x16x32_bf16 v[92:95], v[128:131], v[206:209], v[92:95]
	v_mfma_f32_16x16x32_bf16 v[88:91], v[136:139], v[206:209], v[88:91]
	v_mfma_f32_16x16x32_bf16 v[76:79], v[128:131], v[214:217], v[76:79]
	v_mfma_f32_16x16x32_bf16 v[72:75], v[136:139], v[214:217], v[72:75]
	v_mfma_f32_16x16x32_bf16 v[124:127], v[132:135], v[194:197], v[124:127]
	v_mfma_f32_16x16x32_bf16 v[120:123], v[140:143], v[194:197], v[120:123]
	v_mfma_f32_16x16x32_bf16 v[108:111], v[132:135], v[202:205], v[108:111]
	v_mfma_f32_16x16x32_bf16 v[104:107], v[140:143], v[202:205], v[104:107]
	v_mfma_f32_16x16x32_bf16 v[92:95], v[132:135], v[210:213], v[92:95]
	v_mfma_f32_16x16x32_bf16 v[88:91], v[140:143], v[210:213], v[88:91]
	v_mfma_f32_16x16x32_bf16 v[76:79], v[132:135], v[218:221], v[76:79]
	v_mfma_f32_16x16x32_bf16 v[72:75], v[140:143], v[218:221], v[72:75]
	s_setprio 0
	s_setprio 1
	v_mfma_f32_16x16x32_bf16 v[116:119], v[160:163], v[190:193], v[116:119]
	v_mfma_f32_16x16x32_bf16 v[112:115], v[182:185], v[190:193], v[112:115]
	v_mfma_f32_16x16x32_bf16 v[100:103], v[160:163], v[198:201], v[100:103]
	v_mfma_f32_16x16x32_bf16 v[96:99], v[182:185], v[198:201], v[96:99]
	v_mfma_f32_16x16x32_bf16 v[84:87], v[160:163], v[206:209], v[84:87]
	v_mfma_f32_16x16x32_bf16 v[80:83], v[182:185], v[206:209], v[80:83]
	v_mfma_f32_16x16x32_bf16 v[68:71], v[160:163], v[214:217], v[68:71]
	v_mfma_f32_16x16x32_bf16 v[64:67], v[182:185], v[214:217], v[64:67]
	v_mfma_f32_16x16x32_bf16 v[116:119], v[178:181], v[194:197], v[116:119]
	v_mfma_f32_16x16x32_bf16 v[112:115], v[186:189], v[194:197], v[112:115]
	v_mfma_f32_16x16x32_bf16 v[100:103], v[178:181], v[202:205], v[100:103]
	v_mfma_f32_16x16x32_bf16 v[96:99], v[186:189], v[202:205], v[96:99]
	v_mfma_f32_16x16x32_bf16 v[84:87], v[178:181], v[210:213], v[84:87]
	v_mfma_f32_16x16x32_bf16 v[80:83], v[186:189], v[210:213], v[80:83]
	v_mfma_f32_16x16x32_bf16 v[68:71], v[178:181], v[218:221], v[68:71]
	v_mfma_f32_16x16x32_bf16 v[64:67], v[186:189], v[218:221], v[64:67]
	s_setprio 0
	s_barrier
	s_add_u32 s98, s40, 0xfffc0080
	s_addc_u32 s99, s41, -1
	s_add_u32 s100, s38, 0x80
	s_addc_u32 s101, s39, 0
	s_add_i32 s40, s64, s30
	s_mov_b32 m0, s40
	ds_read_b128 v[190:193], v175 offset:49152
	ds_read_b128 v[194:197], v175 offset:50176
	ds_read_b128 v[198:201], v175 offset:51200
	ds_read_b128 v[202:205], v175 offset:52224
	ds_read_b128 v[206:209], v175 offset:53248
	ds_read_b128 v[210:213], v175 offset:54272
	ds_read_b128 v[214:217], v175 offset:55296
	ds_read_b128 v[218:221], v175 offset:56320
	global_load_lds_dwordx4 v146, s[100:101]
	s_add_i32 m0, s40, 0x2000
	s_add_u32 s38, s38, 0x40080
	s_addc_u32 s39, s39, 0
	s_add_i32 s40, s65, s30
	global_load_lds_dwordx4 v150, s[100:101]
	s_mov_b32 m0, s40
	s_nop 0
	global_load_lds_dwordx4 v146, s[38:39]
	s_add_i32 m0, s40, 0x2000
	s_nop 0
	global_load_lds_dwordx4 v150, s[38:39]
	s_mov_b32 m0, s47
	s_nop 0
	global_load_lds_dwordx4 v144, s[98:99]
	s_mov_b32 m0, s48
	s_nop 0
	global_load_lds_dwordx4 v148, s[98:99]
	s_waitcnt vmcnt(8)
	s_waitcnt lgkmcnt(0)
	s_barrier
	s_setprio 1
	s_waitcnt lgkmcnt(0)
	v_mfma_f32_16x16x32_bf16 v[60:63], v[128:131], v[190:193], v[60:63]
	v_mfma_f32_16x16x32_bf16 v[56:59], v[136:139], v[190:193], v[56:59]
	v_mfma_f32_16x16x32_bf16 v[44:47], v[128:131], v[198:201], v[44:47]
	v_mfma_f32_16x16x32_bf16 v[40:43], v[136:139], v[198:201], v[40:43]
	v_mfma_f32_16x16x32_bf16 v[28:31], v[128:131], v[206:209], v[28:31]
	v_mfma_f32_16x16x32_bf16 v[24:27], v[136:139], v[206:209], v[24:27]
	v_mfma_f32_16x16x32_bf16 v[12:15], v[128:131], v[214:217], v[12:15]
	v_mfma_f32_16x16x32_bf16 v[8:11], v[136:139], v[214:217], v[8:11]
	v_mfma_f32_16x16x32_bf16 v[60:63], v[132:135], v[194:197], v[60:63]
	v_mfma_f32_16x16x32_bf16 v[56:59], v[140:143], v[194:197], v[56:59]
	v_mfma_f32_16x16x32_bf16 v[44:47], v[132:135], v[202:205], v[44:47]
	v_mfma_f32_16x16x32_bf16 v[40:43], v[140:143], v[202:205], v[40:43]
	v_mfma_f32_16x16x32_bf16 v[28:31], v[132:135], v[210:213], v[28:31]
	v_mfma_f32_16x16x32_bf16 v[24:27], v[140:143], v[210:213], v[24:27]
	v_mfma_f32_16x16x32_bf16 v[12:15], v[132:135], v[218:221], v[12:15]
	v_mfma_f32_16x16x32_bf16 v[8:11], v[140:143], v[218:221], v[8:11]
	s_setprio 0
	s_setprio 1
	v_mfma_f32_16x16x32_bf16 v[52:55], v[160:163], v[190:193], v[52:55]
	v_mfma_f32_16x16x32_bf16 v[48:51], v[182:185], v[190:193], v[48:51]
	v_mfma_f32_16x16x32_bf16 v[36:39], v[160:163], v[198:201], v[36:39]
	v_mfma_f32_16x16x32_bf16 v[32:35], v[182:185], v[198:201], v[32:35]
	v_mfma_f32_16x16x32_bf16 v[20:23], v[160:163], v[206:209], v[20:23]
	v_mfma_f32_16x16x32_bf16 v[16:19], v[182:185], v[206:209], v[16:19]
	v_mfma_f32_16x16x32_bf16 v[4:7], v[160:163], v[214:217], v[4:7]
	v_mfma_f32_16x16x32_bf16 v[0:3], v[182:185], v[214:217], v[0:3]
	v_mfma_f32_16x16x32_bf16 v[52:55], v[178:181], v[194:197], v[52:55]
	v_mfma_f32_16x16x32_bf16 v[48:51], v[186:189], v[194:197], v[48:51]
	v_mfma_f32_16x16x32_bf16 v[36:39], v[178:181], v[202:205], v[36:39]
	v_mfma_f32_16x16x32_bf16 v[32:35], v[186:189], v[202:205], v[32:35]
	v_mfma_f32_16x16x32_bf16 v[20:23], v[178:181], v[210:213], v[20:23]
	v_mfma_f32_16x16x32_bf16 v[16:19], v[186:189], v[210:213], v[16:19]
	v_mfma_f32_16x16x32_bf16 v[4:7], v[178:181], v[218:221], v[4:7]
	v_mfma_f32_16x16x32_bf16 v[0:3], v[186:189], v[218:221], v[0:3]
	s_setprio 0
	s_add_i32 s63, s63, 2
	s_add_u32 s36, s36, 0x100
	s_addc_u32 s37, s37, 0
	s_add_u32 s61, s61, 0x100
	s_addc_u32 s62, s62, 0
	s_cmp_gt_u32 s63, 13
	s_barrier
	s_cbranch_scc0 .LBB0_755
	s_and_b64 vcc, exec, s[12:13]
	s_cbranch_vccz .LBB0_758
	s_barrier

; #define PG8_STAGE(bufoff, gbase, voff) do { _Pragma("unroll") for (int _i = 0; _i < 2; ++_i) \
;         __builtin_amdgcn_global_load_lds((const unsigned*)((const char*)(gbase) + (voff)[_i]), (PG8_LAS unsigned*)(lds + (bufoff) + ldsw + _i * 8192), 16, 0, 0); } while (0)
; #define PG8_LDA(dst, b, h) do { _Pragma("unroll") for (int m = 0; m < 4; ++m) _Pragma("unroll") for (int k = 0; k < 2; ++k) dst[m][k] = *(const PG8_LAS bf16x8*)(lds + PG8_SA(b, h) + aoff + m * 2048 + k * 1024); } while (0)
; #define PG8_LDB(dst, b, h) do { _Pragma("unroll") for (int n = 0; n < 2; ++n) _Pragma("unroll") for (int k = 0; k < 2; ++k) dst[n][k] = *(const PG8_LAS bf16x8*)(lds + PG8_SB(b, h) + boff + n * 2048 + k * 1024); } while (0)
; #define PG8_MMA(ai, bj, At, Bt) do { __builtin_amdgcn_s_setprio(1); _Pragma("unroll") for (int m = 0; m < 4; ++m) _Pragma("unroll") for (int n = 0; n < 2; ++n) _Pragma("unroll") for (int k = 0; k < 2; ++k) \
;         acc[ai][bj][m][n] = __builtin_amdgcn_mfma_f32_16x16x32_bf16(Bt[n][k], At[m][k], acc[ai][bj][m][n], 0, 0, 0); __builtin_amdgcn_s_setprio(0); } while (0)
; #define PG8_WAIT_V(n) asm volatile("s_waitcnt vmcnt(" #n ")" ::: "memory")
; #define PG8_WAIT_L(n) asm volatile("s_waitcnt lgkmcnt(" #n ")" ::: "memory")
; #define PG8_BAR __builtin_amdgcn_s_barrier()
; #define PG8_SCHED __builtin_amdgcn_sched_barrier(0)
; template <class Epi, class Sched, bool ALIGN_EPI = false, bool SP2 = false>
; __device__ __forceinline__ void gemm_phase(PG8_LAS unsigned char* lds, const Gemm g, const Sched& S, const Epi& E) {
;     ...
;             const char* a2 = last ? nA : cA + (size_t)(t + 2) * kstep; const char* b2 = last ? nB : cB + (size_t)(t + 2) * kstep;
;     ...
;             PG8_LDB(B0, 0, 0); PG8_LDB(B1, 0, 1); PG8_SCHED; PG8_LDA(At, 0, 0); PG8_STAGE(PG8_SA(1, 1), a1 + hstep, voffA);
;             PG8_WAIT_V(8); PG8_WAIT_L(0); PG8_BAR; PG8_MMA(0, 0, At, B0); PG8_MMA(0, 1, At, B1); PG8_BAR; PG8_SCHED;
;             PG8_LDA(At, 0, 1); PG8_STAGE(PG8_SB(0, 0), b2, voffB); PG8_STAGE(PG8_SB(0, 1), b2 + hstep, voffB); PG8_STAGE(PG8_SA(0, 0), a2, voffA);
;             PG8_WAIT_V(8); PG8_WAIT_L(0); PG8_BAR; PG8_MMA(1, 0, At, B0); PG8_MMA(1, 1, At, B1); PG8_BAR; PG8_SCHED;
.LBB0_842:
	ds_read_b128 v[144:147], v151
	ds_read_b128 v[156:159], v151 offset:1024
	ds_read_b128 v[160:163], v151 offset:2048
	ds_read_b128 v[168:171], v151 offset:3072
	ds_read_b128 v[172:175], v152
	ds_read_b128 v[176:179], v152 offset:1024
	ds_read_b128 v[180:183], v152 offset:2048
	ds_read_b128 v[184:187], v152 offset:3072
	s_add_u32 s26, s24, 0xfff00080
	s_addc_u32 s27, s25, -1
	s_cmp_eq_u32 s50, 60
	s_cselect_b32 s29, s17, s27
	s_cselect_b32 s28, s23, s26
	s_cselect_b32 s27, s15, s49
	s_cselect_b32 s26, s47, s48
	s_add_i32 m0, s34, 0xc000
	ds_read_b128 v[188:191], v153
	ds_read_b128 v[192:195], v153 offset:1024
	ds_read_b128 v[196:199], v153 offset:2048
	ds_read_b128 v[200:203], v153 offset:3072
	ds_read_b128 v[204:207], v153 offset:4096
	ds_read_b128 v[208:211], v153 offset:5120
	ds_read_b128 v[212:215], v153 offset:6144
	ds_read_b128 v[216:219], v153 offset:7168
	global_load_lds_dwordx4 v136, s[24:25]
	s_add_i32 m0, s34, 0xe000
	s_nop 0
	global_load_lds_dwordx4 v138, s[24:25]
	s_waitcnt vmcnt(8)
	s_waitcnt lgkmcnt(0)
	s_barrier
	s_setprio 1
	s_waitcnt lgkmcnt(0)
	v_mfma_f32_16x16x32_bf16 v[124:127], v[144:147], v[188:191], v[124:127]
	v_mfma_f32_16x16x32_bf16 v[120:123], v[160:163], v[188:191], v[120:123]
	v_mfma_f32_16x16x32_bf16 v[108:111], v[144:147], v[196:199], v[108:111]
	v_mfma_f32_16x16x32_bf16 v[104:107], v[160:163], v[196:199], v[104:107]
	v_mfma_f32_16x16x32_bf16 v[92:95], v[144:147], v[204:207], v[92:95]
	v_mfma_f32_16x16x32_bf16 v[88:91], v[160:163], v[204:207], v[88:91]
	v_mfma_f32_16x16x32_bf16 v[76:79], v[144:147], v[212:215], v[76:79]
	v_mfma_f32_16x16x32_bf16 v[72:75], v[160:163], v[212:215], v[72:75]
	v_mfma_f32_16x16x32_bf16 v[124:127], v[156:159], v[192:195], v[124:127]
	v_mfma_f32_16x16x32_bf16 v[120:123], v[168:171], v[192:195], v[120:123]
	v_mfma_f32_16x16x32_bf16 v[108:111], v[156:159], v[200:203], v[108:111]
	v_mfma_f32_16x16x32_bf16 v[104:107], v[168:171], v[200:203], v[104:107]
	v_mfma_f32_16x16x32_bf16 v[92:95], v[156:159], v[208:211], v[92:95]
	v_mfma_f32_16x16x32_bf16 v[88:91], v[168:171], v[208:211], v[88:91]
	v_mfma_f32_16x16x32_bf16 v[76:79], v[156:159], v[216:219], v[76:79]
	v_mfma_f32_16x16x32_bf16 v[72:75], v[168:171], v[216:219], v[72:75]
	s_setprio 0
	s_setprio 1
	v_mfma_f32_16x16x32_bf16 v[116:119], v[172:175], v[188:191], v[116:119]
	v_mfma_f32_16x16x32_bf16 v[112:115], v[180:183], v[188:191], v[112:115]
	v_mfma_f32_16x16x32_bf16 v[100:103], v[172:175], v[196:199], v[100:103]
	v_mfma_f32_16x16x32_bf16 v[96:99], v[180:183], v[196:199], v[96:99]
	v_mfma_f32_16x16x32_bf16 v[84:87], v[172:175], v[204:207], v[84:87]
	v_mfma_f32_16x16x32_bf16 v[80:83], v[180:183], v[204:207], v[80:83]
	v_mfma_f32_16x16x32_bf16 v[68:71], v[172:175], v[212:215], v[68:71]
	v_mfma_f32_16x16x32_bf16 v[64:67], v[180:183], v[212:215], v[64:67]
	v_mfma_f32_16x16x32_bf16 v[116:119], v[176:179], v[192:195], v[116:119]
	v_mfma_f32_16x16x32_bf16 v[112:115], v[184:187], v[192:195], v[112:115]
	v_mfma_f32_16x16x32_bf16 v[100:103], v[176:179], v[200:203], v[100:103]
	v_mfma_f32_16x16x32_bf16 v[96:99], v[184:187], v[200:203], v[96:99]
	v_mfma_f32_16x16x32_bf16 v[84:87], v[176:179], v[208:211], v[84:87]
	v_mfma_f32_16x16x32_bf16 v[80:83], v[184:187], v[208:211], v[80:83]
	v_mfma_f32_16x16x32_bf16 v[68:71], v[176:179], v[216:219], v[68:71]
	v_mfma_f32_16x16x32_bf16 v[64:67], v[184:187], v[216:219], v[64:67]
	s_setprio 0
	s_barrier
	s_add_i32 s51, s44, s33
	s_mov_b32 m0, s51
	ds_read_b128 v[188:191], v153 offset:16384
	ds_read_b128 v[192:195], v153 offset:17408
	ds_read_b128 v[196:199], v153 offset:18432
	ds_read_b128 v[200:203], v153 offset:19456
	ds_read_b128 v[204:207], v153 offset:20480
	ds_read_b128 v[208:211], v153 offset:21504
	ds_read_b128 v[212:215], v153 offset:22528
	ds_read_b128 v[216:219], v153 offset:23552
	global_load_lds_dwordx4 v130, s[26:27]
	s_add_i32 m0, s51, 0x2000
	s_add_u32 s52, s26, 0x100000
	s_addc_u32 s53, s27, 0
	s_add_i32 s51, s45, s33
	global_load_lds_dwordx4 v134, s[26:27]
	s_mov_b32 m0, s51
	s_nop 0
	global_load_lds_dwordx4 v130, s[52:53]
	s_add_i32 m0, s51, 0x2000
	s_nop 0
	global_load_lds_dwordx4 v134, s[52:53]
	s_mov_b32 m0, s34
	s_nop 0
	global_load_lds_dwordx4 v128, s[28:29]
	s_mov_b32 m0, s35
	s_nop 0
	global_load_lds_dwordx4 v132, s[28:29]
	s_waitcnt vmcnt(8)
	s_waitcnt lgkmcnt(0)
	s_barrier
	s_setprio 1
	s_waitcnt lgkmcnt(0)
	v_mfma_f32_16x16x32_bf16 v[60:63], v[144:147], v[188:191], v[60:63]
	v_mfma_f32_16x16x32_bf16 v[56:59], v[160:163], v[188:191], v[56:59]
	v_mfma_f32_16x16x32_bf16 v[44:47], v[144:147], v[196:199], v[44:47]
	v_mfma_f32_16x16x32_bf16 v[40:43], v[160:163], v[196:199], v[40:43]
	v_mfma_f32_16x16x32_bf16 v[28:31], v[144:147], v[204:207], v[28:31]
	v_mfma_f32_16x16x32_bf16 v[24:27], v[160:163], v[204:207], v[24:27]
	v_mfma_f32_16x16x32_bf16 v[12:15], v[144:147], v[212:215], v[12:15]
	v_mfma_f32_16x16x32_bf16 v[8:11], v[160:163], v[212:215], v[8:11]
	v_mfma_f32_16x16x32_bf16 v[60:63], v[156:159], v[192:195], v[60:63]
	v_mfma_f32_16x16x32_bf16 v[56:59], v[168:171], v[192:195], v[56:59]
	v_mfma_f32_16x16x32_bf16 v[44:47], v[156:159], v[200:203], v[44:47]
	v_mfma_f32_16x16x32_bf16 v[40:43], v[168:171], v[200:203], v[40:43]
	v_mfma_f32_16x16x32_bf16 v[28:31], v[156:159], v[208:211], v[28:31]
	v_mfma_f32_16x16x32_bf16 v[24:27], v[168:171], v[208:211], v[24:27]
	v_mfma_f32_16x16x32_bf16 v[12:15], v[156:159], v[216:219], v[12:15]
	v_mfma_f32_16x16x32_bf16 v[8:11], v[168:171], v[216:219], v[8:11]
	s_setprio 0
	s_setprio 1
	v_mfma_f32_16x16x32_bf16 v[52:55], v[172:175], v[188:191], v[52:55]
	v_mfma_f32_16x16x32_bf16 v[48:51], v[180:183], v[188:191], v[48:51]
	v_mfma_f32_16x16x32_bf16 v[36:39], v[172:175], v[196:199], v[36:39]
	v_mfma_f32_16x16x32_bf16 v[32:35], v[180:183], v[196:199], v[32:35]
	v_mfma_f32_16x16x32_bf16 v[20:23], v[172:175], v[204:207], v[20:23]
	v_mfma_f32_16x16x32_bf16 v[16:19], v[180:183], v[204:207], v[16:19]
	v_mfma_f32_16x16x32_bf16 v[4:7], v[172:175], v[212:215], v[4:7]
	v_mfma_f32_16x16x32_bf16 v[0:3], v[180:183], v[212:215], v[0:3]
	v_mfma_f32_16x16x32_bf16 v[52:55], v[176:179], v[192:195], v[52:55]
	v_mfma_f32_16x16x32_bf16 v[48:51], v[184:187], v[192:195], v[48:51]
	v_mfma_f32_16x16x32_bf16 v[36:39], v[176:179], v[200:203], v[36:39]
	v_mfma_f32_16x16x32_bf16 v[32:35], v[184:187], v[200:203], v[32:35]
	v_mfma_f32_16x16x32_bf16 v[20:23], v[176:179], v[208:211], v[20:23]
	v_mfma_f32_16x16x32_bf16 v[16:19], v[184:187], v[208:211], v[16:19]
	v_mfma_f32_16x16x32_bf16 v[4:7], v[176:179], v[216:219], v[4:7]
	v_mfma_f32_16x16x32_bf16 v[0:3], v[184:187], v[216:219], v[0:3]
	s_setprio 0
	s_barrier
; #define PG8_STAGE(bufoff, gbase, voff) do { _Pragma("unroll") for (int _i = 0; _i < 2; ++_i) \
;         __builtin_amdgcn_global_load_lds((const unsigned*)((const char*)(gbase) + (voff)[_i]), (PG8_LAS unsigned*)(lds + (bufoff) + ldsw + _i * 8192), 16, 0, 0); } while (0)
; #define PG8_LDA(dst, b, h) do { _Pragma("unroll") for (int m = 0; m < 4; ++m) _Pragma("unroll") for (int k = 0; k < 2; ++k) dst[m][k] = *(const PG8_LAS bf16x8*)(lds + PG8_SA(b, h) + aoff + m * 2048 + k * 1024); } while (0)
; #define PG8_LDB(dst, b, h) do { _Pragma("unroll") for (int n = 0; n < 2; ++n) _Pragma("unroll") for (int k = 0; k < 2; ++k) dst[n][k] = *(const PG8_LAS bf16x8*)(lds + PG8_SB(b, h) + boff + n * 2048 + k * 1024); } while (0)
; #define PG8_MMA(ai, bj, At, Bt) do { __builtin_amdgcn_s_setprio(1); _Pragma("unroll") for (int m = 0; m < 4; ++m) _Pragma("unroll") for (int n = 0; n < 2; ++n) _Pragma("unroll") for (int k = 0; k < 2; ++k) \
;         acc[ai][bj][m][n] = __builtin_amdgcn_mfma_f32_16x16x32_bf16(Bt[n][k], At[m][k], acc[ai][bj][m][n], 0, 0, 0); __builtin_amdgcn_s_setprio(0); } while (0)
; #define PG8_WAIT_V(n) asm volatile("s_waitcnt vmcnt(" #n ")" ::: "memory")
; #define PG8_WAIT_L(n) asm volatile("s_waitcnt lgkmcnt(" #n ")" ::: "memory")
; #define PG8_BAR __builtin_amdgcn_s_barrier()
; #define PG8_SCHED __builtin_amdgcn_sched_barrier(0)
; template <class Epi, class Sched, bool ALIGN_EPI = false, bool SP2 = false>
; __device__ __forceinline__ void gemm_phase(PG8_LAS unsigned char* lds, const Gemm g, const Sched& S, const Epi& E) {
;     ...
;         for (int t = 0; t < nt; t += 2) {
;     ...
;             PG8_LDB(B0, 1, 0); PG8_LDB(B1, 1, 1); PG8_SCHED; PG8_LDA(At, 1, 0); PG8_STAGE(PG8_SA(0, 1), a2 + hstep, voffA);
;             PG8_WAIT_V(8); PG8_WAIT_L(0); PG8_BAR; PG8_MMA(0, 0, At, B0); PG8_MMA(0, 1, At, B1); PG8_BAR; PG8_SCHED;
;             PG8_LDA(At, 1, 1); PG8_STAGE(PG8_SB(1, 0), b3, voffB); PG8_STAGE(PG8_SB(1, 1), b3 + hstep, voffB); PG8_STAGE(PG8_SA(1, 0), a3, voffA);
;             PG8_WAIT_V(8); PG8_WAIT_L(0); PG8_BAR; PG8_MMA(1, 0, At, B0); PG8_MMA(1, 1, At, B1); PG8_BAR; PG8_SCHED;
	s_add_i32 s51, 0, 0x18000
	v_add_u32_e32 v155, s51, v149
	s_add_i32 s52, 0, 0x1c000
	ds_read_b128 v[144:147], v155
	ds_read_b128 v[156:159], v155 offset:1024
	ds_read_b128 v[160:163], v155 offset:2048
	ds_read_b128 v[168:171], v155 offset:3072
	v_add_u32_e32 v155, s52, v149
	ds_read_b128 v[172:175], v155
	ds_read_b128 v[176:179], v155 offset:1024
	ds_read_b128 v[180:183], v155 offset:2048
	ds_read_b128 v[184:187], v155 offset:3072
	s_add_u32 s28, s28, 0x100000
	s_addc_u32 s29, s29, 0
	s_mov_b32 m0, s36
	ds_read_b128 v[188:191], v153 offset:32768
	ds_read_b128 v[192:195], v153 offset:33792
	ds_read_b128 v[196:199], v153 offset:34816
	ds_read_b128 v[200:203], v153 offset:35840
	ds_read_b128 v[204:207], v153 offset:36864
	ds_read_b128 v[208:211], v153 offset:37888
	ds_read_b128 v[212:215], v153 offset:38912
	ds_read_b128 v[216:219], v153 offset:39936
	global_load_lds_dwordx4 v128, s[28:29]
	s_mov_b32 m0, s37
	s_nop 0
	global_load_lds_dwordx4 v132, s[28:29]
	s_waitcnt vmcnt(8)
	s_waitcnt lgkmcnt(0)
	s_barrier
	s_setprio 1
	s_waitcnt lgkmcnt(0)
	v_mfma_f32_16x16x32_bf16 v[124:127], v[144:147], v[188:191], v[124:127]
	v_mfma_f32_16x16x32_bf16 v[120:123], v[160:163], v[188:191], v[120:123]
	v_mfma_f32_16x16x32_bf16 v[108:111], v[144:147], v[196:199], v[108:111]
	v_mfma_f32_16x16x32_bf16 v[104:107], v[160:163], v[196:199], v[104:107]
	v_mfma_f32_16x16x32_bf16 v[92:95], v[144:147], v[204:207], v[92:95]
	v_mfma_f32_16x16x32_bf16 v[88:91], v[160:163], v[204:207], v[88:91]
	v_mfma_f32_16x16x32_bf16 v[76:79], v[144:147], v[212:215], v[76:79]
	v_mfma_f32_16x16x32_bf16 v[72:75], v[160:163], v[212:215], v[72:75]
	v_mfma_f32_16x16x32_bf16 v[124:127], v[156:159], v[192:195], v[124:127]
	v_mfma_f32_16x16x32_bf16 v[120:123], v[168:171], v[192:195], v[120:123]
	v_mfma_f32_16x16x32_bf16 v[108:111], v[156:159], v[200:203], v[108:111]
	v_mfma_f32_16x16x32_bf16 v[104:107], v[168:171], v[200:203], v[104:107]
	v_mfma_f32_16x16x32_bf16 v[92:95], v[156:159], v[208:211], v[92:95]
	v_mfma_f32_16x16x32_bf16 v[88:91], v[168:171], v[208:211], v[88:91]
	v_mfma_f32_16x16x32_bf16 v[76:79], v[156:159], v[216:219], v[76:79]
	v_mfma_f32_16x16x32_bf16 v[72:75], v[168:171], v[216:219], v[72:75]
	s_setprio 0
	s_setprio 1
	v_mfma_f32_16x16x32_bf16 v[116:119], v[172:175], v[188:191], v[116:119]
	v_mfma_f32_16x16x32_bf16 v[112:115], v[180:183], v[188:191], v[112:115]
	v_mfma_f32_16x16x32_bf16 v[100:103], v[172:175], v[196:199], v[100:103]
	v_mfma_f32_16x16x32_bf16 v[96:99], v[180:183], v[196:199], v[96:99]
	v_mfma_f32_16x16x32_bf16 v[84:87], v[172:175], v[204:207], v[84:87]
	v_mfma_f32_16x16x32_bf16 v[80:83], v[180:183], v[204:207], v[80:83]
	v_mfma_f32_16x16x32_bf16 v[68:71], v[172:175], v[212:215], v[68:71]
	v_mfma_f32_16x16x32_bf16 v[64:67], v[180:183], v[212:215], v[64:67]
	v_mfma_f32_16x16x32_bf16 v[116:119], v[176:179], v[192:195], v[116:119]
	v_mfma_f32_16x16x32_bf16 v[112:115], v[184:187], v[192:195], v[112:115]
	v_mfma_f32_16x16x32_bf16 v[100:103], v[176:179], v[200:203], v[100:103]
	v_mfma_f32_16x16x32_bf16 v[96:99], v[184:187], v[200:203], v[96:99]
	v_mfma_f32_16x16x32_bf16 v[84:87], v[176:179], v[208:211], v[84:87]
	v_mfma_f32_16x16x32_bf16 v[80:83], v[184:187], v[208:211], v[80:83]
	v_mfma_f32_16x16x32_bf16 v[68:71], v[176:179], v[216:219], v[68:71]
	v_mfma_f32_16x16x32_bf16 v[64:67], v[184:187], v[216:219], v[64:67]
	s_setprio 0
	s_barrier
	s_add_u32 s98, s28, 0xfff00080
	s_addc_u32 s99, s29, -1
	s_add_u32 s100, s26, 0x80
	s_addc_u32 s101, s27, 0
	s_add_i32 s28, s51, s33
	s_mov_b32 m0, s28
	ds_read_b128 v[188:191], v153 offset:49152
	ds_read_b128 v[192:195], v153 offset:50176
	ds_read_b128 v[196:199], v153 offset:51200
	ds_read_b128 v[200:203], v153 offset:52224
	ds_read_b128 v[204:207], v153 offset:53248
	ds_read_b128 v[208:211], v153 offset:54272
	ds_read_b128 v[212:215], v153 offset:55296
	ds_read_b128 v[216:219], v153 offset:56320
	global_load_lds_dwordx4 v130, s[100:101]
	s_add_i32 m0, s28, 0x2000
	s_add_u32 s26, s26, 0x100080
	s_addc_u32 s27, s27, 0
	s_add_i32 s28, s52, s33
	global_load_lds_dwordx4 v134, s[100:101]
	s_mov_b32 m0, s28
	s_nop 0
	global_load_lds_dwordx4 v130, s[26:27]
	s_add_i32 m0, s28, 0x2000
	s_nop 0
	global_load_lds_dwordx4 v134, s[26:27]
	s_mov_b32 m0, s39
	s_nop 0
	global_load_lds_dwordx4 v128, s[98:99]
	s_mov_b32 m0, s40
	s_nop 0
	global_load_lds_dwordx4 v132, s[98:99]
	s_waitcnt vmcnt(8)
	s_waitcnt lgkmcnt(0)
	s_barrier
	s_setprio 1
	s_waitcnt lgkmcnt(0)
	v_mfma_f32_16x16x32_bf16 v[60:63], v[144:147], v[188:191], v[60:63]
	v_mfma_f32_16x16x32_bf16 v[56:59], v[160:163], v[188:191], v[56:59]
	v_mfma_f32_16x16x32_bf16 v[44:47], v[144:147], v[196:199], v[44:47]
	v_mfma_f32_16x16x32_bf16 v[40:43], v[160:163], v[196:199], v[40:43]
	v_mfma_f32_16x16x32_bf16 v[28:31], v[144:147], v[204:207], v[28:31]
	v_mfma_f32_16x16x32_bf16 v[24:27], v[160:163], v[204:207], v[24:27]
	v_mfma_f32_16x16x32_bf16 v[12:15], v[144:147], v[212:215], v[12:15]
	v_mfma_f32_16x16x32_bf16 v[8:11], v[160:163], v[212:215], v[8:11]
	v_mfma_f32_16x16x32_bf16 v[60:63], v[156:159], v[192:195], v[60:63]
	v_mfma_f32_16x16x32_bf16 v[56:59], v[168:171], v[192:195], v[56:59]
	v_mfma_f32_16x16x32_bf16 v[44:47], v[156:159], v[200:203], v[44:47]
	v_mfma_f32_16x16x32_bf16 v[40:43], v[168:171], v[200:203], v[40:43]
	v_mfma_f32_16x16x32_bf16 v[28:31], v[156:159], v[208:211], v[28:31]
	v_mfma_f32_16x16x32_bf16 v[24:27], v[168:171], v[208:211], v[24:27]
	v_mfma_f32_16x16x32_bf16 v[12:15], v[156:159], v[216:219], v[12:15]
	v_mfma_f32_16x16x32_bf16 v[8:11], v[168:171], v[216:219], v[8:11]
	s_setprio 0
	s_setprio 1
	v_mfma_f32_16x16x32_bf16 v[52:55], v[172:175], v[188:191], v[52:55]
	v_mfma_f32_16x16x32_bf16 v[48:51], v[180:183], v[188:191], v[48:51]
	v_mfma_f32_16x16x32_bf16 v[36:39], v[172:175], v[196:199], v[36:39]
	v_mfma_f32_16x16x32_bf16 v[32:35], v[180:183], v[196:199], v[32:35]
	v_mfma_f32_16x16x32_bf16 v[20:23], v[172:175], v[204:207], v[20:23]
	v_mfma_f32_16x16x32_bf16 v[16:19], v[180:183], v[204:207], v[16:19]
	v_mfma_f32_16x16x32_bf16 v[4:7], v[172:175], v[212:215], v[4:7]
	v_mfma_f32_16x16x32_bf16 v[0:3], v[180:183], v[212:215], v[0:3]
	v_mfma_f32_16x16x32_bf16 v[52:55], v[176:179], v[192:195], v[52:55]
	v_mfma_f32_16x16x32_bf16 v[48:51], v[184:187], v[192:195], v[48:51]
	v_mfma_f32_16x16x32_bf16 v[36:39], v[176:179], v[200:203], v[36:39]
	v_mfma_f32_16x16x32_bf16 v[32:35], v[184:187], v[200:203], v[32:35]
	v_mfma_f32_16x16x32_bf16 v[20:23], v[176:179], v[208:211], v[20:23]
	v_mfma_f32_16x16x32_bf16 v[16:19], v[184:187], v[208:211], v[16:19]
	v_mfma_f32_16x16x32_bf16 v[4:7], v[176:179], v[216:219], v[4:7]
	v_mfma_f32_16x16x32_bf16 v[0:3], v[184:187], v[216:219], v[0:3]
	s_setprio 0
	s_add_i32 s50, s50, 2
	s_add_u32 s24, s24, 0x100
	s_addc_u32 s25, s25, 0
	s_add_u32 s48, s48, 0x100
	s_addc_u32 s49, s49, 0
	s_cmp_gt_u32 s50, 61
	s_barrier
; #define PG8_LAS __attribute__((address_space(3)))
; __device__ __forceinline__ unsigned cvt_pk_bf16(float lo, float hi) { const f32x2_t v = {lo, hi}; const bf16x2_t b = __builtin_convertvector(v, bf16x2_t); return __builtin_bit_cast(unsigned, b); }
; #define PG8_BAR __builtin_amdgcn_s_barrier()
;     __device__ __forceinline__ void operator()(const f32x4 (&acc)[2][2][4][2], const Unit& u, int wr, int wc, int fr, int fq, const PG8_LAS float*) const {
;         const int row0 = u.pm * BM + wr * 64 + fr; const int col0 = u.pn * BM + wc * 32 + 8 * fq;
; #pragma unroll
;         for (int ai = 0; ai < 2; ++ai)
; #pragma unroll
;             for (int m = 0; m < 4; ++m) { const int row = row0 + ai * HALF + m * 16; const size_t off = (size_t)row * ldc + col0; float ss = 0.f;
; #pragma unroll
;                 for (int bj = 0; bj < 2; ++bj) {
;                     const f32x4 b0 = *(const f32x4*)(base + off + bj * HALF), b1 = *(const f32x4*)(base + off + bj * HALF + 4);
;                     const f32x4 v0 = b0 + acc[ai][bj][m][0], v1 = b1 + acc[ai][bj][m][1];
;                     *(f32x4*)(out + off + bj * HALF) = v0; *(f32x4*)(out + off + bj * HALF + 4) = v1;
;                     if (xb) { u32x4 w; w.x = cvt_pk_bf16(v0[0], v0[1]); w.y = cvt_pk_bf16(v0[2], v0[3]); w.z = cvt_pk_bf16(v1[0], v1[1]); w.w = cvt_pk_bf16(v1[2], v1[3]);
;                         *(u32x4*)(xb + off + bj * HALF) = w;
;                         ss += ((v0[0] * v0[0] + v0[1] * v0[1]) + (v0[2] * v0[2] + v0[3] * v0[3])) + ((v1[0] * v1[0] + v1[1] * v1[1]) + (v1[2] * v1[2] + v1[3] * v1[3])); } }
;                 if (xb) { ss += __shfl_xor(ss, 16); ss += __shfl_xor(ss, 32); if (fq == 0) ssq[(size_t)row * 16 + u.pn * 4 + wc] = ss; } }
; template <class Epi, class Sched, bool ALIGN_EPI = false, bool SP2 = false>
; __device__ __forceinline__ void gemm_phase(PG8_LAS unsigned char* lds, const Gemm g, const Sched& S, const Epi& E) {
;     ...
;         if constexpr (ALIGN_EPI) { if (wr == 0) PG8_BAR; }
	s_cbranch_scc0 .LBB0_842
	v_mbcnt_lo_u32_b32 v234, -1, 0
	v_mbcnt_hi_u32_b32 v234, -1, v234
	v_bfe_u32 v234, v234, 3, 1
	v_sub_u32_e32 v231, 0, v234
	v_and_b32_e32 v230, 0xffff8010, v231
	v_and_b32_e32 v235, 0x7ff0, v231
	v_sub_u32_e32 v244, 0x8000, v235
	v_mov_b32_e32 v245, 0
	s_mov_b32 s98, 0xff00ff
	s_mov_b32 s99, 0xff00ff
	s_and_b64 vcc, exec, s[12:13]
	s_cbranch_vccz .LBB0_845
	s_barrier
.LBB0_845:
	v_lshl_add_u32 v146, s22, 8, v148
	v_lshl_or_b32 v144, s6, 8, v150
	v_ashrrev_i32_e32 v147, 31, v146
	v_ashrrev_i32_e32 v145, 31, v144
	v_lshlrev_b64 v[156:157], 10, v[146:147]
	v_lshl_add_u64 v[164:165], v[156:157], 0, v[144:145]
	v_lshl_add_u64 v[172:173], v[164:165], 2, s[68:69]
	global_load_dwordx4 v[156:159], v[172:173], off
	global_load_dwordx4 v[160:163], v[172:173], off offset:16
	v_readlane_b32 s22, v254, 39
	v_readlane_b32 s23, v254, 40
	v_xor_b32_e32 v155, 32, v154
	s_waitcnt vmcnt(0)
	v_pk_add_f32 v[126:127], v[126:127], v[158:159]
	v_pk_add_f32 v[124:125], v[124:125], v[156:157]
	v_pk_add_f32 v[158:159], v[122:123], v[162:163]
	v_pk_add_f32 v[156:157], v[120:121], v[160:161]
	v_lshl_add_u64 v[164:165], v[164:165], 1, s[22:23]
	v_cvt_pk_bf16_f32 v120, v124, v125
	v_cvt_pk_bf16_f32 v121, v126, v127
	v_cvt_pk_bf16_f32 v122, v156, v157
	v_cvt_pk_bf16_f32 v123, v158, v159
	v_lshl_add_u64 v[228:229], v[172:173], 0, v[230:231]
	v_lshl_add_u64 v[232:233], v[172:173], 0, v[244:245]
	s_nop 1
	v_mov_b32_dpp v236, v156 row_ror:8 row_mask:0xf bank_mask:0xf
	v_mov_b32_dpp v237, v157 row_ror:8 row_mask:0xf bank_mask:0xf
	v_mov_b32_dpp v238, v158 row_ror:8 row_mask:0xf bank_mask:0xf
	v_mov_b32_dpp v239, v159 row_ror:8 row_mask:0xf bank_mask:0xf
	v_mov_b32_dpp v240, v124 row_ror:8 row_mask:0xf bank_mask:0xf
	v_mov_b32_dpp v241, v125 row_ror:8 row_mask:0xf bank_mask:0xf
	v_mov_b32_dpp v242, v126 row_ror:8 row_mask:0xf bank_mask:0xf
	v_mov_b32_dpp v243, v127 row_ror:8 row_mask:0xf bank_mask:0xf
	s_nop 0
	v_cndmask_b32_e64 v236, v236, v124, s[98:99]
	v_cndmask_b32_e64 v237, v237, v125, s[98:99]
	v_cndmask_b32_e64 v238, v238, v126, s[98:99]
	v_cndmask_b32_e64 v239, v239, v127, s[98:99]
	v_cndmask_b32_e64 v240, v156, v240, s[98:99]
	v_cndmask_b32_e64 v241, v157, v241, s[98:99]
	v_cndmask_b32_e64 v242, v158, v242, s[98:99]
	v_cndmask_b32_e64 v243, v159, v243, s[98:99]
	global_store_dwordx4 v[228:229], v[236:239], off
	global_store_dwordx4 v[232:233], v[240:243], off
	global_store_dwordx4 v[164:165], v[120:123], off
	global_load_dwordx4 v[160:163], v[172:173], off offset:512
	global_load_dwordx4 v[168:171], v[172:173], off offset:528
	v_mul_f32_e32 v122, v125, v125
	v_mul_f32_e32 v123, v127, v127
	v_mul_f32_e32 v125, v157, v157
	v_mul_f32_e32 v127, v159, v159
	v_fmac_f32_e32 v122, v124, v124
	v_fmac_f32_e32 v123, v126, v126
	v_fmac_f32_e32 v125, v156, v156
	v_fmac_f32_e32 v127, v158, v158
	v_add_f32_e32 v122, v122, v123
	v_add_f32_e32 v123, v125, v127
	v_add_f32_e32 v126, v122, v123
	v_and_b32_e32 v121, 64, v154
	v_xor_b32_e32 v120, 16, v154
	v_add_u32_e32 v121, 64, v121
	v_cmp_lt_i32_e32 vcc, v120, v121
	s_lshl_b32 s22, s6, 2
	s_ashr_i32 s23, s22, 31
	v_cndmask_b32_e32 v120, v154, v120, vcc
	v_lshlrev_b32_e32 v120, 2, v120
	v_cmp_lt_i32_e32 vcc, v155, v121
	s_waitcnt vmcnt(1)
	v_pk_add_f32 v[118:119], v[118:119], v[162:163]
	v_pk_add_f32 v[116:117], v[116:117], v[160:161]
	s_waitcnt vmcnt(0)
	v_pk_add_f32 v[124:125], v[114:115], v[170:171]
	v_pk_add_f32 v[122:123], v[112:113], v[168:169]
	v_mul_f32_e32 v112, v117, v117
	v_mul_f32_e32 v113, v119, v119
	v_mul_f32_e32 v114, v123, v123
	v_mul_f32_e32 v115, v125, v125
	v_fmac_f32_e32 v112, v116, v116
	v_fmac_f32_e32 v113, v118, v118
	v_fmac_f32_e32 v114, v122, v122
	v_fmac_f32_e32 v115, v124, v124
	v_add_f32_e32 v112, v112, v113
	v_add_f32_e32 v113, v114, v115
	v_add_f32_e32 v112, v112, v113
	v_add_f32_e32 v112, v126, v112
	v_mov_b32_e32 v113, v112
	s_nop 1
	v_permlane16_swap_b32_e32 v113, v112
	v_cndmask_b32_e32 v114, v154, v155, vcc
	v_lshlrev_b32_e32 v114, 2, v114
	v_lshl_add_u64 v[228:229], v[172:173], 0, v[230:231]
	v_lshl_add_u64 v[232:233], v[172:173], 0, v[244:245]
	s_nop 1
	v_mov_b32_dpp v236, v122 row_ror:8 row_mask:0xf bank_mask:0xf
	v_mov_b32_dpp v237, v123 row_ror:8 row_mask:0xf bank_mask:0xf
	v_mov_b32_dpp v238, v124 row_ror:8 row_mask:0xf bank_mask:0xf
	v_mov_b32_dpp v239, v125 row_ror:8 row_mask:0xf bank_mask:0xf
	v_mov_b32_dpp v240, v116 row_ror:8 row_mask:0xf bank_mask:0xf
	v_mov_b32_dpp v241, v117 row_ror:8 row_mask:0xf bank_mask:0xf
	v_mov_b32_dpp v242, v118 row_ror:8 row_mask:0xf bank_mask:0xf
	v_mov_b32_dpp v243, v119 row_ror:8 row_mask:0xf bank_mask:0xf
	s_nop 0
	v_cndmask_b32_e64 v236, v236, v116, s[98:99]
	v_cndmask_b32_e64 v237, v237, v117, s[98:99]
	v_cndmask_b32_e64 v238, v238, v118, s[98:99]
	v_cndmask_b32_e64 v239, v239, v119, s[98:99]
	v_cndmask_b32_e64 v240, v122, v240, s[98:99]
	v_cndmask_b32_e64 v241, v123, v241, s[98:99]
	v_cndmask_b32_e64 v242, v124, v242, s[98:99]
	v_cndmask_b32_e64 v243, v125, v243, s[98:99]
	global_store_dwordx4 v[228:229], v[236:239], off offset:512
	global_store_dwordx4 v[232:233], v[240:243], off offset:512
	s_waitcnt lgkmcnt(0)
	v_add_f32_e32 v112, v112, v113
	v_mov_b32_e32 v113, v112
	s_nop 1
	v_permlane32_swap_b32_e32 v113, v112
	v_cvt_pk_bf16_f32 v116, v116, v117
	v_cvt_pk_bf16_f32 v117, v118, v119
	v_cvt_pk_bf16_f32 v118, v122, v123
	v_cvt_pk_bf16_f32 v119, v124, v125
	global_store_dwordx4 v[164:165], v[116:119], off offset:256
	s_and_saveexec_b64 s[24:25], s[2:3]
	s_cbranch_execz .LBB0_847
	v_readlane_b32 s26, v254, 41
	s_waitcnt lgkmcnt(0)
	v_add_f32_e32 v115, v112, v113
	v_lshlrev_b64 v[112:113], 6, v[146:147]
	v_readlane_b32 s27, v254, 42
	s_lshl_b32 s6, s38, 2
	s_nop 0
	v_lshl_add_u64 v[112:113], s[26:27], 0, v[112:113]
	v_lshl_add_u64 v[112:113], s[22:23], 2, v[112:113]
	v_lshl_add_u64 v[112:113], v[112:113], 0, s[6:7]
	global_store_dword v[112:113], v115, off
; __device__ __forceinline__ unsigned cvt_pk_bf16(float lo, float hi) { const f32x2_t v = {lo, hi}; const bf16x2_t b = __builtin_convertvector(v, bf16x2_t); return __builtin_bit_cast(unsigned, b); }
;     __device__ __forceinline__ void operator()(const f32x4 (&acc)[2][2][4][2], const Unit& u, int wr, int wc, int fr, int fq, const PG8_LAS float*) const {
;     ...
;             for (int m = 0; m < 4; ++m) { const int row = row0 + ai * HALF + m * 16; const size_t off = (size_t)row * ldc + col0; float ss = 0.f;
; #pragma unroll
;                 for (int bj = 0; bj < 2; ++bj) {
;                     const f32x4 b0 = *(const f32x4*)(base + off + bj * HALF), b1 = *(const f32x4*)(base + off + bj * HALF + 4);
;                     const f32x4 v0 = b0 + acc[ai][bj][m][0], v1 = b1 + acc[ai][bj][m][1];
;                     *(f32x4*)(out + off + bj * HALF) = v0; *(f32x4*)(out + off + bj * HALF + 4) = v1;
;                     if (xb) { u32x4 w; w.x = cvt_pk_bf16(v0[0], v0[1]); w.y = cvt_pk_bf16(v0[2], v0[3]); w.z = cvt_pk_bf16(v1[0], v1[1]); w.w = cvt_pk_bf16(v1[2], v1[3]);
;                         *(u32x4*)(xb + off + bj * HALF) = w;
;                         ss += ((v0[0] * v0[0] + v0[1] * v0[1]) + (v0[2] * v0[2] + v0[3] * v0[3])) + ((v1[0] * v1[0] + v1[1] * v1[1]) + (v1[2] * v1[2] + v1[3] * v1[3])); } }
;                 if (xb) { ss += __shfl_xor(ss, 16); ss += __shfl_xor(ss, 32); if (fq == 0) ssq[(size_t)row * 16 + u.pn * 4 + wc] = ss; } }
.LBB0_847:
	s_or_b64 exec, exec, s[24:25]
	v_or_b32_e32 v112, 16, v146
	s_waitcnt lgkmcnt(0)
	v_ashrrev_i32_e32 v113, 31, v112
	v_lshlrev_b64 v[116:117], 10, v[112:113]
	v_lshl_add_u64 v[126:127], v[116:117], 0, v[144:145]
	v_lshl_add_u64 v[156:157], v[126:127], 2, s[68:69]
	global_load_dwordx4 v[116:119], v[156:157], off
	global_load_dwordx4 v[122:125], v[156:157], off offset:16
	v_readlane_b32 s24, v254, 39
	v_readlane_b32 s25, v254, 40
	s_waitcnt vmcnt(1)
	v_pk_add_f32 v[110:111], v[110:111], v[118:119]
	v_pk_add_f32 v[108:109], v[108:109], v[116:117]
	s_waitcnt vmcnt(0)
	v_pk_add_f32 v[106:107], v[106:107], v[124:125]
	v_pk_add_f32 v[104:105], v[104:105], v[122:123]
	v_lshl_add_u64 v[126:127], v[126:127], 1, s[24:25]
	v_cvt_pk_bf16_f32 v116, v108, v109
	v_cvt_pk_bf16_f32 v117, v110, v111
	v_cvt_pk_bf16_f32 v118, v104, v105
	v_cvt_pk_bf16_f32 v119, v106, v107
	v_lshl_add_u64 v[228:229], v[156:157], 0, v[230:231]
	v_lshl_add_u64 v[232:233], v[156:157], 0, v[244:245]
	s_nop 1
	v_mov_b32_dpp v236, v104 row_ror:8 row_mask:0xf bank_mask:0xf
	v_mov_b32_dpp v237, v105 row_ror:8 row_mask:0xf bank_mask:0xf
	v_mov_b32_dpp v238, v106 row_ror:8 row_mask:0xf bank_mask:0xf
	v_mov_b32_dpp v239, v107 row_ror:8 row_mask:0xf bank_mask:0xf
	v_mov_b32_dpp v240, v108 row_ror:8 row_mask:0xf bank_mask:0xf
	v_mov_b32_dpp v241, v109 row_ror:8 row_mask:0xf bank_mask:0xf
	v_mov_b32_dpp v242, v110 row_ror:8 row_mask:0xf bank_mask:0xf
	v_mov_b32_dpp v243, v111 row_ror:8 row_mask:0xf bank_mask:0xf
	s_nop 0
	v_cndmask_b32_e64 v236, v236, v108, s[98:99]
	v_cndmask_b32_e64 v237, v237, v109, s[98:99]
	v_cndmask_b32_e64 v238, v238, v110, s[98:99]
	v_cndmask_b32_e64 v239, v239, v111, s[98:99]
	v_cndmask_b32_e64 v240, v104, v240, s[98:99]
	v_cndmask_b32_e64 v241, v105, v241, s[98:99]
	v_cndmask_b32_e64 v242, v106, v242, s[98:99]
	v_cndmask_b32_e64 v243, v107, v243, s[98:99]
	global_store_dwordx4 v[228:229], v[236:239], off
	global_store_dwordx4 v[232:233], v[240:243], off
	global_store_dwordx4 v[126:127], v[116:119], off
	global_load_dwordx4 v[116:119], v[156:157], off offset:512
	s_nop 0
	global_load_dwordx4 v[122:125], v[156:157], off offset:528
	v_mul_f32_e32 v109, v109, v109
	v_mul_f32_e32 v111, v111, v111
	v_mul_f32_e32 v105, v105, v105
	v_mul_f32_e32 v107, v107, v107
	v_fmac_f32_e32 v109, v108, v108
	v_fmac_f32_e32 v111, v110, v110
	v_fmac_f32_e32 v105, v104, v104
	v_fmac_f32_e32 v107, v106, v106
	v_add_f32_e32 v104, v109, v111
	v_add_f32_e32 v105, v105, v107
	v_add_f32_e32 v108, v104, v105
	s_waitcnt vmcnt(1)
	v_pk_add_f32 v[102:103], v[102:103], v[118:119]
	v_pk_add_f32 v[100:101], v[100:101], v[116:117]
	s_waitcnt vmcnt(0)
	v_pk_add_f32 v[106:107], v[98:99], v[124:125]
	v_pk_add_f32 v[104:105], v[96:97], v[122:123]
	v_mul_f32_e32 v96, v101, v101
	v_mul_f32_e32 v97, v103, v103
	v_mul_f32_e32 v98, v105, v105
	v_mul_f32_e32 v99, v107, v107
	v_fmac_f32_e32 v96, v100, v100
	v_fmac_f32_e32 v97, v102, v102
	v_fmac_f32_e32 v98, v104, v104
	v_fmac_f32_e32 v99, v106, v106
	v_add_f32_e32 v96, v96, v97
	v_add_f32_e32 v97, v98, v99
	v_add_f32_e32 v96, v96, v97
	v_add_f32_e32 v96, v108, v96
	v_mov_b32_e32 v97, v96
	s_nop 1
	v_permlane16_swap_b32_e32 v97, v96
	v_lshl_add_u64 v[228:229], v[156:157], 0, v[230:231]
	v_lshl_add_u64 v[232:233], v[156:157], 0, v[244:245]
	s_nop 1
	v_mov_b32_dpp v236, v104 row_ror:8 row_mask:0xf bank_mask:0xf
	v_mov_b32_dpp v237, v105 row_ror:8 row_mask:0xf bank_mask:0xf
	v_mov_b32_dpp v238, v106 row_ror:8 row_mask:0xf bank_mask:0xf
	v_mov_b32_dpp v239, v107 row_ror:8 row_mask:0xf bank_mask:0xf
	v_mov_b32_dpp v240, v100 row_ror:8 row_mask:0xf bank_mask:0xf
	v_mov_b32_dpp v241, v101 row_ror:8 row_mask:0xf bank_mask:0xf
	v_mov_b32_dpp v242, v102 row_ror:8 row_mask:0xf bank_mask:0xf
	v_mov_b32_dpp v243, v103 row_ror:8 row_mask:0xf bank_mask:0xf
	s_nop 0
	v_cndmask_b32_e64 v236, v236, v100, s[98:99]
	v_cndmask_b32_e64 v237, v237, v101, s[98:99]
	v_cndmask_b32_e64 v238, v238, v102, s[98:99]
	v_cndmask_b32_e64 v239, v239, v103, s[98:99]
	v_cndmask_b32_e64 v240, v104, v240, s[98:99]
	v_cndmask_b32_e64 v241, v105, v241, s[98:99]
	v_cndmask_b32_e64 v242, v106, v242, s[98:99]
	v_cndmask_b32_e64 v243, v107, v243, s[98:99]
	global_store_dwordx4 v[228:229], v[236:239], off offset:512
	global_store_dwordx4 v[232:233], v[240:243], off offset:512
	v_cvt_pk_bf16_f32 v98, v100, v101
	v_cvt_pk_bf16_f32 v99, v102, v103
	v_cvt_pk_bf16_f32 v100, v104, v105
	s_waitcnt lgkmcnt(0)
	v_add_f32_e32 v96, v96, v97
	v_mov_b32_e32 v97, v96
	s_nop 1
	v_permlane32_swap_b32_e32 v97, v96
	v_cvt_pk_bf16_f32 v101, v106, v107
	global_store_dwordx4 v[126:127], v[98:101], off offset:256
	s_and_saveexec_b64 s[24:25], s[2:3]
	s_cbranch_execz .LBB0_849
	v_readlane_b32 s26, v254, 41
	s_waitcnt lgkmcnt(0)
	v_add_f32_e32 v98, v96, v97
	v_lshlrev_b64 v[96:97], 6, v[112:113]
	v_readlane_b32 s27, v254, 42
	s_lshl_b32 s6, s38, 2
	s_nop 0
	v_lshl_add_u64 v[96:97], s[26:27], 0, v[96:97]
	v_lshl_add_u64 v[96:97], s[22:23], 2, v[96:97]
	v_lshl_add_u64 v[96:97], v[96:97], 0, s[6:7]
	global_store_dword v[96:97], v98, off
; __device__ __forceinline__ unsigned cvt_pk_bf16(float lo, float hi) { const f32x2_t v = {lo, hi}; const bf16x2_t b = __builtin_convertvector(v, bf16x2_t); return __builtin_bit_cast(unsigned, b); }
;     __device__ __forceinline__ void operator()(const f32x4 (&acc)[2][2][4][2], const Unit& u, int wr, int wc, int fr, int fq, const PG8_LAS float*) const {
;     ...
;             for (int m = 0; m < 4; ++m) { const int row = row0 + ai * HALF + m * 16; const size_t off = (size_t)row * ldc + col0; float ss = 0.f;
; #pragma unroll
;                 for (int bj = 0; bj < 2; ++bj) {
;                     const f32x4 b0 = *(const f32x4*)(base + off + bj * HALF), b1 = *(const f32x4*)(base + off + bj * HALF + 4);
;                     const f32x4 v0 = b0 + acc[ai][bj][m][0], v1 = b1 + acc[ai][bj][m][1];
;                     *(f32x4*)(out + off + bj * HALF) = v0; *(f32x4*)(out + off + bj * HALF + 4) = v1;
;                     if (xb) { u32x4 w; w.x = cvt_pk_bf16(v0[0], v0[1]); w.y = cvt_pk_bf16(v0[2], v0[3]); w.z = cvt_pk_bf16(v1[0], v1[1]); w.w = cvt_pk_bf16(v1[2], v1[3]);
;                         *(u32x4*)(xb + off + bj * HALF) = w;
;                         ss += ((v0[0] * v0[0] + v0[1] * v0[1]) + (v0[2] * v0[2] + v0[3] * v0[3])) + ((v1[0] * v1[0] + v1[1] * v1[1]) + (v1[2] * v1[2] + v1[3] * v1[3])); } }
;                 if (xb) { ss += __shfl_xor(ss, 16); ss += __shfl_xor(ss, 32); if (fq == 0) ssq[(size_t)row * 16 + u.pn * 4 + wc] = ss; } }
.LBB0_849:
	s_or_b64 exec, exec, s[24:25]
	v_or_b32_e32 v96, 32, v146
	s_waitcnt lgkmcnt(0)
	v_ashrrev_i32_e32 v97, 31, v96
	v_lshlrev_b64 v[98:99], 10, v[96:97]
	v_lshl_add_u64 v[106:107], v[98:99], 0, v[144:145]
	v_lshl_add_u64 v[108:109], v[106:107], 2, s[68:69]
	global_load_dwordx4 v[98:101], v[108:109], off
	global_load_dwordx4 v[102:105], v[108:109], off offset:16
	v_readlane_b32 s24, v254, 39
	v_readlane_b32 s25, v254, 40
	s_waitcnt vmcnt(1)
	v_pk_add_f32 v[94:95], v[94:95], v[100:101]
	v_pk_add_f32 v[92:93], v[92:93], v[98:99]
	s_waitcnt vmcnt(0)
	v_pk_add_f32 v[90:91], v[90:91], v[104:105]
	v_pk_add_f32 v[88:89], v[88:89], v[102:103]
	v_lshl_add_u64 v[106:107], v[106:107], 1, s[24:25]
	v_cvt_pk_bf16_f32 v98, v92, v93
	v_cvt_pk_bf16_f32 v99, v94, v95
	v_cvt_pk_bf16_f32 v100, v88, v89
	v_cvt_pk_bf16_f32 v101, v90, v91
	v_lshl_add_u64 v[228:229], v[108:109], 0, v[230:231]
	v_lshl_add_u64 v[232:233], v[108:109], 0, v[244:245]
	s_nop 1
	v_mov_b32_dpp v236, v88 row_ror:8 row_mask:0xf bank_mask:0xf
	v_mov_b32_dpp v237, v89 row_ror:8 row_mask:0xf bank_mask:0xf
	v_mov_b32_dpp v238, v90 row_ror:8 row_mask:0xf bank_mask:0xf
	v_mov_b32_dpp v239, v91 row_ror:8 row_mask:0xf bank_mask:0xf
	v_mov_b32_dpp v240, v92 row_ror:8 row_mask:0xf bank_mask:0xf
	v_mov_b32_dpp v241, v93 row_ror:8 row_mask:0xf bank_mask:0xf
	v_mov_b32_dpp v242, v94 row_ror:8 row_mask:0xf bank_mask:0xf
	v_mov_b32_dpp v243, v95 row_ror:8 row_mask:0xf bank_mask:0xf
	s_nop 0
	v_cndmask_b32_e64 v236, v236, v92, s[98:99]
	v_cndmask_b32_e64 v237, v237, v93, s[98:99]
	v_cndmask_b32_e64 v238, v238, v94, s[98:99]
	v_cndmask_b32_e64 v239, v239, v95, s[98:99]
	v_cndmask_b32_e64 v240, v88, v240, s[98:99]
	v_cndmask_b32_e64 v241, v89, v241, s[98:99]
	v_cndmask_b32_e64 v242, v90, v242, s[98:99]
	v_cndmask_b32_e64 v243, v91, v243, s[98:99]
	global_store_dwordx4 v[228:229], v[236:239], off
	global_store_dwordx4 v[232:233], v[240:243], off
	global_store_dwordx4 v[106:107], v[98:101], off
	global_load_dwordx4 v[98:101], v[108:109], off offset:512
	s_nop 0
	global_load_dwordx4 v[102:105], v[108:109], off offset:528
	v_mul_f32_e32 v93, v93, v93
	v_mul_f32_e32 v95, v95, v95
	v_mul_f32_e32 v89, v89, v89
	v_mul_f32_e32 v91, v91, v91
	v_fmac_f32_e32 v93, v92, v92
	v_fmac_f32_e32 v95, v94, v94
	v_fmac_f32_e32 v89, v88, v88
	v_fmac_f32_e32 v91, v90, v90
	v_add_f32_e32 v88, v93, v95
	v_add_f32_e32 v89, v89, v91
	v_add_f32_e32 v92, v88, v89
	s_waitcnt vmcnt(1)
	v_pk_add_f32 v[86:87], v[86:87], v[100:101]
	v_pk_add_f32 v[84:85], v[84:85], v[98:99]
	s_waitcnt vmcnt(0)
	v_pk_add_f32 v[90:91], v[82:83], v[104:105]
	v_pk_add_f32 v[88:89], v[80:81], v[102:103]
	v_mul_f32_e32 v80, v85, v85
	v_mul_f32_e32 v81, v87, v87
	v_mul_f32_e32 v82, v89, v89
	v_mul_f32_e32 v83, v91, v91
	v_fmac_f32_e32 v80, v84, v84
	v_fmac_f32_e32 v81, v86, v86
	v_fmac_f32_e32 v82, v88, v88
	v_fmac_f32_e32 v83, v90, v90
	v_add_f32_e32 v80, v80, v81
	v_add_f32_e32 v81, v82, v83
	v_add_f32_e32 v80, v80, v81
	v_add_f32_e32 v80, v92, v80
	v_mov_b32_e32 v81, v80
	s_nop 1
	v_permlane16_swap_b32_e32 v81, v80
	v_lshl_add_u64 v[228:229], v[108:109], 0, v[230:231]
	v_lshl_add_u64 v[232:233], v[108:109], 0, v[244:245]
	s_nop 1
	v_mov_b32_dpp v236, v88 row_ror:8 row_mask:0xf bank_mask:0xf
	v_mov_b32_dpp v237, v89 row_ror:8 row_mask:0xf bank_mask:0xf
	v_mov_b32_dpp v238, v90 row_ror:8 row_mask:0xf bank_mask:0xf
	v_mov_b32_dpp v239, v91 row_ror:8 row_mask:0xf bank_mask:0xf
	v_mov_b32_dpp v240, v84 row_ror:8 row_mask:0xf bank_mask:0xf
	v_mov_b32_dpp v241, v85 row_ror:8 row_mask:0xf bank_mask:0xf
	v_mov_b32_dpp v242, v86 row_ror:8 row_mask:0xf bank_mask:0xf
	v_mov_b32_dpp v243, v87 row_ror:8 row_mask:0xf bank_mask:0xf
	s_nop 0
	v_cndmask_b32_e64 v236, v236, v84, s[98:99]
	v_cndmask_b32_e64 v237, v237, v85, s[98:99]
	v_cndmask_b32_e64 v238, v238, v86, s[98:99]
	v_cndmask_b32_e64 v239, v239, v87, s[98:99]
	v_cndmask_b32_e64 v240, v88, v240, s[98:99]
	v_cndmask_b32_e64 v241, v89, v241, s[98:99]
	v_cndmask_b32_e64 v242, v90, v242, s[98:99]
	v_cndmask_b32_e64 v243, v91, v243, s[98:99]
	global_store_dwordx4 v[228:229], v[236:239], off offset:512
	global_store_dwordx4 v[232:233], v[240:243], off offset:512
	v_cvt_pk_bf16_f32 v82, v84, v85
	v_cvt_pk_bf16_f32 v83, v86, v87
	v_cvt_pk_bf16_f32 v84, v88, v89
	s_waitcnt lgkmcnt(0)
	v_add_f32_e32 v80, v80, v81
	v_mov_b32_e32 v81, v80
	s_nop 1
	v_permlane32_swap_b32_e32 v81, v80
	v_cvt_pk_bf16_f32 v85, v90, v91
	global_store_dwordx4 v[106:107], v[82:85], off offset:256
	s_and_saveexec_b64 s[24:25], s[2:3]
	s_cbranch_execz .LBB0_851
	v_readlane_b32 s26, v254, 41
	s_waitcnt lgkmcnt(0)
	v_add_f32_e32 v82, v80, v81
	v_lshlrev_b64 v[80:81], 6, v[96:97]
	v_readlane_b32 s27, v254, 42
	s_lshl_b32 s6, s38, 2
	s_nop 0
	v_lshl_add_u64 v[80:81], s[26:27], 0, v[80:81]
	v_lshl_add_u64 v[80:81], s[22:23], 2, v[80:81]
	v_lshl_add_u64 v[80:81], v[80:81], 0, s[6:7]
	global_store_dword v[80:81], v82, off
; __device__ __forceinline__ unsigned cvt_pk_bf16(float lo, float hi) { const f32x2_t v = {lo, hi}; const bf16x2_t b = __builtin_convertvector(v, bf16x2_t); return __builtin_bit_cast(unsigned, b); }
;     __device__ __forceinline__ void operator()(const f32x4 (&acc)[2][2][4][2], const Unit& u, int wr, int wc, int fr, int fq, const PG8_LAS float*) const {
;     ...
;             for (int m = 0; m < 4; ++m) { const int row = row0 + ai * HALF + m * 16; const size_t off = (size_t)row * ldc + col0; float ss = 0.f;
; #pragma unroll
;                 for (int bj = 0; bj < 2; ++bj) {
;                     const f32x4 b0 = *(const f32x4*)(base + off + bj * HALF), b1 = *(const f32x4*)(base + off + bj * HALF + 4);
;                     const f32x4 v0 = b0 + acc[ai][bj][m][0], v1 = b1 + acc[ai][bj][m][1];
;                     *(f32x4*)(out + off + bj * HALF) = v0; *(f32x4*)(out + off + bj * HALF + 4) = v1;
;                     if (xb) { u32x4 w; w.x = cvt_pk_bf16(v0[0], v0[1]); w.y = cvt_pk_bf16(v0[2], v0[3]); w.z = cvt_pk_bf16(v1[0], v1[1]); w.w = cvt_pk_bf16(v1[2], v1[3]);
;                         *(u32x4*)(xb + off + bj * HALF) = w;
;                         ss += ((v0[0] * v0[0] + v0[1] * v0[1]) + (v0[2] * v0[2] + v0[3] * v0[3])) + ((v1[0] * v1[0] + v1[1] * v1[1]) + (v1[2] * v1[2] + v1[3] * v1[3])); } }
;                 if (xb) { ss += __shfl_xor(ss, 16); ss += __shfl_xor(ss, 32); if (fq == 0) ssq[(size_t)row * 16 + u.pn * 4 + wc] = ss; } }
.LBB0_851:
	s_or_b64 exec, exec, s[24:25]
	v_or_b32_e32 v80, 48, v146
	s_waitcnt lgkmcnt(0)
	v_ashrrev_i32_e32 v81, 31, v80
	v_lshlrev_b64 v[82:83], 10, v[80:81]
	v_lshl_add_u64 v[90:91], v[82:83], 0, v[144:145]
	v_lshl_add_u64 v[92:93], v[90:91], 2, s[68:69]
	global_load_dwordx4 v[82:85], v[92:93], off
	global_load_dwordx4 v[86:89], v[92:93], off offset:16
	v_readlane_b32 s24, v254, 39
	v_readlane_b32 s25, v254, 40
	s_waitcnt vmcnt(1)
	v_pk_add_f32 v[78:79], v[78:79], v[84:85]
	v_pk_add_f32 v[76:77], v[76:77], v[82:83]
	s_waitcnt vmcnt(0)
	v_pk_add_f32 v[74:75], v[74:75], v[88:89]
	v_pk_add_f32 v[72:73], v[72:73], v[86:87]
	v_lshl_add_u64 v[90:91], v[90:91], 1, s[24:25]
	v_cvt_pk_bf16_f32 v82, v76, v77
	v_cvt_pk_bf16_f32 v83, v78, v79
	v_cvt_pk_bf16_f32 v84, v72, v73
	v_cvt_pk_bf16_f32 v85, v74, v75
	v_lshl_add_u64 v[228:229], v[92:93], 0, v[230:231]
	v_lshl_add_u64 v[232:233], v[92:93], 0, v[244:245]
	s_nop 1
	v_mov_b32_dpp v236, v72 row_ror:8 row_mask:0xf bank_mask:0xf
	v_mov_b32_dpp v237, v73 row_ror:8 row_mask:0xf bank_mask:0xf
	v_mov_b32_dpp v238, v74 row_ror:8 row_mask:0xf bank_mask:0xf
	v_mov_b32_dpp v239, v75 row_ror:8 row_mask:0xf bank_mask:0xf
	v_mov_b32_dpp v240, v76 row_ror:8 row_mask:0xf bank_mask:0xf
	v_mov_b32_dpp v241, v77 row_ror:8 row_mask:0xf bank_mask:0xf
	v_mov_b32_dpp v242, v78 row_ror:8 row_mask:0xf bank_mask:0xf
	v_mov_b32_dpp v243, v79 row_ror:8 row_mask:0xf bank_mask:0xf
	s_nop 0
	v_cndmask_b32_e64 v236, v236, v76, s[98:99]
	v_cndmask_b32_e64 v237, v237, v77, s[98:99]
	v_cndmask_b32_e64 v238, v238, v78, s[98:99]
	v_cndmask_b32_e64 v239, v239, v79, s[98:99]
	v_cndmask_b32_e64 v240, v72, v240, s[98:99]
	v_cndmask_b32_e64 v241, v73, v241, s[98:99]
	v_cndmask_b32_e64 v242, v74, v242, s[98:99]
	v_cndmask_b32_e64 v243, v75, v243, s[98:99]
	global_store_dwordx4 v[228:229], v[236:239], off
	global_store_dwordx4 v[232:233], v[240:243], off
	global_store_dwordx4 v[90:91], v[82:85], off
	global_load_dwordx4 v[82:85], v[92:93], off offset:512
	s_nop 0
	global_load_dwordx4 v[86:89], v[92:93], off offset:528
	v_mul_f32_e32 v77, v77, v77
	v_mul_f32_e32 v79, v79, v79
	v_mul_f32_e32 v73, v73, v73
	v_mul_f32_e32 v75, v75, v75
	v_fmac_f32_e32 v77, v76, v76
	v_fmac_f32_e32 v79, v78, v78
	v_fmac_f32_e32 v73, v72, v72
	v_fmac_f32_e32 v75, v74, v74
	v_add_f32_e32 v72, v77, v79
	v_add_f32_e32 v73, v73, v75
	v_add_f32_e32 v76, v72, v73
	s_waitcnt vmcnt(1)
	v_pk_add_f32 v[70:71], v[70:71], v[84:85]
	v_pk_add_f32 v[68:69], v[68:69], v[82:83]
	s_waitcnt vmcnt(0)
	v_pk_add_f32 v[74:75], v[66:67], v[88:89]
	v_pk_add_f32 v[72:73], v[64:65], v[86:87]
	v_mul_f32_e32 v64, v69, v69
	v_mul_f32_e32 v65, v71, v71
	v_mul_f32_e32 v66, v73, v73
	v_mul_f32_e32 v67, v75, v75
	v_fmac_f32_e32 v64, v68, v68
	v_fmac_f32_e32 v65, v70, v70
	v_fmac_f32_e32 v66, v72, v72
	v_fmac_f32_e32 v67, v74, v74
	v_add_f32_e32 v64, v64, v65
	v_add_f32_e32 v65, v66, v67
	v_add_f32_e32 v64, v64, v65
	v_add_f32_e32 v64, v76, v64
	v_mov_b32_e32 v65, v64
	s_nop 1
	v_permlane16_swap_b32_e32 v65, v64
	v_lshl_add_u64 v[228:229], v[92:93], 0, v[230:231]
	v_lshl_add_u64 v[232:233], v[92:93], 0, v[244:245]
	s_nop 1
	v_mov_b32_dpp v236, v72 row_ror:8 row_mask:0xf bank_mask:0xf
	v_mov_b32_dpp v237, v73 row_ror:8 row_mask:0xf bank_mask:0xf
	v_mov_b32_dpp v238, v74 row_ror:8 row_mask:0xf bank_mask:0xf
	v_mov_b32_dpp v239, v75 row_ror:8 row_mask:0xf bank_mask:0xf
	v_mov_b32_dpp v240, v68 row_ror:8 row_mask:0xf bank_mask:0xf
	v_mov_b32_dpp v241, v69 row_ror:8 row_mask:0xf bank_mask:0xf
	v_mov_b32_dpp v242, v70 row_ror:8 row_mask:0xf bank_mask:0xf
	v_mov_b32_dpp v243, v71 row_ror:8 row_mask:0xf bank_mask:0xf
	s_nop 0
	v_cndmask_b32_e64 v236, v236, v68, s[98:99]
	v_cndmask_b32_e64 v237, v237, v69, s[98:99]
	v_cndmask_b32_e64 v238, v238, v70, s[98:99]
	v_cndmask_b32_e64 v239, v239, v71, s[98:99]
	v_cndmask_b32_e64 v240, v72, v240, s[98:99]
	v_cndmask_b32_e64 v241, v73, v241, s[98:99]
	v_cndmask_b32_e64 v242, v74, v242, s[98:99]
	v_cndmask_b32_e64 v243, v75, v243, s[98:99]
	global_store_dwordx4 v[228:229], v[236:239], off offset:512
	global_store_dwordx4 v[232:233], v[240:243], off offset:512
	v_cvt_pk_bf16_f32 v66, v68, v69
	v_cvt_pk_bf16_f32 v67, v70, v71
	v_cvt_pk_bf16_f32 v68, v72, v73
	s_waitcnt lgkmcnt(0)
	v_add_f32_e32 v64, v64, v65
	v_mov_b32_e32 v65, v64
	s_nop 1
	v_permlane32_swap_b32_e32 v65, v64
	v_cvt_pk_bf16_f32 v69, v74, v75
	global_store_dwordx4 v[90:91], v[66:69], off offset:256
	s_and_saveexec_b64 s[24:25], s[2:3]
	s_cbranch_execz .LBB0_853
	v_readlane_b32 s26, v254, 41
	s_waitcnt lgkmcnt(0)
	v_add_f32_e32 v66, v64, v65
	v_lshlrev_b64 v[64:65], 6, v[80:81]
	v_readlane_b32 s27, v254, 42
	s_lshl_b32 s6, s38, 2
	s_nop 0
	v_lshl_add_u64 v[64:65], s[26:27], 0, v[64:65]
	v_lshl_add_u64 v[64:65], s[22:23], 2, v[64:65]
	v_lshl_add_u64 v[64:65], v[64:65], 0, s[6:7]
	global_store_dword v[64:65], v66, off
; __device__ __forceinline__ unsigned cvt_pk_bf16(float lo, float hi) { const f32x2_t v = {lo, hi}; const bf16x2_t b = __builtin_convertvector(v, bf16x2_t); return __builtin_bit_cast(unsigned, b); }
;     __device__ __forceinline__ void operator()(const f32x4 (&acc)[2][2][4][2], const Unit& u, int wr, int wc, int fr, int fq, const PG8_LAS float*) const {
;     ...
;             for (int m = 0; m < 4; ++m) { const int row = row0 + ai * HALF + m * 16; const size_t off = (size_t)row * ldc + col0; float ss = 0.f;
; #pragma unroll
;                 for (int bj = 0; bj < 2; ++bj) {
;                     const f32x4 b0 = *(const f32x4*)(base + off + bj * HALF), b1 = *(const f32x4*)(base + off + bj * HALF + 4);
;                     const f32x4 v0 = b0 + acc[ai][bj][m][0], v1 = b1 + acc[ai][bj][m][1];
;                     *(f32x4*)(out + off + bj * HALF) = v0; *(f32x4*)(out + off + bj * HALF + 4) = v1;
;                     if (xb) { u32x4 w; w.x = cvt_pk_bf16(v0[0], v0[1]); w.y = cvt_pk_bf16(v0[2], v0[3]); w.z = cvt_pk_bf16(v1[0], v1[1]); w.w = cvt_pk_bf16(v1[2], v1[3]);
;                         *(u32x4*)(xb + off + bj * HALF) = w;
;                         ss += ((v0[0] * v0[0] + v0[1] * v0[1]) + (v0[2] * v0[2] + v0[3] * v0[3])) + ((v1[0] * v1[0] + v1[1] * v1[1]) + (v1[2] * v1[2] + v1[3] * v1[3])); } }
;                 if (xb) { ss += __shfl_xor(ss, 16); ss += __shfl_xor(ss, 32); if (fq == 0) ssq[(size_t)row * 16 + u.pn * 4 + wc] = ss; } }
.LBB0_853:
	s_or_b64 exec, exec, s[24:25]
	v_add_u32_e32 v64, 0x80, v146
	s_waitcnt lgkmcnt(0)
	v_ashrrev_i32_e32 v65, 31, v64
	v_lshlrev_b64 v[66:67], 10, v[64:65]
	v_lshl_add_u64 v[74:75], v[66:67], 0, v[144:145]
	v_lshl_add_u64 v[76:77], v[74:75], 2, s[68:69]
	global_load_dwordx4 v[66:69], v[76:77], off
	global_load_dwordx4 v[70:73], v[76:77], off offset:16
	v_readlane_b32 s24, v254, 39
	v_readlane_b32 s25, v254, 40
	s_waitcnt vmcnt(1)
	v_pk_add_f32 v[62:63], v[62:63], v[68:69]
	v_pk_add_f32 v[60:61], v[60:61], v[66:67]
	s_waitcnt vmcnt(0)
	v_pk_add_f32 v[58:59], v[58:59], v[72:73]
	v_pk_add_f32 v[56:57], v[56:57], v[70:71]
	v_lshl_add_u64 v[74:75], v[74:75], 1, s[24:25]
	v_cvt_pk_bf16_f32 v66, v60, v61
	v_cvt_pk_bf16_f32 v67, v62, v63
	v_cvt_pk_bf16_f32 v68, v56, v57
	v_cvt_pk_bf16_f32 v69, v58, v59
	v_lshl_add_u64 v[228:229], v[76:77], 0, v[230:231]
	v_lshl_add_u64 v[232:233], v[76:77], 0, v[244:245]
	s_nop 1
	v_mov_b32_dpp v236, v56 row_ror:8 row_mask:0xf bank_mask:0xf
	v_mov_b32_dpp v237, v57 row_ror:8 row_mask:0xf bank_mask:0xf
	v_mov_b32_dpp v238, v58 row_ror:8 row_mask:0xf bank_mask:0xf
	v_mov_b32_dpp v239, v59 row_ror:8 row_mask:0xf bank_mask:0xf
	v_mov_b32_dpp v240, v60 row_ror:8 row_mask:0xf bank_mask:0xf
	v_mov_b32_dpp v241, v61 row_ror:8 row_mask:0xf bank_mask:0xf
	v_mov_b32_dpp v242, v62 row_ror:8 row_mask:0xf bank_mask:0xf
	v_mov_b32_dpp v243, v63 row_ror:8 row_mask:0xf bank_mask:0xf
	s_nop 0
	v_cndmask_b32_e64 v236, v236, v60, s[98:99]
	v_cndmask_b32_e64 v237, v237, v61, s[98:99]
	v_cndmask_b32_e64 v238, v238, v62, s[98:99]
	v_cndmask_b32_e64 v239, v239, v63, s[98:99]
	v_cndmask_b32_e64 v240, v56, v240, s[98:99]
	v_cndmask_b32_e64 v241, v57, v241, s[98:99]
	v_cndmask_b32_e64 v242, v58, v242, s[98:99]
	v_cndmask_b32_e64 v243, v59, v243, s[98:99]
	global_store_dwordx4 v[228:229], v[236:239], off
	global_store_dwordx4 v[232:233], v[240:243], off
	global_store_dwordx4 v[74:75], v[66:69], off
	global_load_dwordx4 v[66:69], v[76:77], off offset:512
	s_nop 0
	global_load_dwordx4 v[70:73], v[76:77], off offset:528
	v_mul_f32_e32 v61, v61, v61
	v_mul_f32_e32 v63, v63, v63
	v_mul_f32_e32 v57, v57, v57
	v_mul_f32_e32 v59, v59, v59
	v_fmac_f32_e32 v61, v60, v60
	v_fmac_f32_e32 v63, v62, v62
	v_fmac_f32_e32 v57, v56, v56
	v_fmac_f32_e32 v59, v58, v58
	v_add_f32_e32 v56, v61, v63
	v_add_f32_e32 v57, v57, v59
	v_add_f32_e32 v60, v56, v57
	s_waitcnt vmcnt(1)
	v_pk_add_f32 v[54:55], v[54:55], v[68:69]
	v_pk_add_f32 v[52:53], v[52:53], v[66:67]
	s_waitcnt vmcnt(0)
	v_pk_add_f32 v[58:59], v[50:51], v[72:73]
	v_pk_add_f32 v[56:57], v[48:49], v[70:71]
	v_mul_f32_e32 v48, v53, v53
	v_mul_f32_e32 v49, v55, v55
	v_mul_f32_e32 v50, v57, v57
	v_mul_f32_e32 v51, v59, v59
	v_fmac_f32_e32 v48, v52, v52
	v_fmac_f32_e32 v49, v54, v54
	v_fmac_f32_e32 v50, v56, v56
	v_fmac_f32_e32 v51, v58, v58
	v_add_f32_e32 v48, v48, v49
	v_add_f32_e32 v49, v50, v51
	v_add_f32_e32 v48, v48, v49
	v_add_f32_e32 v48, v60, v48
	v_mov_b32_e32 v49, v48
	s_nop 1
	v_permlane16_swap_b32_e32 v49, v48
	v_lshl_add_u64 v[228:229], v[76:77], 0, v[230:231]
	v_lshl_add_u64 v[232:233], v[76:77], 0, v[244:245]
	s_nop 1
	v_mov_b32_dpp v236, v56 row_ror:8 row_mask:0xf bank_mask:0xf
	v_mov_b32_dpp v237, v57 row_ror:8 row_mask:0xf bank_mask:0xf
	v_mov_b32_dpp v238, v58 row_ror:8 row_mask:0xf bank_mask:0xf
	v_mov_b32_dpp v239, v59 row_ror:8 row_mask:0xf bank_mask:0xf
	v_mov_b32_dpp v240, v52 row_ror:8 row_mask:0xf bank_mask:0xf
	v_mov_b32_dpp v241, v53 row_ror:8 row_mask:0xf bank_mask:0xf
	v_mov_b32_dpp v242, v54 row_ror:8 row_mask:0xf bank_mask:0xf
	v_mov_b32_dpp v243, v55 row_ror:8 row_mask:0xf bank_mask:0xf
	s_nop 0
	v_cndmask_b32_e64 v236, v236, v52, s[98:99]
	v_cndmask_b32_e64 v237, v237, v53, s[98:99]
	v_cndmask_b32_e64 v238, v238, v54, s[98:99]
	v_cndmask_b32_e64 v239, v239, v55, s[98:99]
	v_cndmask_b32_e64 v240, v56, v240, s[98:99]
	v_cndmask_b32_e64 v241, v57, v241, s[98:99]
	v_cndmask_b32_e64 v242, v58, v242, s[98:99]
	v_cndmask_b32_e64 v243, v59, v243, s[98:99]
	global_store_dwordx4 v[228:229], v[236:239], off offset:512
	global_store_dwordx4 v[232:233], v[240:243], off offset:512
	v_cvt_pk_bf16_f32 v50, v52, v53
	v_cvt_pk_bf16_f32 v51, v54, v55
	v_cvt_pk_bf16_f32 v52, v56, v57
	s_waitcnt lgkmcnt(0)
	v_add_f32_e32 v48, v48, v49
	v_mov_b32_e32 v49, v48
	s_nop 1
	v_permlane32_swap_b32_e32 v49, v48
	v_cvt_pk_bf16_f32 v53, v58, v59
	global_store_dwordx4 v[74:75], v[50:53], off offset:256
	s_and_saveexec_b64 s[24:25], s[2:3]
	s_cbranch_execz .LBB0_855
	v_readlane_b32 s26, v254, 41
	s_waitcnt lgkmcnt(0)
	v_add_f32_e32 v50, v48, v49
	v_lshlrev_b64 v[48:49], 6, v[64:65]
	v_readlane_b32 s27, v254, 42
	s_lshl_b32 s6, s38, 2
	s_nop 0
	v_lshl_add_u64 v[48:49], s[26:27], 0, v[48:49]
	v_lshl_add_u64 v[48:49], s[22:23], 2, v[48:49]
	v_lshl_add_u64 v[48:49], v[48:49], 0, s[6:7]
	global_store_dword v[48:49], v50, off
; __device__ __forceinline__ unsigned cvt_pk_bf16(float lo, float hi) { const f32x2_t v = {lo, hi}; const bf16x2_t b = __builtin_convertvector(v, bf16x2_t); return __builtin_bit_cast(unsigned, b); }
;     __device__ __forceinline__ void operator()(const f32x4 (&acc)[2][2][4][2], const Unit& u, int wr, int wc, int fr, int fq, const PG8_LAS float*) const {
;     ...
;             for (int m = 0; m < 4; ++m) { const int row = row0 + ai * HALF + m * 16; const size_t off = (size_t)row * ldc + col0; float ss = 0.f;
; #pragma unroll
;                 for (int bj = 0; bj < 2; ++bj) {
;                     const f32x4 b0 = *(const f32x4*)(base + off + bj * HALF), b1 = *(const f32x4*)(base + off + bj * HALF + 4);
;                     const f32x4 v0 = b0 + acc[ai][bj][m][0], v1 = b1 + acc[ai][bj][m][1];
;                     *(f32x4*)(out + off + bj * HALF) = v0; *(f32x4*)(out + off + bj * HALF + 4) = v1;
;                     if (xb) { u32x4 w; w.x = cvt_pk_bf16(v0[0], v0[1]); w.y = cvt_pk_bf16(v0[2], v0[3]); w.z = cvt_pk_bf16(v1[0], v1[1]); w.w = cvt_pk_bf16(v1[2], v1[3]);
;                         *(u32x4*)(xb + off + bj * HALF) = w;
;                         ss += ((v0[0] * v0[0] + v0[1] * v0[1]) + (v0[2] * v0[2] + v0[3] * v0[3])) + ((v1[0] * v1[0] + v1[1] * v1[1]) + (v1[2] * v1[2] + v1[3] * v1[3])); } }
;                 if (xb) { ss += __shfl_xor(ss, 16); ss += __shfl_xor(ss, 32); if (fq == 0) ssq[(size_t)row * 16 + u.pn * 4 + wc] = ss; } }
.LBB0_855:
	s_or_b64 exec, exec, s[24:25]
	v_add_u32_e32 v48, 0x90, v146
	s_waitcnt lgkmcnt(0)
	v_ashrrev_i32_e32 v49, 31, v48
	v_lshlrev_b64 v[50:51], 10, v[48:49]
	v_lshl_add_u64 v[58:59], v[50:51], 0, v[144:145]
	v_lshl_add_u64 v[60:61], v[58:59], 2, s[68:69]
	global_load_dwordx4 v[50:53], v[60:61], off
	global_load_dwordx4 v[54:57], v[60:61], off offset:16
	v_readlane_b32 s24, v254, 39
	v_readlane_b32 s25, v254, 40
	s_waitcnt vmcnt(1)
	v_pk_add_f32 v[46:47], v[46:47], v[52:53]
	v_pk_add_f32 v[44:45], v[44:45], v[50:51]
	s_waitcnt vmcnt(0)
	v_pk_add_f32 v[42:43], v[42:43], v[56:57]
	v_pk_add_f32 v[40:41], v[40:41], v[54:55]
	v_lshl_add_u64 v[58:59], v[58:59], 1, s[24:25]
	v_cvt_pk_bf16_f32 v50, v44, v45
	v_cvt_pk_bf16_f32 v51, v46, v47
	v_cvt_pk_bf16_f32 v52, v40, v41
	v_cvt_pk_bf16_f32 v53, v42, v43
	v_lshl_add_u64 v[228:229], v[60:61], 0, v[230:231]
	v_lshl_add_u64 v[232:233], v[60:61], 0, v[244:245]
	s_nop 1
	v_mov_b32_dpp v236, v40 row_ror:8 row_mask:0xf bank_mask:0xf
	v_mov_b32_dpp v237, v41 row_ror:8 row_mask:0xf bank_mask:0xf
	v_mov_b32_dpp v238, v42 row_ror:8 row_mask:0xf bank_mask:0xf
	v_mov_b32_dpp v239, v43 row_ror:8 row_mask:0xf bank_mask:0xf
	v_mov_b32_dpp v240, v44 row_ror:8 row_mask:0xf bank_mask:0xf
	v_mov_b32_dpp v241, v45 row_ror:8 row_mask:0xf bank_mask:0xf
	v_mov_b32_dpp v242, v46 row_ror:8 row_mask:0xf bank_mask:0xf
	v_mov_b32_dpp v243, v47 row_ror:8 row_mask:0xf bank_mask:0xf
	s_nop 0
	v_cndmask_b32_e64 v236, v236, v44, s[98:99]
	v_cndmask_b32_e64 v237, v237, v45, s[98:99]
	v_cndmask_b32_e64 v238, v238, v46, s[98:99]
	v_cndmask_b32_e64 v239, v239, v47, s[98:99]
	v_cndmask_b32_e64 v240, v40, v240, s[98:99]
	v_cndmask_b32_e64 v241, v41, v241, s[98:99]
	v_cndmask_b32_e64 v242, v42, v242, s[98:99]
	v_cndmask_b32_e64 v243, v43, v243, s[98:99]
	global_store_dwordx4 v[228:229], v[236:239], off
	global_store_dwordx4 v[232:233], v[240:243], off
	global_store_dwordx4 v[58:59], v[50:53], off
	global_load_dwordx4 v[50:53], v[60:61], off offset:512
	s_nop 0
	global_load_dwordx4 v[54:57], v[60:61], off offset:528
	v_mul_f32_e32 v45, v45, v45
	v_mul_f32_e32 v47, v47, v47
	v_mul_f32_e32 v41, v41, v41
	v_mul_f32_e32 v43, v43, v43
	v_fmac_f32_e32 v45, v44, v44
	v_fmac_f32_e32 v47, v46, v46
	v_fmac_f32_e32 v41, v40, v40
	v_fmac_f32_e32 v43, v42, v42
	v_add_f32_e32 v40, v45, v47
	v_add_f32_e32 v41, v41, v43
	v_add_f32_e32 v44, v40, v41
	s_waitcnt vmcnt(1)
	v_pk_add_f32 v[38:39], v[38:39], v[52:53]
	v_pk_add_f32 v[36:37], v[36:37], v[50:51]
	s_waitcnt vmcnt(0)
	v_pk_add_f32 v[42:43], v[34:35], v[56:57]
	v_pk_add_f32 v[40:41], v[32:33], v[54:55]
	v_mul_f32_e32 v32, v37, v37
	v_mul_f32_e32 v33, v39, v39
	v_mul_f32_e32 v34, v41, v41
	v_mul_f32_e32 v35, v43, v43
	v_fmac_f32_e32 v32, v36, v36
	v_fmac_f32_e32 v33, v38, v38
	v_fmac_f32_e32 v34, v40, v40
	v_fmac_f32_e32 v35, v42, v42
	v_add_f32_e32 v32, v32, v33
	v_add_f32_e32 v33, v34, v35
	v_add_f32_e32 v32, v32, v33
	v_add_f32_e32 v32, v44, v32
	v_mov_b32_e32 v33, v32
	s_nop 1
	v_permlane16_swap_b32_e32 v33, v32
	v_lshl_add_u64 v[228:229], v[60:61], 0, v[230:231]
	v_lshl_add_u64 v[232:233], v[60:61], 0, v[244:245]
	s_nop 1
	v_mov_b32_dpp v236, v40 row_ror:8 row_mask:0xf bank_mask:0xf
	v_mov_b32_dpp v237, v41 row_ror:8 row_mask:0xf bank_mask:0xf
	v_mov_b32_dpp v238, v42 row_ror:8 row_mask:0xf bank_mask:0xf
	v_mov_b32_dpp v239, v43 row_ror:8 row_mask:0xf bank_mask:0xf
	v_mov_b32_dpp v240, v36 row_ror:8 row_mask:0xf bank_mask:0xf
	v_mov_b32_dpp v241, v37 row_ror:8 row_mask:0xf bank_mask:0xf
	v_mov_b32_dpp v242, v38 row_ror:8 row_mask:0xf bank_mask:0xf
	v_mov_b32_dpp v243, v39 row_ror:8 row_mask:0xf bank_mask:0xf
	s_nop 0
	v_cndmask_b32_e64 v236, v236, v36, s[98:99]
	v_cndmask_b32_e64 v237, v237, v37, s[98:99]
	v_cndmask_b32_e64 v238, v238, v38, s[98:99]
	v_cndmask_b32_e64 v239, v239, v39, s[98:99]
	v_cndmask_b32_e64 v240, v40, v240, s[98:99]
	v_cndmask_b32_e64 v241, v41, v241, s[98:99]
	v_cndmask_b32_e64 v242, v42, v242, s[98:99]
	v_cndmask_b32_e64 v243, v43, v243, s[98:99]
	global_store_dwordx4 v[228:229], v[236:239], off offset:512
	global_store_dwordx4 v[232:233], v[240:243], off offset:512
	v_cvt_pk_bf16_f32 v34, v36, v37
	v_cvt_pk_bf16_f32 v35, v38, v39
	v_cvt_pk_bf16_f32 v36, v40, v41
	s_waitcnt lgkmcnt(0)
	v_add_f32_e32 v32, v32, v33
	v_mov_b32_e32 v33, v32
	s_nop 1
	v_permlane32_swap_b32_e32 v33, v32
	v_cvt_pk_bf16_f32 v37, v42, v43
	global_store_dwordx4 v[58:59], v[34:37], off offset:256
	s_and_saveexec_b64 s[24:25], s[2:3]
	s_cbranch_execz .LBB0_857
	v_readlane_b32 s26, v254, 41
	s_waitcnt lgkmcnt(0)
	v_add_f32_e32 v34, v32, v33
	v_lshlrev_b64 v[32:33], 6, v[48:49]
	v_readlane_b32 s27, v254, 42
	s_lshl_b32 s6, s38, 2
	s_nop 0
	v_lshl_add_u64 v[32:33], s[26:27], 0, v[32:33]
	v_lshl_add_u64 v[32:33], s[22:23], 2, v[32:33]
	v_lshl_add_u64 v[32:33], v[32:33], 0, s[6:7]
	global_store_dword v[32:33], v34, off
; __device__ __forceinline__ unsigned cvt_pk_bf16(float lo, float hi) { const f32x2_t v = {lo, hi}; const bf16x2_t b = __builtin_convertvector(v, bf16x2_t); return __builtin_bit_cast(unsigned, b); }
;     __device__ __forceinline__ void operator()(const f32x4 (&acc)[2][2][4][2], const Unit& u, int wr, int wc, int fr, int fq, const PG8_LAS float*) const {
;     ...
;             for (int m = 0; m < 4; ++m) { const int row = row0 + ai * HALF + m * 16; const size_t off = (size_t)row * ldc + col0; float ss = 0.f;
; #pragma unroll
;                 for (int bj = 0; bj < 2; ++bj) {
;                     const f32x4 b0 = *(const f32x4*)(base + off + bj * HALF), b1 = *(const f32x4*)(base + off + bj * HALF + 4);
;                     const f32x4 v0 = b0 + acc[ai][bj][m][0], v1 = b1 + acc[ai][bj][m][1];
;                     *(f32x4*)(out + off + bj * HALF) = v0; *(f32x4*)(out + off + bj * HALF + 4) = v1;
;                     if (xb) { u32x4 w; w.x = cvt_pk_bf16(v0[0], v0[1]); w.y = cvt_pk_bf16(v0[2], v0[3]); w.z = cvt_pk_bf16(v1[0], v1[1]); w.w = cvt_pk_bf16(v1[2], v1[3]);
;                         *(u32x4*)(xb + off + bj * HALF) = w;
;                         ss += ((v0[0] * v0[0] + v0[1] * v0[1]) + (v0[2] * v0[2] + v0[3] * v0[3])) + ((v1[0] * v1[0] + v1[1] * v1[1]) + (v1[2] * v1[2] + v1[3] * v1[3])); } }
;                 if (xb) { ss += __shfl_xor(ss, 16); ss += __shfl_xor(ss, 32); if (fq == 0) ssq[(size_t)row * 16 + u.pn * 4 + wc] = ss; } }
.LBB0_857:
	s_or_b64 exec, exec, s[24:25]
	v_add_u32_e32 v32, 0xa0, v146
	s_waitcnt lgkmcnt(0)
	v_ashrrev_i32_e32 v33, 31, v32
	v_lshlrev_b64 v[34:35], 10, v[32:33]
	v_lshl_add_u64 v[42:43], v[34:35], 0, v[144:145]
	v_lshl_add_u64 v[44:45], v[42:43], 2, s[68:69]
	global_load_dwordx4 v[34:37], v[44:45], off
	global_load_dwordx4 v[38:41], v[44:45], off offset:16
	v_readlane_b32 s24, v254, 39
	v_readlane_b32 s25, v254, 40
	s_waitcnt vmcnt(1)
	v_pk_add_f32 v[30:31], v[30:31], v[36:37]
	v_pk_add_f32 v[28:29], v[28:29], v[34:35]
	s_waitcnt vmcnt(0)
	v_pk_add_f32 v[26:27], v[26:27], v[40:41]
	v_pk_add_f32 v[24:25], v[24:25], v[38:39]
	v_lshl_add_u64 v[42:43], v[42:43], 1, s[24:25]
	v_cvt_pk_bf16_f32 v34, v28, v29
	v_cvt_pk_bf16_f32 v35, v30, v31
	v_cvt_pk_bf16_f32 v36, v24, v25
	v_cvt_pk_bf16_f32 v37, v26, v27
	v_lshl_add_u64 v[228:229], v[44:45], 0, v[230:231]
	v_lshl_add_u64 v[232:233], v[44:45], 0, v[244:245]
	s_nop 1
	v_mov_b32_dpp v236, v24 row_ror:8 row_mask:0xf bank_mask:0xf
	v_mov_b32_dpp v237, v25 row_ror:8 row_mask:0xf bank_mask:0xf
	v_mov_b32_dpp v238, v26 row_ror:8 row_mask:0xf bank_mask:0xf
	v_mov_b32_dpp v239, v27 row_ror:8 row_mask:0xf bank_mask:0xf
	v_mov_b32_dpp v240, v28 row_ror:8 row_mask:0xf bank_mask:0xf
	v_mov_b32_dpp v241, v29 row_ror:8 row_mask:0xf bank_mask:0xf
	v_mov_b32_dpp v242, v30 row_ror:8 row_mask:0xf bank_mask:0xf
	v_mov_b32_dpp v243, v31 row_ror:8 row_mask:0xf bank_mask:0xf
	s_nop 0
	v_cndmask_b32_e64 v236, v236, v28, s[98:99]
	v_cndmask_b32_e64 v237, v237, v29, s[98:99]
	v_cndmask_b32_e64 v238, v238, v30, s[98:99]
	v_cndmask_b32_e64 v239, v239, v31, s[98:99]
	v_cndmask_b32_e64 v240, v24, v240, s[98:99]
	v_cndmask_b32_e64 v241, v25, v241, s[98:99]
	v_cndmask_b32_e64 v242, v26, v242, s[98:99]
	v_cndmask_b32_e64 v243, v27, v243, s[98:99]
	global_store_dwordx4 v[228:229], v[236:239], off
	global_store_dwordx4 v[232:233], v[240:243], off
	global_store_dwordx4 v[42:43], v[34:37], off
	global_load_dwordx4 v[34:37], v[44:45], off offset:512
	s_nop 0
	global_load_dwordx4 v[38:41], v[44:45], off offset:528
	v_mul_f32_e32 v29, v29, v29
	v_mul_f32_e32 v31, v31, v31
	v_mul_f32_e32 v25, v25, v25
	v_mul_f32_e32 v27, v27, v27
	v_fmac_f32_e32 v29, v28, v28
	v_fmac_f32_e32 v31, v30, v30
	v_fmac_f32_e32 v25, v24, v24
	v_fmac_f32_e32 v27, v26, v26
	v_add_f32_e32 v24, v29, v31
	v_add_f32_e32 v25, v25, v27
	v_add_f32_e32 v28, v24, v25
	s_waitcnt vmcnt(1)
	v_pk_add_f32 v[22:23], v[22:23], v[36:37]
	v_pk_add_f32 v[20:21], v[20:21], v[34:35]
	s_waitcnt vmcnt(0)
	v_pk_add_f32 v[26:27], v[18:19], v[40:41]
	v_pk_add_f32 v[24:25], v[16:17], v[38:39]
	v_mul_f32_e32 v16, v21, v21
	v_mul_f32_e32 v17, v23, v23
	v_mul_f32_e32 v18, v25, v25
	v_mul_f32_e32 v19, v27, v27
	v_fmac_f32_e32 v16, v20, v20
	v_fmac_f32_e32 v17, v22, v22
	v_fmac_f32_e32 v18, v24, v24
	v_fmac_f32_e32 v19, v26, v26
	v_add_f32_e32 v16, v16, v17
	v_add_f32_e32 v17, v18, v19
	v_add_f32_e32 v16, v16, v17
	v_add_f32_e32 v16, v28, v16
	v_mov_b32_e32 v17, v16
	s_nop 1
	v_permlane16_swap_b32_e32 v17, v16
	v_lshl_add_u64 v[228:229], v[44:45], 0, v[230:231]
	v_lshl_add_u64 v[232:233], v[44:45], 0, v[244:245]
	s_nop 1
	v_mov_b32_dpp v236, v24 row_ror:8 row_mask:0xf bank_mask:0xf
	v_mov_b32_dpp v237, v25 row_ror:8 row_mask:0xf bank_mask:0xf
	v_mov_b32_dpp v238, v26 row_ror:8 row_mask:0xf bank_mask:0xf
	v_mov_b32_dpp v239, v27 row_ror:8 row_mask:0xf bank_mask:0xf
	v_mov_b32_dpp v240, v20 row_ror:8 row_mask:0xf bank_mask:0xf
	v_mov_b32_dpp v241, v21 row_ror:8 row_mask:0xf bank_mask:0xf
	v_mov_b32_dpp v242, v22 row_ror:8 row_mask:0xf bank_mask:0xf
	v_mov_b32_dpp v243, v23 row_ror:8 row_mask:0xf bank_mask:0xf
	s_nop 0
	v_cndmask_b32_e64 v236, v236, v20, s[98:99]
	v_cndmask_b32_e64 v237, v237, v21, s[98:99]
	v_cndmask_b32_e64 v238, v238, v22, s[98:99]
	v_cndmask_b32_e64 v239, v239, v23, s[98:99]
	v_cndmask_b32_e64 v240, v24, v240, s[98:99]
	v_cndmask_b32_e64 v241, v25, v241, s[98:99]
	v_cndmask_b32_e64 v242, v26, v242, s[98:99]
	v_cndmask_b32_e64 v243, v27, v243, s[98:99]
	global_store_dwordx4 v[228:229], v[236:239], off offset:512
	global_store_dwordx4 v[232:233], v[240:243], off offset:512
	v_cvt_pk_bf16_f32 v18, v20, v21
	v_cvt_pk_bf16_f32 v19, v22, v23
	v_cvt_pk_bf16_f32 v20, v24, v25
	s_waitcnt lgkmcnt(0)
	v_add_f32_e32 v16, v16, v17
	v_mov_b32_e32 v17, v16
	s_nop 1
	v_permlane32_swap_b32_e32 v17, v16
	v_cvt_pk_bf16_f32 v21, v26, v27
	global_store_dwordx4 v[42:43], v[18:21], off offset:256
	s_and_saveexec_b64 s[24:25], s[2:3]
	s_cbranch_execz .LBB0_859
	v_readlane_b32 s26, v254, 41
	s_waitcnt lgkmcnt(0)
	v_add_f32_e32 v18, v16, v17
	v_lshlrev_b64 v[16:17], 6, v[32:33]
	v_readlane_b32 s27, v254, 42
	s_lshl_b32 s6, s38, 2
	s_nop 0
	v_lshl_add_u64 v[16:17], s[26:27], 0, v[16:17]
	v_lshl_add_u64 v[16:17], s[22:23], 2, v[16:17]
	v_lshl_add_u64 v[16:17], v[16:17], 0, s[6:7]
	global_store_dword v[16:17], v18, off
; __device__ __forceinline__ unsigned cvt_pk_bf16(float lo, float hi) { const f32x2_t v = {lo, hi}; const bf16x2_t b = __builtin_convertvector(v, bf16x2_t); return __builtin_bit_cast(unsigned, b); }
;     __device__ __forceinline__ void operator()(const f32x4 (&acc)[2][2][4][2], const Unit& u, int wr, int wc, int fr, int fq, const PG8_LAS float*) const {
;     ...
;             for (int m = 0; m < 4; ++m) { const int row = row0 + ai * HALF + m * 16; const size_t off = (size_t)row * ldc + col0; float ss = 0.f;
; #pragma unroll
;                 for (int bj = 0; bj < 2; ++bj) {
;                     const f32x4 b0 = *(const f32x4*)(base + off + bj * HALF), b1 = *(const f32x4*)(base + off + bj * HALF + 4);
;                     const f32x4 v0 = b0 + acc[ai][bj][m][0], v1 = b1 + acc[ai][bj][m][1];
;                     *(f32x4*)(out + off + bj * HALF) = v0; *(f32x4*)(out + off + bj * HALF + 4) = v1;
;                     if (xb) { u32x4 w; w.x = cvt_pk_bf16(v0[0], v0[1]); w.y = cvt_pk_bf16(v0[2], v0[3]); w.z = cvt_pk_bf16(v1[0], v1[1]); w.w = cvt_pk_bf16(v1[2], v1[3]);
;                         *(u32x4*)(xb + off + bj * HALF) = w;
;                         ss += ((v0[0] * v0[0] + v0[1] * v0[1]) + (v0[2] * v0[2] + v0[3] * v0[3])) + ((v1[0] * v1[0] + v1[1] * v1[1]) + (v1[2] * v1[2] + v1[3] * v1[3])); } }
;                 if (xb) { ss += __shfl_xor(ss, 16); ss += __shfl_xor(ss, 32); if (fq == 0) ssq[(size_t)row * 16 + u.pn * 4 + wc] = ss; } }
.LBB0_859:
	s_or_b64 exec, exec, s[24:25]
	v_add_u32_e32 v16, 0xb0, v146
	s_waitcnt lgkmcnt(0)
	v_ashrrev_i32_e32 v17, 31, v16
	v_lshlrev_b64 v[18:19], 10, v[16:17]
	v_lshl_add_u64 v[26:27], v[18:19], 0, v[144:145]
	v_lshl_add_u64 v[28:29], v[26:27], 2, s[68:69]
	global_load_dwordx4 v[18:21], v[28:29], off
	global_load_dwordx4 v[22:25], v[28:29], off offset:16
	v_readlane_b32 s24, v254, 39
	v_readlane_b32 s25, v254, 40
	s_waitcnt vmcnt(1)
	v_pk_add_f32 v[14:15], v[14:15], v[20:21]
	v_pk_add_f32 v[12:13], v[12:13], v[18:19]
	s_waitcnt vmcnt(0)
	v_pk_add_f32 v[10:11], v[10:11], v[24:25]
	v_pk_add_f32 v[8:9], v[8:9], v[22:23]
	v_lshl_add_u64 v[26:27], v[26:27], 1, s[24:25]
	v_cvt_pk_bf16_f32 v18, v12, v13
	v_cvt_pk_bf16_f32 v19, v14, v15
	v_cvt_pk_bf16_f32 v20, v8, v9
	v_cvt_pk_bf16_f32 v21, v10, v11
	v_lshl_add_u64 v[228:229], v[28:29], 0, v[230:231]
	v_lshl_add_u64 v[232:233], v[28:29], 0, v[244:245]
	s_nop 1
	v_mov_b32_dpp v236, v8 row_ror:8 row_mask:0xf bank_mask:0xf
	v_mov_b32_dpp v237, v9 row_ror:8 row_mask:0xf bank_mask:0xf
	v_mov_b32_dpp v238, v10 row_ror:8 row_mask:0xf bank_mask:0xf
	v_mov_b32_dpp v239, v11 row_ror:8 row_mask:0xf bank_mask:0xf
	v_mov_b32_dpp v240, v12 row_ror:8 row_mask:0xf bank_mask:0xf
	v_mov_b32_dpp v241, v13 row_ror:8 row_mask:0xf bank_mask:0xf
	v_mov_b32_dpp v242, v14 row_ror:8 row_mask:0xf bank_mask:0xf
	v_mov_b32_dpp v243, v15 row_ror:8 row_mask:0xf bank_mask:0xf
	s_nop 0
	v_cndmask_b32_e64 v236, v236, v12, s[98:99]
	v_cndmask_b32_e64 v237, v237, v13, s[98:99]
	v_cndmask_b32_e64 v238, v238, v14, s[98:99]
	v_cndmask_b32_e64 v239, v239, v15, s[98:99]
	v_cndmask_b32_e64 v240, v8, v240, s[98:99]
	v_cndmask_b32_e64 v241, v9, v241, s[98:99]
	v_cndmask_b32_e64 v242, v10, v242, s[98:99]
	v_cndmask_b32_e64 v243, v11, v243, s[98:99]
	global_store_dwordx4 v[228:229], v[236:239], off
	global_store_dwordx4 v[232:233], v[240:243], off
	global_store_dwordx4 v[26:27], v[18:21], off
	global_load_dwordx4 v[18:21], v[28:29], off offset:512
	s_nop 0
	global_load_dwordx4 v[22:25], v[28:29], off offset:528
	v_mul_f32_e32 v13, v13, v13
	v_mul_f32_e32 v15, v15, v15
	v_mul_f32_e32 v9, v9, v9
	v_mul_f32_e32 v11, v11, v11
	v_fmac_f32_e32 v13, v12, v12
	v_fmac_f32_e32 v15, v14, v14
	v_fmac_f32_e32 v9, v8, v8
	v_fmac_f32_e32 v11, v10, v10
	v_add_f32_e32 v8, v13, v15
	v_add_f32_e32 v9, v9, v11
	v_add_f32_e32 v12, v8, v9
	s_waitcnt vmcnt(1)
	v_pk_add_f32 v[6:7], v[6:7], v[20:21]
	v_pk_add_f32 v[4:5], v[4:5], v[18:19]
	s_waitcnt vmcnt(0)
	v_pk_add_f32 v[10:11], v[2:3], v[24:25]
	v_pk_add_f32 v[8:9], v[0:1], v[22:23]
	v_mul_f32_e32 v0, v5, v5
	v_mul_f32_e32 v1, v7, v7
	v_mul_f32_e32 v2, v9, v9
	v_mul_f32_e32 v3, v11, v11
	v_fmac_f32_e32 v0, v4, v4
	v_fmac_f32_e32 v1, v6, v6
	v_fmac_f32_e32 v2, v8, v8
	v_fmac_f32_e32 v3, v10, v10
	v_add_f32_e32 v0, v0, v1
	v_add_f32_e32 v1, v2, v3
	v_add_f32_e32 v0, v0, v1
	v_add_f32_e32 v0, v12, v0
	v_mov_b32_e32 v1, v0
	s_nop 1
	v_permlane16_swap_b32_e32 v1, v0
	v_lshl_add_u64 v[228:229], v[28:29], 0, v[230:231]
	v_lshl_add_u64 v[232:233], v[28:29], 0, v[244:245]
	s_nop 1
	v_mov_b32_dpp v236, v8 row_ror:8 row_mask:0xf bank_mask:0xf
	v_mov_b32_dpp v237, v9 row_ror:8 row_mask:0xf bank_mask:0xf
	v_mov_b32_dpp v238, v10 row_ror:8 row_mask:0xf bank_mask:0xf
	v_mov_b32_dpp v239, v11 row_ror:8 row_mask:0xf bank_mask:0xf
	v_mov_b32_dpp v240, v4 row_ror:8 row_mask:0xf bank_mask:0xf
	v_mov_b32_dpp v241, v5 row_ror:8 row_mask:0xf bank_mask:0xf
	v_mov_b32_dpp v242, v6 row_ror:8 row_mask:0xf bank_mask:0xf
	v_mov_b32_dpp v243, v7 row_ror:8 row_mask:0xf bank_mask:0xf
	s_nop 0
	v_cndmask_b32_e64 v236, v236, v4, s[98:99]
	v_cndmask_b32_e64 v237, v237, v5, s[98:99]
	v_cndmask_b32_e64 v238, v238, v6, s[98:99]
	v_cndmask_b32_e64 v239, v239, v7, s[98:99]
	v_cndmask_b32_e64 v240, v8, v240, s[98:99]
	v_cndmask_b32_e64 v241, v9, v241, s[98:99]
	v_cndmask_b32_e64 v242, v10, v242, s[98:99]
	v_cndmask_b32_e64 v243, v11, v243, s[98:99]
	global_store_dwordx4 v[228:229], v[236:239], off offset:512
	global_store_dwordx4 v[232:233], v[240:243], off offset:512
	v_cvt_pk_bf16_f32 v2, v4, v5
	v_cvt_pk_bf16_f32 v3, v6, v7
	v_cvt_pk_bf16_f32 v4, v8, v9
	s_waitcnt lgkmcnt(0)
	v_add_f32_e32 v0, v0, v1
	v_mov_b32_e32 v1, v0
	s_nop 1
	v_permlane32_swap_b32_e32 v1, v0
	v_cvt_pk_bf16_f32 v5, v10, v11
	global_store_dwordx4 v[26:27], v[2:5], off offset:256
	s_and_saveexec_b64 s[24:25], s[2:3]
	s_cbranch_execz .LBB0_861
	v_readlane_b32 s26, v254, 41
	s_waitcnt lgkmcnt(0)
	v_add_f32_e32 v2, v0, v1
	v_lshlrev_b64 v[0:1], 6, v[16:17]
	v_readlane_b32 s27, v254, 42
	s_lshl_b32 s6, s38, 2
	s_nop 0
	v_lshl_add_u64 v[0:1], s[26:27], 0, v[0:1]
	v_lshl_add_u64 v[0:1], s[22:23], 2, v[0:1]
	v_lshl_add_u64 v[0:1], v[0:1], 0, s[6:7]
	global_store_dword v[0:1], v2, off

; #define PG8_STAGE(bufoff, gbase, voff) do { _Pragma("unroll") for (int _i = 0; _i < 2; ++_i) \
;         __builtin_amdgcn_global_load_lds((const unsigned*)((const char*)(gbase) + (voff)[_i]), (PG8_LAS unsigned*)(lds + (bufoff) + ldsw + _i * 8192), 16, 0, 0); } while (0)
; #define PG8_LDA(dst, b, h) do { _Pragma("unroll") for (int m = 0; m < 4; ++m) _Pragma("unroll") for (int k = 0; k < 2; ++k) dst[m][k] = *(const PG8_LAS bf16x8*)(lds + PG8_SA(b, h) + aoff + m * 2048 + k * 1024); } while (0)
; #define PG8_LDB(dst, b, h) do { _Pragma("unroll") for (int n = 0; n < 2; ++n) _Pragma("unroll") for (int k = 0; k < 2; ++k) dst[n][k] = *(const PG8_LAS bf16x8*)(lds + PG8_SB(b, h) + boff + n * 2048 + k * 1024); } while (0)
; #define PG8_MMA(ai, bj, At, Bt) do { __builtin_amdgcn_s_setprio(1); _Pragma("unroll") for (int m = 0; m < 4; ++m) _Pragma("unroll") for (int n = 0; n < 2; ++n) _Pragma("unroll") for (int k = 0; k < 2; ++k) \
;         acc[ai][bj][m][n] = __builtin_amdgcn_mfma_f32_16x16x32_bf16(Bt[n][k], At[m][k], acc[ai][bj][m][n], 0, 0, 0); __builtin_amdgcn_s_setprio(0); } while (0)
; #define PG8_WAIT_V(n) asm volatile("s_waitcnt vmcnt(" #n ")" ::: "memory")
; #define PG8_WAIT_L(n) asm volatile("s_waitcnt lgkmcnt(" #n ")" ::: "memory")
; template <class Epi, class Sched, bool ALIGN_EPI = false, bool SP2 = false>
; __device__ __forceinline__ void gemm_phase(PG8_LAS unsigned char* lds, const Gemm g, const Sched& S, const Epi& E) {
;     ...
;             const bool last = (t == nt - 2);
;             const char* a1 = cA + (size_t)(t + 1) * kstep;
;             const char* a2 = last ? nA : cA + (size_t)(t + 2) * kstep; const char* b2 = last ? nB : cB + (size_t)(t + 2) * kstep;
;             const char* a3 = a2 + kstep; const char* b3 = b2 + kstep;
;             if (last && has_next) S.a_ready(nxt);
;             if constexpr (SP2) {
;             PG8_LDB(B0, 0, 0); PG8_LDB(B1, 0, 1); PG8_SCHED; PG8_LDA(At, 0, 0); PG8_STAGE(PG8_SA(1, 1), a1 + hstep, voffA);
;             PG8_WAIT_V(8); PG8_WAIT_L(0); PG8_BAR; PG8_MMA(0, 0, At, B0); PG8_MMA(0, 1, At, B1); PG8_BAR; PG8_SCHED;
;             PG8_LDA(At, 0, 1); PG8_STAGE(PG8_SB(0, 0), b2, voffB); PG8_STAGE(PG8_SB(0, 1), b2 + hstep, voffB); PG8_STAGE(PG8_SA(0, 0), a2, voffA);
;             PG8_WAIT_V(8); PG8_WAIT_L(0); PG8_BAR; PG8_MMA(1, 0, At, B0); PG8_MMA(1, 1, At, B1); PG8_BAR; PG8_SCHED;
.LBB0_931:
	ds_read_b128 v[128:131], v171
	ds_read_b128 v[132:135], v171 offset:1024
	ds_read_b128 v[136:139], v171 offset:2048
	ds_read_b128 v[140:143], v171 offset:3072
	ds_read_b128 v[160:163], v172
	ds_read_b128 v[176:179], v172 offset:1024
	ds_read_b128 v[180:183], v172 offset:2048
	ds_read_b128 v[184:187], v172 offset:3072
	s_add_u32 s28, s26, 0xfffc0080
	s_addc_u32 s29, s27, -1
	s_cmp_eq_u32 s54, 12
	s_cselect_b32 s31, s17, s29
	s_cselect_b32 s30, s50, s28
	s_cselect_b32 s29, s15, s53
	s_cselect_b32 s28, s51, s52
	s_add_i32 m0, s25, 0xc000
	ds_read_b128 v[188:191], v173
	ds_read_b128 v[192:195], v173 offset:1024
	ds_read_b128 v[196:199], v173 offset:2048
	ds_read_b128 v[200:203], v173 offset:3072
	ds_read_b128 v[204:207], v173 offset:4096
	ds_read_b128 v[208:211], v173 offset:5120
	ds_read_b128 v[212:215], v173 offset:6144
	ds_read_b128 v[216:219], v173 offset:7168
	global_load_lds_dwordx4 v152, s[26:27]
	s_add_i32 m0, s25, 0xe000
	s_nop 0
	global_load_lds_dwordx4 v154, s[26:27]
	s_waitcnt vmcnt(8)
	s_waitcnt lgkmcnt(0)
	s_barrier
	s_setprio 1
	s_waitcnt lgkmcnt(0)
	v_mfma_f32_16x16x32_bf16 v[124:127], v[128:131], v[188:191], v[124:127]
	v_mfma_f32_16x16x32_bf16 v[120:123], v[136:139], v[188:191], v[120:123]
	v_mfma_f32_16x16x32_bf16 v[116:119], v[128:131], v[196:199], v[116:119]
	v_mfma_f32_16x16x32_bf16 v[108:111], v[136:139], v[196:199], v[108:111]
	v_mfma_f32_16x16x32_bf16 v[96:99], v[128:131], v[204:207], v[96:99]
	v_mfma_f32_16x16x32_bf16 v[88:91], v[136:139], v[204:207], v[88:91]
	v_mfma_f32_16x16x32_bf16 v[84:87], v[128:131], v[212:215], v[84:87]
	v_mfma_f32_16x16x32_bf16 v[76:79], v[136:139], v[212:215], v[76:79]
	v_mfma_f32_16x16x32_bf16 v[124:127], v[132:135], v[192:195], v[124:127]
	v_mfma_f32_16x16x32_bf16 v[120:123], v[140:143], v[192:195], v[120:123]
	v_mfma_f32_16x16x32_bf16 v[116:119], v[132:135], v[200:203], v[116:119]
	v_mfma_f32_16x16x32_bf16 v[108:111], v[140:143], v[200:203], v[108:111]
	v_mfma_f32_16x16x32_bf16 v[96:99], v[132:135], v[208:211], v[96:99]
	v_mfma_f32_16x16x32_bf16 v[88:91], v[140:143], v[208:211], v[88:91]
	v_mfma_f32_16x16x32_bf16 v[84:87], v[132:135], v[216:219], v[84:87]
	v_mfma_f32_16x16x32_bf16 v[76:79], v[140:143], v[216:219], v[76:79]
	s_setprio 0
	s_setprio 1
	v_mfma_f32_16x16x32_bf16 v[112:115], v[160:163], v[188:191], v[112:115]
	v_mfma_f32_16x16x32_bf16 v[104:107], v[180:183], v[188:191], v[104:107]
	v_mfma_f32_16x16x32_bf16 v[100:103], v[160:163], v[196:199], v[100:103]
	v_mfma_f32_16x16x32_bf16 v[92:95], v[180:183], v[196:199], v[92:95]
	v_mfma_f32_16x16x32_bf16 v[80:83], v[160:163], v[204:207], v[80:83]
	v_mfma_f32_16x16x32_bf16 v[72:75], v[180:183], v[204:207], v[72:75]
	v_mfma_f32_16x16x32_bf16 v[68:71], v[160:163], v[212:215], v[68:71]
	v_mfma_f32_16x16x32_bf16 v[64:67], v[180:183], v[212:215], v[64:67]
	v_mfma_f32_16x16x32_bf16 v[112:115], v[176:179], v[192:195], v[112:115]
	v_mfma_f32_16x16x32_bf16 v[104:107], v[184:187], v[192:195], v[104:107]
	v_mfma_f32_16x16x32_bf16 v[100:103], v[176:179], v[200:203], v[100:103]
	v_mfma_f32_16x16x32_bf16 v[92:95], v[184:187], v[200:203], v[92:95]
	v_mfma_f32_16x16x32_bf16 v[80:83], v[176:179], v[208:211], v[80:83]
	v_mfma_f32_16x16x32_bf16 v[72:75], v[184:187], v[208:211], v[72:75]
	v_mfma_f32_16x16x32_bf16 v[68:71], v[176:179], v[216:219], v[68:71]
	v_mfma_f32_16x16x32_bf16 v[64:67], v[184:187], v[216:219], v[64:67]
	s_setprio 0
	s_barrier
	s_add_i32 s55, s44, s22
	s_mov_b32 m0, s55
	ds_read_b128 v[188:191], v173 offset:16384
	ds_read_b128 v[192:195], v173 offset:17408
	ds_read_b128 v[196:199], v173 offset:18432
	ds_read_b128 v[200:203], v173 offset:19456
	ds_read_b128 v[204:207], v173 offset:20480
	ds_read_b128 v[208:211], v173 offset:21504
	ds_read_b128 v[212:215], v173 offset:22528
	ds_read_b128 v[216:219], v173 offset:23552
	global_load_lds_dwordx4 v146, s[28:29]
	s_add_i32 m0, s55, 0x2000
	s_add_u32 s56, s28, 0x40000
	s_addc_u32 s57, s29, 0
	s_add_i32 s55, s45, s22
	global_load_lds_dwordx4 v150, s[28:29]
	s_mov_b32 m0, s55
	s_nop 0
	global_load_lds_dwordx4 v146, s[56:57]
	s_add_i32 m0, s55, 0x2000
	s_nop 0
	global_load_lds_dwordx4 v150, s[56:57]
	s_mov_b32 m0, s25
	s_nop 0
	global_load_lds_dwordx4 v144, s[30:31]
	s_mov_b32 m0, s36
	s_nop 0
	global_load_lds_dwordx4 v148, s[30:31]
	s_waitcnt vmcnt(8)
	s_waitcnt lgkmcnt(0)
	s_barrier
	s_setprio 1
	s_waitcnt lgkmcnt(0)
	v_mfma_f32_16x16x32_bf16 v[60:63], v[128:131], v[188:191], v[60:63]
	v_mfma_f32_16x16x32_bf16 v[56:59], v[136:139], v[188:191], v[56:59]
	v_mfma_f32_16x16x32_bf16 v[52:55], v[128:131], v[196:199], v[52:55]
	v_mfma_f32_16x16x32_bf16 v[44:47], v[136:139], v[196:199], v[44:47]
	v_mfma_f32_16x16x32_bf16 v[32:35], v[128:131], v[204:207], v[32:35]
	v_mfma_f32_16x16x32_bf16 v[24:27], v[136:139], v[204:207], v[24:27]
	v_mfma_f32_16x16x32_bf16 v[20:23], v[128:131], v[212:215], v[20:23]
	v_mfma_f32_16x16x32_bf16 v[12:15], v[136:139], v[212:215], v[12:15]
	v_mfma_f32_16x16x32_bf16 v[60:63], v[132:135], v[192:195], v[60:63]
	v_mfma_f32_16x16x32_bf16 v[56:59], v[140:143], v[192:195], v[56:59]
	v_mfma_f32_16x16x32_bf16 v[52:55], v[132:135], v[200:203], v[52:55]
	v_mfma_f32_16x16x32_bf16 v[44:47], v[140:143], v[200:203], v[44:47]
	v_mfma_f32_16x16x32_bf16 v[32:35], v[132:135], v[208:211], v[32:35]
	v_mfma_f32_16x16x32_bf16 v[24:27], v[140:143], v[208:211], v[24:27]
	v_mfma_f32_16x16x32_bf16 v[20:23], v[132:135], v[216:219], v[20:23]
	v_mfma_f32_16x16x32_bf16 v[12:15], v[140:143], v[216:219], v[12:15]
	s_setprio 0
	s_setprio 1
	v_mfma_f32_16x16x32_bf16 v[48:51], v[160:163], v[188:191], v[48:51]
	v_mfma_f32_16x16x32_bf16 v[40:43], v[180:183], v[188:191], v[40:43]
	v_mfma_f32_16x16x32_bf16 v[36:39], v[160:163], v[196:199], v[36:39]
	v_mfma_f32_16x16x32_bf16 v[28:31], v[180:183], v[196:199], v[28:31]
	v_mfma_f32_16x16x32_bf16 v[16:19], v[160:163], v[204:207], v[16:19]
	v_mfma_f32_16x16x32_bf16 v[8:11], v[180:183], v[204:207], v[8:11]
	v_mfma_f32_16x16x32_bf16 v[4:7], v[160:163], v[212:215], v[4:7]
	v_mfma_f32_16x16x32_bf16 v[0:3], v[180:183], v[212:215], v[0:3]
	v_mfma_f32_16x16x32_bf16 v[48:51], v[176:179], v[192:195], v[48:51]
	v_mfma_f32_16x16x32_bf16 v[40:43], v[184:187], v[192:195], v[40:43]
	v_mfma_f32_16x16x32_bf16 v[36:39], v[176:179], v[200:203], v[36:39]
	v_mfma_f32_16x16x32_bf16 v[28:31], v[184:187], v[200:203], v[28:31]
	v_mfma_f32_16x16x32_bf16 v[16:19], v[176:179], v[208:211], v[16:19]
	v_mfma_f32_16x16x32_bf16 v[8:11], v[184:187], v[208:211], v[8:11]
	v_mfma_f32_16x16x32_bf16 v[4:7], v[176:179], v[216:219], v[4:7]
	v_mfma_f32_16x16x32_bf16 v[0:3], v[184:187], v[216:219], v[0:3]
	s_setprio 0
	s_barrier
; #define PG8_STAGE(bufoff, gbase, voff) do { _Pragma("unroll") for (int _i = 0; _i < 2; ++_i) \
;         __builtin_amdgcn_global_load_lds((const unsigned*)((const char*)(gbase) + (voff)[_i]), (PG8_LAS unsigned*)(lds + (bufoff) + ldsw + _i * 8192), 16, 0, 0); } while (0)
; #define PG8_LDA(dst, b, h) do { _Pragma("unroll") for (int m = 0; m < 4; ++m) _Pragma("unroll") for (int k = 0; k < 2; ++k) dst[m][k] = *(const PG8_LAS bf16x8*)(lds + PG8_SA(b, h) + aoff + m * 2048 + k * 1024); } while (0)
; #define PG8_LDB(dst, b, h) do { _Pragma("unroll") for (int n = 0; n < 2; ++n) _Pragma("unroll") for (int k = 0; k < 2; ++k) dst[n][k] = *(const PG8_LAS bf16x8*)(lds + PG8_SB(b, h) + boff + n * 2048 + k * 1024); } while (0)
; #define PG8_MMA(ai, bj, At, Bt) do { __builtin_amdgcn_s_setprio(1); _Pragma("unroll") for (int m = 0; m < 4; ++m) _Pragma("unroll") for (int n = 0; n < 2; ++n) _Pragma("unroll") for (int k = 0; k < 2; ++k) \
;         acc[ai][bj][m][n] = __builtin_amdgcn_mfma_f32_16x16x32_bf16(Bt[n][k], At[m][k], acc[ai][bj][m][n], 0, 0, 0); __builtin_amdgcn_s_setprio(0); } while (0)
; #define PG8_WAIT_V(n) asm volatile("s_waitcnt vmcnt(" #n ")" ::: "memory")
; #define PG8_WAIT_L(n) asm volatile("s_waitcnt lgkmcnt(" #n ")" ::: "memory")
; #define PG8_BAR __builtin_amdgcn_s_barrier()
; #define PG8_SCHED __builtin_amdgcn_sched_barrier(0)
; template <class Epi, class Sched, bool ALIGN_EPI = false, bool SP2 = false>
; __device__ __forceinline__ void gemm_phase(PG8_LAS unsigned char* lds, const Gemm g, const Sched& S, const Epi& E) {
;     ...
;         for (int t = 0; t < nt; t += 2) {
;     ...
;             PG8_LDB(B0, 1, 0); PG8_LDB(B1, 1, 1); PG8_SCHED; PG8_LDA(At, 1, 0); PG8_STAGE(PG8_SA(0, 1), a2 + hstep, voffA);
;             PG8_WAIT_V(8); PG8_WAIT_L(0); PG8_BAR; PG8_MMA(0, 0, At, B0); PG8_MMA(0, 1, At, B1); PG8_BAR; PG8_SCHED;
;             PG8_LDA(At, 1, 1); PG8_STAGE(PG8_SB(1, 0), b3, voffB); PG8_STAGE(PG8_SB(1, 1), b3 + hstep, voffB); PG8_STAGE(PG8_SA(1, 0), a3, voffA);
;             PG8_WAIT_V(8); PG8_WAIT_L(0); PG8_BAR; PG8_MMA(1, 0, At, B0); PG8_MMA(1, 1, At, B1); PG8_BAR; PG8_SCHED;
	s_add_i32 s55, 0, 0x18000
	s_add_i32 s56, 0, 0x1c000
	v_add_u32_e32 v140, s55, v167
	v_add_u32_e32 v175, s56, v167
	ds_read_b128 v[128:131], v140
	ds_read_b128 v[132:135], v140 offset:1024
	ds_read_b128 v[136:139], v140 offset:2048
	ds_read_b128 v[140:143], v140 offset:3072
	ds_read_b128 v[160:163], v175
	ds_read_b128 v[176:179], v175 offset:1024
	ds_read_b128 v[180:183], v175 offset:2048
	ds_read_b128 v[184:187], v175 offset:3072
	s_add_u32 s30, s30, 0x40000
	s_addc_u32 s31, s31, 0
	s_mov_b32 m0, s37
	ds_read_b128 v[188:191], v173 offset:32768
	ds_read_b128 v[192:195], v173 offset:33792
	ds_read_b128 v[196:199], v173 offset:34816
	ds_read_b128 v[200:203], v173 offset:35840
	ds_read_b128 v[204:207], v173 offset:36864
	ds_read_b128 v[208:211], v173 offset:37888
	ds_read_b128 v[212:215], v173 offset:38912
	ds_read_b128 v[216:219], v173 offset:39936
	global_load_lds_dwordx4 v144, s[30:31]
	s_mov_b32 m0, s38
	s_nop 0
	global_load_lds_dwordx4 v148, s[30:31]
	s_waitcnt vmcnt(8)
	s_waitcnt lgkmcnt(0)
	s_barrier
	s_setprio 1
	s_waitcnt lgkmcnt(0)
	v_mfma_f32_16x16x32_bf16 v[124:127], v[128:131], v[188:191], v[124:127]
	v_mfma_f32_16x16x32_bf16 v[120:123], v[136:139], v[188:191], v[120:123]
	v_mfma_f32_16x16x32_bf16 v[116:119], v[128:131], v[196:199], v[116:119]
	v_mfma_f32_16x16x32_bf16 v[108:111], v[136:139], v[196:199], v[108:111]
	v_mfma_f32_16x16x32_bf16 v[96:99], v[128:131], v[204:207], v[96:99]
	v_mfma_f32_16x16x32_bf16 v[88:91], v[136:139], v[204:207], v[88:91]
	v_mfma_f32_16x16x32_bf16 v[84:87], v[128:131], v[212:215], v[84:87]
	v_mfma_f32_16x16x32_bf16 v[76:79], v[136:139], v[212:215], v[76:79]
	v_mfma_f32_16x16x32_bf16 v[124:127], v[132:135], v[192:195], v[124:127]
	v_mfma_f32_16x16x32_bf16 v[120:123], v[140:143], v[192:195], v[120:123]
	v_mfma_f32_16x16x32_bf16 v[116:119], v[132:135], v[200:203], v[116:119]
	v_mfma_f32_16x16x32_bf16 v[108:111], v[140:143], v[200:203], v[108:111]
	v_mfma_f32_16x16x32_bf16 v[96:99], v[132:135], v[208:211], v[96:99]
	v_mfma_f32_16x16x32_bf16 v[88:91], v[140:143], v[208:211], v[88:91]
	v_mfma_f32_16x16x32_bf16 v[84:87], v[132:135], v[216:219], v[84:87]
	v_mfma_f32_16x16x32_bf16 v[76:79], v[140:143], v[216:219], v[76:79]
	s_setprio 0
	s_setprio 1
	v_mfma_f32_16x16x32_bf16 v[112:115], v[160:163], v[188:191], v[112:115]
	v_mfma_f32_16x16x32_bf16 v[104:107], v[180:183], v[188:191], v[104:107]
	v_mfma_f32_16x16x32_bf16 v[100:103], v[160:163], v[196:199], v[100:103]
	v_mfma_f32_16x16x32_bf16 v[92:95], v[180:183], v[196:199], v[92:95]
	v_mfma_f32_16x16x32_bf16 v[80:83], v[160:163], v[204:207], v[80:83]
	v_mfma_f32_16x16x32_bf16 v[72:75], v[180:183], v[204:207], v[72:75]
	v_mfma_f32_16x16x32_bf16 v[68:71], v[160:163], v[212:215], v[68:71]
	v_mfma_f32_16x16x32_bf16 v[64:67], v[180:183], v[212:215], v[64:67]
	v_mfma_f32_16x16x32_bf16 v[112:115], v[176:179], v[192:195], v[112:115]
	v_mfma_f32_16x16x32_bf16 v[104:107], v[184:187], v[192:195], v[104:107]
	v_mfma_f32_16x16x32_bf16 v[100:103], v[176:179], v[200:203], v[100:103]
	v_mfma_f32_16x16x32_bf16 v[92:95], v[184:187], v[200:203], v[92:95]
	v_mfma_f32_16x16x32_bf16 v[80:83], v[176:179], v[208:211], v[80:83]
	v_mfma_f32_16x16x32_bf16 v[72:75], v[184:187], v[208:211], v[72:75]
	v_mfma_f32_16x16x32_bf16 v[68:71], v[176:179], v[216:219], v[68:71]
	v_mfma_f32_16x16x32_bf16 v[64:67], v[184:187], v[216:219], v[64:67]
	s_setprio 0
	s_barrier
	s_add_u32 s98, s30, 0xfffc0080
	s_addc_u32 s99, s31, -1
	s_add_u32 s100, s28, 0x80
	s_addc_u32 s101, s29, 0
	s_add_i32 s30, s55, s22
	s_mov_b32 m0, s30
	ds_read_b128 v[188:191], v173 offset:49152
	ds_read_b128 v[192:195], v173 offset:50176
	ds_read_b128 v[196:199], v173 offset:51200
	ds_read_b128 v[200:203], v173 offset:52224
	ds_read_b128 v[204:207], v173 offset:53248
	ds_read_b128 v[208:211], v173 offset:54272
	ds_read_b128 v[212:215], v173 offset:55296
	ds_read_b128 v[216:219], v173 offset:56320
	global_load_lds_dwordx4 v146, s[100:101]
	s_add_i32 m0, s30, 0x2000
	s_add_u32 s28, s28, 0x40080
	s_addc_u32 s29, s29, 0
	s_add_i32 s30, s56, s22
	global_load_lds_dwordx4 v150, s[100:101]
	s_mov_b32 m0, s30
	s_nop 0
	global_load_lds_dwordx4 v146, s[28:29]
	s_add_i32 m0, s30, 0x2000
	s_nop 0
	global_load_lds_dwordx4 v150, s[28:29]
	s_mov_b32 m0, s39
	s_nop 0
	global_load_lds_dwordx4 v144, s[98:99]
	s_mov_b32 m0, s40
	s_nop 0
	global_load_lds_dwordx4 v148, s[98:99]
	s_waitcnt vmcnt(8)
	s_waitcnt lgkmcnt(0)
	s_barrier
	s_setprio 1
	s_waitcnt lgkmcnt(0)
	v_mfma_f32_16x16x32_bf16 v[60:63], v[128:131], v[188:191], v[60:63]
	v_mfma_f32_16x16x32_bf16 v[56:59], v[136:139], v[188:191], v[56:59]
	v_mfma_f32_16x16x32_bf16 v[52:55], v[128:131], v[196:199], v[52:55]
	v_mfma_f32_16x16x32_bf16 v[44:47], v[136:139], v[196:199], v[44:47]
	v_mfma_f32_16x16x32_bf16 v[32:35], v[128:131], v[204:207], v[32:35]
	v_mfma_f32_16x16x32_bf16 v[24:27], v[136:139], v[204:207], v[24:27]
	v_mfma_f32_16x16x32_bf16 v[20:23], v[128:131], v[212:215], v[20:23]
	v_mfma_f32_16x16x32_bf16 v[12:15], v[136:139], v[212:215], v[12:15]
	v_mfma_f32_16x16x32_bf16 v[60:63], v[132:135], v[192:195], v[60:63]
	v_mfma_f32_16x16x32_bf16 v[56:59], v[140:143], v[192:195], v[56:59]
	v_mfma_f32_16x16x32_bf16 v[52:55], v[132:135], v[200:203], v[52:55]
	v_mfma_f32_16x16x32_bf16 v[44:47], v[140:143], v[200:203], v[44:47]
	v_mfma_f32_16x16x32_bf16 v[32:35], v[132:135], v[208:211], v[32:35]
	v_mfma_f32_16x16x32_bf16 v[24:27], v[140:143], v[208:211], v[24:27]
	v_mfma_f32_16x16x32_bf16 v[20:23], v[132:135], v[216:219], v[20:23]
	v_mfma_f32_16x16x32_bf16 v[12:15], v[140:143], v[216:219], v[12:15]
	s_setprio 0
	s_setprio 1
	v_mfma_f32_16x16x32_bf16 v[48:51], v[160:163], v[188:191], v[48:51]
	v_mfma_f32_16x16x32_bf16 v[40:43], v[180:183], v[188:191], v[40:43]
	v_mfma_f32_16x16x32_bf16 v[36:39], v[160:163], v[196:199], v[36:39]
	v_mfma_f32_16x16x32_bf16 v[28:31], v[180:183], v[196:199], v[28:31]
	v_mfma_f32_16x16x32_bf16 v[16:19], v[160:163], v[204:207], v[16:19]
	v_mfma_f32_16x16x32_bf16 v[8:11], v[180:183], v[204:207], v[8:11]
	v_mfma_f32_16x16x32_bf16 v[4:7], v[160:163], v[212:215], v[4:7]
	v_mfma_f32_16x16x32_bf16 v[0:3], v[180:183], v[212:215], v[0:3]
	v_mfma_f32_16x16x32_bf16 v[48:51], v[176:179], v[192:195], v[48:51]
	v_mfma_f32_16x16x32_bf16 v[40:43], v[184:187], v[192:195], v[40:43]
	v_mfma_f32_16x16x32_bf16 v[36:39], v[176:179], v[200:203], v[36:39]
	v_mfma_f32_16x16x32_bf16 v[28:31], v[184:187], v[200:203], v[28:31]
	v_mfma_f32_16x16x32_bf16 v[16:19], v[176:179], v[208:211], v[16:19]
	v_mfma_f32_16x16x32_bf16 v[8:11], v[184:187], v[208:211], v[8:11]
	v_mfma_f32_16x16x32_bf16 v[4:7], v[176:179], v[216:219], v[4:7]
	v_mfma_f32_16x16x32_bf16 v[0:3], v[184:187], v[216:219], v[0:3]
	s_setprio 0
	s_add_i32 s54, s54, 2
	s_add_u32 s26, s26, 0x100
	s_addc_u32 s27, s27, 0
	s_add_u32 s52, s52, 0x100
	s_addc_u32 s53, s53, 0
	s_cmp_gt_u32 s54, 13
	s_barrier
	s_cbranch_scc0 .LBB0_931
	s_and_b64 vcc, exec, s[12:13]
	s_cbranch_vccz .LBB0_934
	s_barrier

; #define PG8_STAGE(bufoff, gbase, voff) do { _Pragma("unroll") for (int _i = 0; _i < 2; ++_i) \
;         __builtin_amdgcn_global_load_lds((const unsigned*)((const char*)(gbase) + (voff)[_i]), (PG8_LAS unsigned*)(lds + (bufoff) + ldsw + _i * 8192), 16, 0, 0); } while (0)
; #define PG8_LDA(dst, b, h) do { _Pragma("unroll") for (int m = 0; m < 4; ++m) _Pragma("unroll") for (int k = 0; k < 2; ++k) dst[m][k] = *(const PG8_LAS bf16x8*)(lds + PG8_SA(b, h) + aoff + m * 2048 + k * 1024); } while (0)
; #define PG8_LDB(dst, b, h) do { _Pragma("unroll") for (int n = 0; n < 2; ++n) _Pragma("unroll") for (int k = 0; k < 2; ++k) dst[n][k] = *(const PG8_LAS bf16x8*)(lds + PG8_SB(b, h) + boff + n * 2048 + k * 1024); } while (0)
; #define PG8_MMA(ai, bj, At, Bt) do { __builtin_amdgcn_s_setprio(1); _Pragma("unroll") for (int m = 0; m < 4; ++m) _Pragma("unroll") for (int n = 0; n < 2; ++n) _Pragma("unroll") for (int k = 0; k < 2; ++k) \
;         acc[ai][bj][m][n] = __builtin_amdgcn_mfma_f32_16x16x32_bf16(Bt[n][k], At[m][k], acc[ai][bj][m][n], 0, 0, 0); __builtin_amdgcn_s_setprio(0); } while (0)
; #define PG8_WAIT_V(n) asm volatile("s_waitcnt vmcnt(" #n ")" ::: "memory")
; #define PG8_WAIT_L(n) asm volatile("s_waitcnt lgkmcnt(" #n ")" ::: "memory")
; template <class Epi, class Sched, bool ALIGN_EPI = false, bool SP2 = false>
; __device__ __forceinline__ void gemm_phase(PG8_LAS unsigned char* lds, const Gemm g, const Sched& S, const Epi& E) {
;     ...
;             const bool last = (t == nt - 2);
;             const char* a1 = cA + (size_t)(t + 1) * kstep;
;             const char* a2 = last ? nA : cA + (size_t)(t + 2) * kstep; const char* b2 = last ? nB : cB + (size_t)(t + 2) * kstep;
;             const char* a3 = a2 + kstep; const char* b3 = b2 + kstep;
;             if (last && has_next) S.a_ready(nxt);
;             if constexpr (SP2) {
;             PG8_LDB(B0, 0, 0); PG8_LDB(B1, 0, 1); PG8_SCHED; PG8_LDA(At, 0, 0); PG8_STAGE(PG8_SA(1, 1), a1 + hstep, voffA);
;             PG8_WAIT_V(8); PG8_WAIT_L(0); PG8_BAR; PG8_MMA(0, 0, At, B0); PG8_MMA(0, 1, At, B1); PG8_BAR; PG8_SCHED;
;             PG8_LDA(At, 0, 1); PG8_STAGE(PG8_SB(0, 0), b2, voffB); PG8_STAGE(PG8_SB(0, 1), b2 + hstep, voffB); PG8_STAGE(PG8_SA(0, 0), a2, voffA);
;             PG8_WAIT_V(8); PG8_WAIT_L(0); PG8_BAR; PG8_MMA(1, 0, At, B0); PG8_MMA(1, 1, At, B1); PG8_BAR; PG8_SCHED;
.LBB0_1556:
	ds_read_b128 v[128:131], v173
	ds_read_b128 v[132:135], v173 offset:1024
	ds_read_b128 v[136:139], v173 offset:2048
	ds_read_b128 v[140:143], v173 offset:3072
	ds_read_b128 v[160:163], v174
	ds_read_b128 v[178:181], v174 offset:1024
	ds_read_b128 v[182:185], v174 offset:2048
	ds_read_b128 v[186:189], v174 offset:3072
	s_add_u32 s38, s36, 0xfffc0080
	s_addc_u32 s39, s37, -1
	s_cmp_eq_u32 s64, 12
	s_cselect_b32 s41, s25, s39
	s_cselect_b32 s40, s60, s38
	s_cselect_b32 s39, s23, s63
	s_cselect_b32 s38, s61, s62
	s_add_i32 m0, s35, 0xc000
	ds_read_b128 v[190:193], v175
	ds_read_b128 v[194:197], v175 offset:1024
	ds_read_b128 v[198:201], v175 offset:2048
	ds_read_b128 v[202:205], v175 offset:3072
	ds_read_b128 v[206:209], v175 offset:4096
	ds_read_b128 v[210:213], v175 offset:5120
	ds_read_b128 v[214:217], v175 offset:6144
	ds_read_b128 v[218:221], v175 offset:7168
	global_load_lds_dwordx4 v152, s[36:37]
	s_add_i32 m0, s35, 0xe000
	s_nop 0
	global_load_lds_dwordx4 v154, s[36:37]
	s_waitcnt vmcnt(8)
	s_waitcnt lgkmcnt(0)
	s_barrier
	s_setprio 1
	s_waitcnt lgkmcnt(0)
	v_mfma_f32_16x16x32_bf16 v[124:127], v[128:131], v[190:193], v[124:127]
	v_mfma_f32_16x16x32_bf16 v[120:123], v[136:139], v[190:193], v[120:123]
	v_mfma_f32_16x16x32_bf16 v[108:111], v[128:131], v[198:201], v[108:111]
	v_mfma_f32_16x16x32_bf16 v[104:107], v[136:139], v[198:201], v[104:107]
	v_mfma_f32_16x16x32_bf16 v[92:95], v[128:131], v[206:209], v[92:95]
	v_mfma_f32_16x16x32_bf16 v[88:91], v[136:139], v[206:209], v[88:91]
	v_mfma_f32_16x16x32_bf16 v[76:79], v[128:131], v[214:217], v[76:79]
	v_mfma_f32_16x16x32_bf16 v[72:75], v[136:139], v[214:217], v[72:75]
	v_mfma_f32_16x16x32_bf16 v[124:127], v[132:135], v[194:197], v[124:127]
	v_mfma_f32_16x16x32_bf16 v[120:123], v[140:143], v[194:197], v[120:123]
	v_mfma_f32_16x16x32_bf16 v[108:111], v[132:135], v[202:205], v[108:111]
	v_mfma_f32_16x16x32_bf16 v[104:107], v[140:143], v[202:205], v[104:107]
	v_mfma_f32_16x16x32_bf16 v[92:95], v[132:135], v[210:213], v[92:95]
	v_mfma_f32_16x16x32_bf16 v[88:91], v[140:143], v[210:213], v[88:91]
	v_mfma_f32_16x16x32_bf16 v[76:79], v[132:135], v[218:221], v[76:79]
	v_mfma_f32_16x16x32_bf16 v[72:75], v[140:143], v[218:221], v[72:75]
	s_setprio 0
	s_setprio 1
	v_mfma_f32_16x16x32_bf16 v[116:119], v[160:163], v[190:193], v[116:119]
	v_mfma_f32_16x16x32_bf16 v[112:115], v[182:185], v[190:193], v[112:115]
	v_mfma_f32_16x16x32_bf16 v[100:103], v[160:163], v[198:201], v[100:103]
	v_mfma_f32_16x16x32_bf16 v[96:99], v[182:185], v[198:201], v[96:99]
	v_mfma_f32_16x16x32_bf16 v[84:87], v[160:163], v[206:209], v[84:87]
	v_mfma_f32_16x16x32_bf16 v[80:83], v[182:185], v[206:209], v[80:83]
	v_mfma_f32_16x16x32_bf16 v[68:71], v[160:163], v[214:217], v[68:71]
	v_mfma_f32_16x16x32_bf16 v[64:67], v[182:185], v[214:217], v[64:67]
	v_mfma_f32_16x16x32_bf16 v[116:119], v[178:181], v[194:197], v[116:119]
	v_mfma_f32_16x16x32_bf16 v[112:115], v[186:189], v[194:197], v[112:115]
	v_mfma_f32_16x16x32_bf16 v[100:103], v[178:181], v[202:205], v[100:103]
	v_mfma_f32_16x16x32_bf16 v[96:99], v[186:189], v[202:205], v[96:99]
	v_mfma_f32_16x16x32_bf16 v[84:87], v[178:181], v[210:213], v[84:87]
	v_mfma_f32_16x16x32_bf16 v[80:83], v[186:189], v[210:213], v[80:83]
	v_mfma_f32_16x16x32_bf16 v[68:71], v[178:181], v[218:221], v[68:71]
	v_mfma_f32_16x16x32_bf16 v[64:67], v[186:189], v[218:221], v[64:67]
	s_setprio 0
	s_barrier
	s_add_i32 s65, s51, s30
	s_mov_b32 m0, s65
	ds_read_b128 v[190:193], v175 offset:16384
	ds_read_b128 v[194:197], v175 offset:17408
	ds_read_b128 v[198:201], v175 offset:18432
	ds_read_b128 v[202:205], v175 offset:19456
	ds_read_b128 v[206:209], v175 offset:20480
	ds_read_b128 v[210:213], v175 offset:21504
	ds_read_b128 v[214:217], v175 offset:22528
	ds_read_b128 v[218:221], v175 offset:23552
	global_load_lds_dwordx4 v146, s[38:39]
	s_add_i32 m0, s65, 0x2000
	s_add_u32 s66, s38, 0x40000
	s_addc_u32 s67, s39, 0
	s_add_i32 s65, s52, s30
	global_load_lds_dwordx4 v150, s[38:39]
	s_mov_b32 m0, s65
	s_nop 0
	global_load_lds_dwordx4 v146, s[66:67]
	s_add_i32 m0, s65, 0x2000
	s_nop 0
	global_load_lds_dwordx4 v150, s[66:67]
	s_mov_b32 m0, s35
	s_nop 0
	global_load_lds_dwordx4 v144, s[40:41]
	s_mov_b32 m0, s44
	s_nop 0
	global_load_lds_dwordx4 v148, s[40:41]
	s_waitcnt vmcnt(8)
	s_waitcnt lgkmcnt(0)
	s_barrier
	s_setprio 1
	s_waitcnt lgkmcnt(0)
	v_mfma_f32_16x16x32_bf16 v[60:63], v[128:131], v[190:193], v[60:63]
	v_mfma_f32_16x16x32_bf16 v[56:59], v[136:139], v[190:193], v[56:59]
	v_mfma_f32_16x16x32_bf16 v[44:47], v[128:131], v[198:201], v[44:47]
	v_mfma_f32_16x16x32_bf16 v[40:43], v[136:139], v[198:201], v[40:43]
	v_mfma_f32_16x16x32_bf16 v[28:31], v[128:131], v[206:209], v[28:31]
	v_mfma_f32_16x16x32_bf16 v[24:27], v[136:139], v[206:209], v[24:27]
	v_mfma_f32_16x16x32_bf16 v[12:15], v[128:131], v[214:217], v[12:15]
	v_mfma_f32_16x16x32_bf16 v[8:11], v[136:139], v[214:217], v[8:11]
	v_mfma_f32_16x16x32_bf16 v[60:63], v[132:135], v[194:197], v[60:63]
	v_mfma_f32_16x16x32_bf16 v[56:59], v[140:143], v[194:197], v[56:59]
	v_mfma_f32_16x16x32_bf16 v[44:47], v[132:135], v[202:205], v[44:47]
	v_mfma_f32_16x16x32_bf16 v[40:43], v[140:143], v[202:205], v[40:43]
	v_mfma_f32_16x16x32_bf16 v[28:31], v[132:135], v[210:213], v[28:31]
	v_mfma_f32_16x16x32_bf16 v[24:27], v[140:143], v[210:213], v[24:27]
	v_mfma_f32_16x16x32_bf16 v[12:15], v[132:135], v[218:221], v[12:15]
	v_mfma_f32_16x16x32_bf16 v[8:11], v[140:143], v[218:221], v[8:11]
	s_setprio 0
	s_setprio 1
	v_mfma_f32_16x16x32_bf16 v[52:55], v[160:163], v[190:193], v[52:55]
	v_mfma_f32_16x16x32_bf16 v[48:51], v[182:185], v[190:193], v[48:51]
	v_mfma_f32_16x16x32_bf16 v[36:39], v[160:163], v[198:201], v[36:39]
	v_mfma_f32_16x16x32_bf16 v[32:35], v[182:185], v[198:201], v[32:35]
	v_mfma_f32_16x16x32_bf16 v[20:23], v[160:163], v[206:209], v[20:23]
	v_mfma_f32_16x16x32_bf16 v[16:19], v[182:185], v[206:209], v[16:19]
	v_mfma_f32_16x16x32_bf16 v[4:7], v[160:163], v[214:217], v[4:7]
	v_mfma_f32_16x16x32_bf16 v[0:3], v[182:185], v[214:217], v[0:3]
	v_mfma_f32_16x16x32_bf16 v[52:55], v[178:181], v[194:197], v[52:55]
	v_mfma_f32_16x16x32_bf16 v[48:51], v[186:189], v[194:197], v[48:51]
	v_mfma_f32_16x16x32_bf16 v[36:39], v[178:181], v[202:205], v[36:39]
	v_mfma_f32_16x16x32_bf16 v[32:35], v[186:189], v[202:205], v[32:35]
	v_mfma_f32_16x16x32_bf16 v[20:23], v[178:181], v[210:213], v[20:23]
	v_mfma_f32_16x16x32_bf16 v[16:19], v[186:189], v[210:213], v[16:19]
	v_mfma_f32_16x16x32_bf16 v[4:7], v[178:181], v[218:221], v[4:7]
	v_mfma_f32_16x16x32_bf16 v[0:3], v[186:189], v[218:221], v[0:3]
	s_setprio 0
	s_barrier
; #define PG8_STAGE(bufoff, gbase, voff) do { _Pragma("unroll") for (int _i = 0; _i < 2; ++_i) \
;         __builtin_amdgcn_global_load_lds((const unsigned*)((const char*)(gbase) + (voff)[_i]), (PG8_LAS unsigned*)(lds + (bufoff) + ldsw + _i * 8192), 16, 0, 0); } while (0)
; #define PG8_LDA(dst, b, h) do { _Pragma("unroll") for (int m = 0; m < 4; ++m) _Pragma("unroll") for (int k = 0; k < 2; ++k) dst[m][k] = *(const PG8_LAS bf16x8*)(lds + PG8_SA(b, h) + aoff + m * 2048 + k * 1024); } while (0)
; #define PG8_LDB(dst, b, h) do { _Pragma("unroll") for (int n = 0; n < 2; ++n) _Pragma("unroll") for (int k = 0; k < 2; ++k) dst[n][k] = *(const PG8_LAS bf16x8*)(lds + PG8_SB(b, h) + boff + n * 2048 + k * 1024); } while (0)
; #define PG8_MMA(ai, bj, At, Bt) do { __builtin_amdgcn_s_setprio(1); _Pragma("unroll") for (int m = 0; m < 4; ++m) _Pragma("unroll") for (int n = 0; n < 2; ++n) _Pragma("unroll") for (int k = 0; k < 2; ++k) \
;         acc[ai][bj][m][n] = __builtin_amdgcn_mfma_f32_16x16x32_bf16(Bt[n][k], At[m][k], acc[ai][bj][m][n], 0, 0, 0); __builtin_amdgcn_s_setprio(0); } while (0)
; #define PG8_WAIT_V(n) asm volatile("s_waitcnt vmcnt(" #n ")" ::: "memory")
; #define PG8_WAIT_L(n) asm volatile("s_waitcnt lgkmcnt(" #n ")" ::: "memory")
; #define PG8_BAR __builtin_amdgcn_s_barrier()
; #define PG8_SCHED __builtin_amdgcn_sched_barrier(0)
; template <class Epi, class Sched, bool ALIGN_EPI = false, bool SP2 = false>
; __device__ __forceinline__ void gemm_phase(PG8_LAS unsigned char* lds, const Gemm g, const Sched& S, const Epi& E) {
;     ...
;         for (int t = 0; t < nt; t += 2) {
;     ...
;             PG8_LDB(B0, 1, 0); PG8_LDB(B1, 1, 1); PG8_SCHED; PG8_LDA(At, 1, 0); PG8_STAGE(PG8_SA(0, 1), a2 + hstep, voffA);
;             PG8_WAIT_V(8); PG8_WAIT_L(0); PG8_BAR; PG8_MMA(0, 0, At, B0); PG8_MMA(0, 1, At, B1); PG8_BAR; PG8_SCHED;
;             PG8_LDA(At, 1, 1); PG8_STAGE(PG8_SB(1, 0), b3, voffB); PG8_STAGE(PG8_SB(1, 1), b3 + hstep, voffB); PG8_STAGE(PG8_SA(1, 0), a3, voffA);
;             PG8_WAIT_V(8); PG8_WAIT_L(0); PG8_BAR; PG8_MMA(1, 0, At, B0); PG8_MMA(1, 1, At, B1); PG8_BAR; PG8_SCHED;
	s_add_i32 s65, 0, 0x18000
	s_add_i32 s66, 0, 0x1c000
	v_add_u32_e32 v140, s65, v169
	v_add_u32_e32 v177, s66, v169
	ds_read_b128 v[128:131], v140
	ds_read_b128 v[132:135], v140 offset:1024
	ds_read_b128 v[136:139], v140 offset:2048
	ds_read_b128 v[140:143], v140 offset:3072
	ds_read_b128 v[160:163], v177
	ds_read_b128 v[178:181], v177 offset:1024
	ds_read_b128 v[182:185], v177 offset:2048
	ds_read_b128 v[186:189], v177 offset:3072
	s_add_u32 s40, s40, 0x40000
	s_addc_u32 s41, s41, 0
	s_mov_b32 m0, s45
	ds_read_b128 v[190:193], v175 offset:32768
	ds_read_b128 v[194:197], v175 offset:33792
	ds_read_b128 v[198:201], v175 offset:34816
	ds_read_b128 v[202:205], v175 offset:35840
	ds_read_b128 v[206:209], v175 offset:36864
	ds_read_b128 v[210:213], v175 offset:37888
	ds_read_b128 v[214:217], v175 offset:38912
	ds_read_b128 v[218:221], v175 offset:39936
	global_load_lds_dwordx4 v144, s[40:41]
	s_mov_b32 m0, s46
	s_nop 0
	global_load_lds_dwordx4 v148, s[40:41]
	s_waitcnt vmcnt(8)
	s_waitcnt lgkmcnt(0)
	s_barrier
	s_setprio 1
	s_waitcnt lgkmcnt(0)
	v_mfma_f32_16x16x32_bf16 v[124:127], v[128:131], v[190:193], v[124:127]
	v_mfma_f32_16x16x32_bf16 v[120:123], v[136:139], v[190:193], v[120:123]
	v_mfma_f32_16x16x32_bf16 v[108:111], v[128:131], v[198:201], v[108:111]
	v_mfma_f32_16x16x32_bf16 v[104:107], v[136:139], v[198:201], v[104:107]
	v_mfma_f32_16x16x32_bf16 v[92:95], v[128:131], v[206:209], v[92:95]
	v_mfma_f32_16x16x32_bf16 v[88:91], v[136:139], v[206:209], v[88:91]
	v_mfma_f32_16x16x32_bf16 v[76:79], v[128:131], v[214:217], v[76:79]
	v_mfma_f32_16x16x32_bf16 v[72:75], v[136:139], v[214:217], v[72:75]
	v_mfma_f32_16x16x32_bf16 v[124:127], v[132:135], v[194:197], v[124:127]
	v_mfma_f32_16x16x32_bf16 v[120:123], v[140:143], v[194:197], v[120:123]
	v_mfma_f32_16x16x32_bf16 v[108:111], v[132:135], v[202:205], v[108:111]
	v_mfma_f32_16x16x32_bf16 v[104:107], v[140:143], v[202:205], v[104:107]
	v_mfma_f32_16x16x32_bf16 v[92:95], v[132:135], v[210:213], v[92:95]
	v_mfma_f32_16x16x32_bf16 v[88:91], v[140:143], v[210:213], v[88:91]
	v_mfma_f32_16x16x32_bf16 v[76:79], v[132:135], v[218:221], v[76:79]
	v_mfma_f32_16x16x32_bf16 v[72:75], v[140:143], v[218:221], v[72:75]
	s_setprio 0
	s_setprio 1
	v_mfma_f32_16x16x32_bf16 v[116:119], v[160:163], v[190:193], v[116:119]
	v_mfma_f32_16x16x32_bf16 v[112:115], v[182:185], v[190:193], v[112:115]
	v_mfma_f32_16x16x32_bf16 v[100:103], v[160:163], v[198:201], v[100:103]
	v_mfma_f32_16x16x32_bf16 v[96:99], v[182:185], v[198:201], v[96:99]
	v_mfma_f32_16x16x32_bf16 v[84:87], v[160:163], v[206:209], v[84:87]
	v_mfma_f32_16x16x32_bf16 v[80:83], v[182:185], v[206:209], v[80:83]
	v_mfma_f32_16x16x32_bf16 v[68:71], v[160:163], v[214:217], v[68:71]
	v_mfma_f32_16x16x32_bf16 v[64:67], v[182:185], v[214:217], v[64:67]
	v_mfma_f32_16x16x32_bf16 v[116:119], v[178:181], v[194:197], v[116:119]
	v_mfma_f32_16x16x32_bf16 v[112:115], v[186:189], v[194:197], v[112:115]
	v_mfma_f32_16x16x32_bf16 v[100:103], v[178:181], v[202:205], v[100:103]
	v_mfma_f32_16x16x32_bf16 v[96:99], v[186:189], v[202:205], v[96:99]
	v_mfma_f32_16x16x32_bf16 v[84:87], v[178:181], v[210:213], v[84:87]
	v_mfma_f32_16x16x32_bf16 v[80:83], v[186:189], v[210:213], v[80:83]
	v_mfma_f32_16x16x32_bf16 v[68:71], v[178:181], v[218:221], v[68:71]
	v_mfma_f32_16x16x32_bf16 v[64:67], v[186:189], v[218:221], v[64:67]
	s_setprio 0
	s_barrier
	s_add_u32 s98, s40, 0xfffc0080
	s_addc_u32 s99, s41, -1
	s_add_u32 s100, s38, 0x80
	s_addc_u32 s101, s39, 0
	s_add_i32 s40, s65, s30
	s_mov_b32 m0, s40
	ds_read_b128 v[190:193], v175 offset:49152
	ds_read_b128 v[194:197], v175 offset:50176
	ds_read_b128 v[198:201], v175 offset:51200
	ds_read_b128 v[202:205], v175 offset:52224
	ds_read_b128 v[206:209], v175 offset:53248
	ds_read_b128 v[210:213], v175 offset:54272
	ds_read_b128 v[214:217], v175 offset:55296
	ds_read_b128 v[218:221], v175 offset:56320
	global_load_lds_dwordx4 v146, s[100:101]
	s_add_i32 m0, s40, 0x2000
	s_add_u32 s38, s38, 0x40080
	s_addc_u32 s39, s39, 0
	s_add_i32 s40, s66, s30
	global_load_lds_dwordx4 v150, s[100:101]
	s_mov_b32 m0, s40
	s_nop 0
	global_load_lds_dwordx4 v146, s[38:39]
	s_add_i32 m0, s40, 0x2000
	s_nop 0
	global_load_lds_dwordx4 v150, s[38:39]
	s_mov_b32 m0, s47
	s_nop 0
	global_load_lds_dwordx4 v144, s[98:99]
	s_mov_b32 m0, s48
	s_nop 0
	global_load_lds_dwordx4 v148, s[98:99]
	s_waitcnt vmcnt(8)
	s_waitcnt lgkmcnt(0)
	s_barrier
	s_setprio 1
	s_waitcnt lgkmcnt(0)
	v_mfma_f32_16x16x32_bf16 v[60:63], v[128:131], v[190:193], v[60:63]
	v_mfma_f32_16x16x32_bf16 v[56:59], v[136:139], v[190:193], v[56:59]
	v_mfma_f32_16x16x32_bf16 v[44:47], v[128:131], v[198:201], v[44:47]
	v_mfma_f32_16x16x32_bf16 v[40:43], v[136:139], v[198:201], v[40:43]
	v_mfma_f32_16x16x32_bf16 v[28:31], v[128:131], v[206:209], v[28:31]
	v_mfma_f32_16x16x32_bf16 v[24:27], v[136:139], v[206:209], v[24:27]
	v_mfma_f32_16x16x32_bf16 v[12:15], v[128:131], v[214:217], v[12:15]
	v_mfma_f32_16x16x32_bf16 v[8:11], v[136:139], v[214:217], v[8:11]
	v_mfma_f32_16x16x32_bf16 v[60:63], v[132:135], v[194:197], v[60:63]
	v_mfma_f32_16x16x32_bf16 v[56:59], v[140:143], v[194:197], v[56:59]
	v_mfma_f32_16x16x32_bf16 v[44:47], v[132:135], v[202:205], v[44:47]
	v_mfma_f32_16x16x32_bf16 v[40:43], v[140:143], v[202:205], v[40:43]
	v_mfma_f32_16x16x32_bf16 v[28:31], v[132:135], v[210:213], v[28:31]
	v_mfma_f32_16x16x32_bf16 v[24:27], v[140:143], v[210:213], v[24:27]
	v_mfma_f32_16x16x32_bf16 v[12:15], v[132:135], v[218:221], v[12:15]
	v_mfma_f32_16x16x32_bf16 v[8:11], v[140:143], v[218:221], v[8:11]
	s_setprio 0
	s_setprio 1
	v_mfma_f32_16x16x32_bf16 v[52:55], v[160:163], v[190:193], v[52:55]
	v_mfma_f32_16x16x32_bf16 v[48:51], v[182:185], v[190:193], v[48:51]
	v_mfma_f32_16x16x32_bf16 v[36:39], v[160:163], v[198:201], v[36:39]
	v_mfma_f32_16x16x32_bf16 v[32:35], v[182:185], v[198:201], v[32:35]
	v_mfma_f32_16x16x32_bf16 v[20:23], v[160:163], v[206:209], v[20:23]
	v_mfma_f32_16x16x32_bf16 v[16:19], v[182:185], v[206:209], v[16:19]
	v_mfma_f32_16x16x32_bf16 v[4:7], v[160:163], v[214:217], v[4:7]
	v_mfma_f32_16x16x32_bf16 v[0:3], v[182:185], v[214:217], v[0:3]
	v_mfma_f32_16x16x32_bf16 v[52:55], v[178:181], v[194:197], v[52:55]
	v_mfma_f32_16x16x32_bf16 v[48:51], v[186:189], v[194:197], v[48:51]
	v_mfma_f32_16x16x32_bf16 v[36:39], v[178:181], v[202:205], v[36:39]
	v_mfma_f32_16x16x32_bf16 v[32:35], v[186:189], v[202:205], v[32:35]
	v_mfma_f32_16x16x32_bf16 v[20:23], v[178:181], v[210:213], v[20:23]
	v_mfma_f32_16x16x32_bf16 v[16:19], v[186:189], v[210:213], v[16:19]
	v_mfma_f32_16x16x32_bf16 v[4:7], v[178:181], v[218:221], v[4:7]
	v_mfma_f32_16x16x32_bf16 v[0:3], v[186:189], v[218:221], v[0:3]
	s_setprio 0
	s_add_i32 s64, s64, 2
	s_add_u32 s36, s36, 0x100
	s_addc_u32 s37, s37, 0
	s_add_u32 s62, s62, 0x100
	s_addc_u32 s63, s63, 0
	s_cmp_gt_u32 s64, 13
	s_barrier
	s_cbranch_scc0 .LBB0_1556
	s_and_b64 vcc, exec, s[12:13]
	s_cbranch_vccz .LBB0_1559
	s_barrier

; #define PG8_STAGE(bufoff, gbase, voff) do { _Pragma("unroll") for (int _i = 0; _i < 2; ++_i) \
;         __builtin_amdgcn_global_load_lds((const unsigned*)((const char*)(gbase) + (voff)[_i]), (PG8_LAS unsigned*)(lds + (bufoff) + ldsw + _i * 8192), 16, 0, 0); } while (0)
; #define PG8_LDA(dst, b, h) do { _Pragma("unroll") for (int m = 0; m < 4; ++m) _Pragma("unroll") for (int k = 0; k < 2; ++k) dst[m][k] = *(const PG8_LAS bf16x8*)(lds + PG8_SA(b, h) + aoff + m * 2048 + k * 1024); } while (0)
; #define PG8_LDB(dst, b, h) do { _Pragma("unroll") for (int n = 0; n < 2; ++n) _Pragma("unroll") for (int k = 0; k < 2; ++k) dst[n][k] = *(const PG8_LAS bf16x8*)(lds + PG8_SB(b, h) + boff + n * 2048 + k * 1024); } while (0)
; #define PG8_MMA(ai, bj, At, Bt) do { __builtin_amdgcn_s_setprio(1); _Pragma("unroll") for (int m = 0; m < 4; ++m) _Pragma("unroll") for (int n = 0; n < 2; ++n) _Pragma("unroll") for (int k = 0; k < 2; ++k) \
;         acc[ai][bj][m][n] = __builtin_amdgcn_mfma_f32_16x16x32_bf16(Bt[n][k], At[m][k], acc[ai][bj][m][n], 0, 0, 0); __builtin_amdgcn_s_setprio(0); } while (0)
; #define PG8_WAIT_V(n) asm volatile("s_waitcnt vmcnt(" #n ")" ::: "memory")
; #define PG8_WAIT_L(n) asm volatile("s_waitcnt lgkmcnt(" #n ")" ::: "memory")
; template <class Epi, class Sched, bool ALIGN_EPI = false, bool SP2 = false>
; __device__ __forceinline__ void gemm_phase(PG8_LAS unsigned char* lds, const Gemm g, const Sched& S, const Epi& E) {
;     ...
;             const bool last = (t == nt - 2);
;             const char* a1 = cA + (size_t)(t + 1) * kstep;
;             const char* a2 = last ? nA : cA + (size_t)(t + 2) * kstep; const char* b2 = last ? nB : cB + (size_t)(t + 2) * kstep;
;             const char* a3 = a2 + kstep; const char* b3 = b2 + kstep;
;             if (last && has_next) S.a_ready(nxt);
;             if constexpr (SP2) {
;             PG8_LDB(B0, 0, 0); PG8_LDB(B1, 0, 1); PG8_SCHED; PG8_LDA(At, 0, 0); PG8_STAGE(PG8_SA(1, 1), a1 + hstep, voffA);
;             PG8_WAIT_V(8); PG8_WAIT_L(0); PG8_BAR; PG8_MMA(0, 0, At, B0); PG8_MMA(0, 1, At, B1); PG8_BAR; PG8_SCHED;
;             PG8_LDA(At, 0, 1); PG8_STAGE(PG8_SB(0, 0), b2, voffB); PG8_STAGE(PG8_SB(0, 1), b2 + hstep, voffB); PG8_STAGE(PG8_SA(0, 0), a2, voffA);
;             PG8_WAIT_V(8); PG8_WAIT_L(0); PG8_BAR; PG8_MMA(1, 0, At, B0); PG8_MMA(1, 1, At, B1); PG8_BAR; PG8_SCHED;
.LBB0_1641:
	ds_read_b128 v[144:147], v153
	ds_read_b128 v[156:159], v153 offset:1024
	ds_read_b128 v[160:163], v153 offset:2048
	ds_read_b128 v[164:167], v153 offset:3072
	ds_read_b128 v[168:171], v154
	ds_read_b128 v[172:175], v154 offset:1024
	ds_read_b128 v[176:179], v154 offset:2048
	ds_read_b128 v[180:183], v154 offset:3072
	s_add_u32 s30, s28, 0xfff00080
	s_addc_u32 s31, s29, -1
	s_cmp_eq_u32 s58, 60
	s_cselect_b32 s35, s21, s31
	s_cselect_b32 s34, s54, s30
	s_cselect_b32 s31, s19, s57
	s_cselect_b32 s30, s55, s56
	s_add_i32 m0, s39, 0xc000
	ds_read_b128 v[184:187], v155
	ds_read_b128 v[188:191], v155 offset:1024
	ds_read_b128 v[192:195], v155 offset:2048
	ds_read_b128 v[196:199], v155 offset:3072
	ds_read_b128 v[200:203], v155 offset:4096
	ds_read_b128 v[204:207], v155 offset:5120
	ds_read_b128 v[208:211], v155 offset:6144
	ds_read_b128 v[212:215], v155 offset:7168
	global_load_lds_dwordx4 v136, s[28:29]
	s_add_i32 m0, s39, 0xe000
	s_nop 0
	global_load_lds_dwordx4 v138, s[28:29]
	s_waitcnt vmcnt(8)
	s_waitcnt lgkmcnt(0)
	s_barrier
	s_setprio 1
	s_waitcnt lgkmcnt(0)
	v_mfma_f32_16x16x32_bf16 v[124:127], v[144:147], v[184:187], v[124:127]
	v_mfma_f32_16x16x32_bf16 v[120:123], v[160:163], v[184:187], v[120:123]
	v_mfma_f32_16x16x32_bf16 v[108:111], v[144:147], v[192:195], v[108:111]
	v_mfma_f32_16x16x32_bf16 v[104:107], v[160:163], v[192:195], v[104:107]
	v_mfma_f32_16x16x32_bf16 v[92:95], v[144:147], v[200:203], v[92:95]
	v_mfma_f32_16x16x32_bf16 v[88:91], v[160:163], v[200:203], v[88:91]
	v_mfma_f32_16x16x32_bf16 v[76:79], v[144:147], v[208:211], v[76:79]
	v_mfma_f32_16x16x32_bf16 v[72:75], v[160:163], v[208:211], v[72:75]
	v_mfma_f32_16x16x32_bf16 v[124:127], v[156:159], v[188:191], v[124:127]
	v_mfma_f32_16x16x32_bf16 v[120:123], v[164:167], v[188:191], v[120:123]
	v_mfma_f32_16x16x32_bf16 v[108:111], v[156:159], v[196:199], v[108:111]
	v_mfma_f32_16x16x32_bf16 v[104:107], v[164:167], v[196:199], v[104:107]
	v_mfma_f32_16x16x32_bf16 v[92:95], v[156:159], v[204:207], v[92:95]
	v_mfma_f32_16x16x32_bf16 v[88:91], v[164:167], v[204:207], v[88:91]
	v_mfma_f32_16x16x32_bf16 v[76:79], v[156:159], v[212:215], v[76:79]
	v_mfma_f32_16x16x32_bf16 v[72:75], v[164:167], v[212:215], v[72:75]
	s_setprio 0
	s_setprio 1
	v_mfma_f32_16x16x32_bf16 v[116:119], v[168:171], v[184:187], v[116:119]
	v_mfma_f32_16x16x32_bf16 v[112:115], v[176:179], v[184:187], v[112:115]
	v_mfma_f32_16x16x32_bf16 v[100:103], v[168:171], v[192:195], v[100:103]
	v_mfma_f32_16x16x32_bf16 v[96:99], v[176:179], v[192:195], v[96:99]
	v_mfma_f32_16x16x32_bf16 v[84:87], v[168:171], v[200:203], v[84:87]
	v_mfma_f32_16x16x32_bf16 v[80:83], v[176:179], v[200:203], v[80:83]
	v_mfma_f32_16x16x32_bf16 v[68:71], v[168:171], v[208:211], v[68:71]
	v_mfma_f32_16x16x32_bf16 v[64:67], v[176:179], v[208:211], v[64:67]
	v_mfma_f32_16x16x32_bf16 v[116:119], v[172:175], v[188:191], v[116:119]
	v_mfma_f32_16x16x32_bf16 v[112:115], v[180:183], v[188:191], v[112:115]
	v_mfma_f32_16x16x32_bf16 v[100:103], v[172:175], v[196:199], v[100:103]
	v_mfma_f32_16x16x32_bf16 v[96:99], v[180:183], v[196:199], v[96:99]
	v_mfma_f32_16x16x32_bf16 v[84:87], v[172:175], v[204:207], v[84:87]
	v_mfma_f32_16x16x32_bf16 v[80:83], v[180:183], v[204:207], v[80:83]
	v_mfma_f32_16x16x32_bf16 v[68:71], v[172:175], v[212:215], v[68:71]
	v_mfma_f32_16x16x32_bf16 v[64:67], v[180:183], v[212:215], v[64:67]
	s_setprio 0
	s_barrier
	s_add_i32 s59, s48, s38
	s_mov_b32 m0, s59
	ds_read_b128 v[184:187], v155 offset:16384
	ds_read_b128 v[188:191], v155 offset:17408
	ds_read_b128 v[192:195], v155 offset:18432
	ds_read_b128 v[196:199], v155 offset:19456
	ds_read_b128 v[200:203], v155 offset:20480
	ds_read_b128 v[204:207], v155 offset:21504
	ds_read_b128 v[208:211], v155 offset:22528
	ds_read_b128 v[212:215], v155 offset:23552
	global_load_lds_dwordx4 v130, s[30:31]
	s_add_i32 m0, s59, 0x2000
	s_add_u32 s60, s30, 0x100000
	s_addc_u32 s61, s31, 0
	s_add_i32 s59, s49, s38
	global_load_lds_dwordx4 v134, s[30:31]
	s_mov_b32 m0, s59
	s_nop 0
	global_load_lds_dwordx4 v130, s[60:61]
	s_add_i32 m0, s59, 0x2000
	s_nop 0
	global_load_lds_dwordx4 v134, s[60:61]
	s_mov_b32 m0, s39
	s_nop 0
	global_load_lds_dwordx4 v128, s[34:35]
	s_mov_b32 m0, s40
	s_nop 0
	global_load_lds_dwordx4 v132, s[34:35]
	s_waitcnt vmcnt(8)
	s_waitcnt lgkmcnt(0)
	s_barrier
	s_setprio 1
	s_waitcnt lgkmcnt(0)
	v_mfma_f32_16x16x32_bf16 v[60:63], v[144:147], v[184:187], v[60:63]
	v_mfma_f32_16x16x32_bf16 v[56:59], v[160:163], v[184:187], v[56:59]
	v_mfma_f32_16x16x32_bf16 v[44:47], v[144:147], v[192:195], v[44:47]
	v_mfma_f32_16x16x32_bf16 v[40:43], v[160:163], v[192:195], v[40:43]
	v_mfma_f32_16x16x32_bf16 v[28:31], v[144:147], v[200:203], v[28:31]
	v_mfma_f32_16x16x32_bf16 v[24:27], v[160:163], v[200:203], v[24:27]
	v_mfma_f32_16x16x32_bf16 v[12:15], v[144:147], v[208:211], v[12:15]
	v_mfma_f32_16x16x32_bf16 v[8:11], v[160:163], v[208:211], v[8:11]
	v_mfma_f32_16x16x32_bf16 v[60:63], v[156:159], v[188:191], v[60:63]
	v_mfma_f32_16x16x32_bf16 v[56:59], v[164:167], v[188:191], v[56:59]
	v_mfma_f32_16x16x32_bf16 v[44:47], v[156:159], v[196:199], v[44:47]
	v_mfma_f32_16x16x32_bf16 v[40:43], v[164:167], v[196:199], v[40:43]
	v_mfma_f32_16x16x32_bf16 v[28:31], v[156:159], v[204:207], v[28:31]
	v_mfma_f32_16x16x32_bf16 v[24:27], v[164:167], v[204:207], v[24:27]
	v_mfma_f32_16x16x32_bf16 v[12:15], v[156:159], v[212:215], v[12:15]
	v_mfma_f32_16x16x32_bf16 v[8:11], v[164:167], v[212:215], v[8:11]
	s_setprio 0
	s_setprio 1
	v_mfma_f32_16x16x32_bf16 v[52:55], v[168:171], v[184:187], v[52:55]
	v_mfma_f32_16x16x32_bf16 v[48:51], v[176:179], v[184:187], v[48:51]
	v_mfma_f32_16x16x32_bf16 v[36:39], v[168:171], v[192:195], v[36:39]
	v_mfma_f32_16x16x32_bf16 v[32:35], v[176:179], v[192:195], v[32:35]
	v_mfma_f32_16x16x32_bf16 v[20:23], v[168:171], v[200:203], v[20:23]
	v_mfma_f32_16x16x32_bf16 v[16:19], v[176:179], v[200:203], v[16:19]
	v_mfma_f32_16x16x32_bf16 v[4:7], v[168:171], v[208:211], v[4:7]
	v_mfma_f32_16x16x32_bf16 v[0:3], v[176:179], v[208:211], v[0:3]
	v_mfma_f32_16x16x32_bf16 v[52:55], v[172:175], v[188:191], v[52:55]
	v_mfma_f32_16x16x32_bf16 v[48:51], v[180:183], v[188:191], v[48:51]
	v_mfma_f32_16x16x32_bf16 v[36:39], v[172:175], v[196:199], v[36:39]
	v_mfma_f32_16x16x32_bf16 v[32:35], v[180:183], v[196:199], v[32:35]
	v_mfma_f32_16x16x32_bf16 v[20:23], v[172:175], v[204:207], v[20:23]
	v_mfma_f32_16x16x32_bf16 v[16:19], v[180:183], v[204:207], v[16:19]
	v_mfma_f32_16x16x32_bf16 v[4:7], v[172:175], v[212:215], v[4:7]
	v_mfma_f32_16x16x32_bf16 v[0:3], v[180:183], v[212:215], v[0:3]
	s_setprio 0
	s_barrier
; #define PG8_STAGE(bufoff, gbase, voff) do { _Pragma("unroll") for (int _i = 0; _i < 2; ++_i) \
;         __builtin_amdgcn_global_load_lds((const unsigned*)((const char*)(gbase) + (voff)[_i]), (PG8_LAS unsigned*)(lds + (bufoff) + ldsw + _i * 8192), 16, 0, 0); } while (0)
; #define PG8_LDA(dst, b, h) do { _Pragma("unroll") for (int m = 0; m < 4; ++m) _Pragma("unroll") for (int k = 0; k < 2; ++k) dst[m][k] = *(const PG8_LAS bf16x8*)(lds + PG8_SA(b, h) + aoff + m * 2048 + k * 1024); } while (0)
; #define PG8_LDB(dst, b, h) do { _Pragma("unroll") for (int n = 0; n < 2; ++n) _Pragma("unroll") for (int k = 0; k < 2; ++k) dst[n][k] = *(const PG8_LAS bf16x8*)(lds + PG8_SB(b, h) + boff + n * 2048 + k * 1024); } while (0)
; #define PG8_MMA(ai, bj, At, Bt) do { __builtin_amdgcn_s_setprio(1); _Pragma("unroll") for (int m = 0; m < 4; ++m) _Pragma("unroll") for (int n = 0; n < 2; ++n) _Pragma("unroll") for (int k = 0; k < 2; ++k) \
;         acc[ai][bj][m][n] = __builtin_amdgcn_mfma_f32_16x16x32_bf16(Bt[n][k], At[m][k], acc[ai][bj][m][n], 0, 0, 0); __builtin_amdgcn_s_setprio(0); } while (0)
; #define PG8_WAIT_V(n) asm volatile("s_waitcnt vmcnt(" #n ")" ::: "memory")
; #define PG8_WAIT_L(n) asm volatile("s_waitcnt lgkmcnt(" #n ")" ::: "memory")
; #define PG8_BAR __builtin_amdgcn_s_barrier()
; #define PG8_SCHED __builtin_amdgcn_sched_barrier(0)
; template <class Epi, class Sched, bool ALIGN_EPI = false, bool SP2 = false>
; __device__ __forceinline__ void gemm_phase(PG8_LAS unsigned char* lds, const Gemm g, const Sched& S, const Epi& E) {
;     ...
;             PG8_LDB(B0, 1, 0); PG8_LDB(B1, 1, 1); PG8_SCHED; PG8_LDA(At, 1, 0); PG8_STAGE(PG8_SA(0, 1), a2 + hstep, voffA);
;             PG8_WAIT_V(8); PG8_WAIT_L(0); PG8_BAR; PG8_MMA(0, 0, At, B0); PG8_MMA(0, 1, At, B1); PG8_BAR; PG8_SCHED;
	s_add_i32 s59, 0, 0x18000
	s_add_i32 s60, 0, 0x1c000
	v_add_u32_e32 v164, s59, v151
	v_add_u32_e32 v180, s60, v151
	ds_read_b128 v[144:147], v164
	ds_read_b128 v[156:159], v164 offset:1024
	ds_read_b128 v[160:163], v164 offset:2048
	ds_read_b128 v[164:167], v164 offset:3072
	ds_read_b128 v[168:171], v180
	ds_read_b128 v[172:175], v180 offset:1024
	ds_read_b128 v[176:179], v180 offset:2048
	ds_read_b128 v[180:183], v180 offset:3072
	s_add_u32 s34, s34, 0x100000
	s_addc_u32 s35, s35, 0
	s_mov_b32 m0, s41
	ds_read_b128 v[184:187], v155 offset:32768
	ds_read_b128 v[188:191], v155 offset:33792
	ds_read_b128 v[192:195], v155 offset:34816
	ds_read_b128 v[196:199], v155 offset:35840
	ds_read_b128 v[200:203], v155 offset:36864
	ds_read_b128 v[204:207], v155 offset:37888
	ds_read_b128 v[208:211], v155 offset:38912
	ds_read_b128 v[212:215], v155 offset:39936
	global_load_lds_dwordx4 v128, s[34:35]
	s_mov_b32 m0, s42
	s_nop 0
	global_load_lds_dwordx4 v132, s[34:35]
	s_waitcnt vmcnt(8)
	s_waitcnt lgkmcnt(0)
	s_barrier
	s_setprio 1
	s_waitcnt lgkmcnt(0)
	v_mfma_f32_16x16x32_bf16 v[124:127], v[144:147], v[184:187], v[124:127]
	v_mfma_f32_16x16x32_bf16 v[120:123], v[160:163], v[184:187], v[120:123]
	v_mfma_f32_16x16x32_bf16 v[108:111], v[144:147], v[192:195], v[108:111]
	v_mfma_f32_16x16x32_bf16 v[104:107], v[160:163], v[192:195], v[104:107]
	v_mfma_f32_16x16x32_bf16 v[92:95], v[144:147], v[200:203], v[92:95]
	v_mfma_f32_16x16x32_bf16 v[88:91], v[160:163], v[200:203], v[88:91]
	v_mfma_f32_16x16x32_bf16 v[76:79], v[144:147], v[208:211], v[76:79]
	v_mfma_f32_16x16x32_bf16 v[72:75], v[160:163], v[208:211], v[72:75]
	v_mfma_f32_16x16x32_bf16 v[124:127], v[156:159], v[188:191], v[124:127]
	v_mfma_f32_16x16x32_bf16 v[120:123], v[164:167], v[188:191], v[120:123]
	v_mfma_f32_16x16x32_bf16 v[108:111], v[156:159], v[196:199], v[108:111]
	v_mfma_f32_16x16x32_bf16 v[104:107], v[164:167], v[196:199], v[104:107]
	v_mfma_f32_16x16x32_bf16 v[92:95], v[156:159], v[204:207], v[92:95]
	v_mfma_f32_16x16x32_bf16 v[88:91], v[164:167], v[204:207], v[88:91]
	v_mfma_f32_16x16x32_bf16 v[76:79], v[156:159], v[212:215], v[76:79]
	v_mfma_f32_16x16x32_bf16 v[72:75], v[164:167], v[212:215], v[72:75]
	s_setprio 0
	s_setprio 1
	v_mfma_f32_16x16x32_bf16 v[116:119], v[168:171], v[184:187], v[116:119]
	v_mfma_f32_16x16x32_bf16 v[112:115], v[176:179], v[184:187], v[112:115]
	v_mfma_f32_16x16x32_bf16 v[100:103], v[168:171], v[192:195], v[100:103]
	v_mfma_f32_16x16x32_bf16 v[96:99], v[176:179], v[192:195], v[96:99]
	v_mfma_f32_16x16x32_bf16 v[84:87], v[168:171], v[200:203], v[84:87]
	v_mfma_f32_16x16x32_bf16 v[80:83], v[176:179], v[200:203], v[80:83]
	v_mfma_f32_16x16x32_bf16 v[68:71], v[168:171], v[208:211], v[68:71]
	v_mfma_f32_16x16x32_bf16 v[64:67], v[176:179], v[208:211], v[64:67]
	v_mfma_f32_16x16x32_bf16 v[116:119], v[172:175], v[188:191], v[116:119]
	v_mfma_f32_16x16x32_bf16 v[112:115], v[180:183], v[188:191], v[112:115]
	v_mfma_f32_16x16x32_bf16 v[100:103], v[172:175], v[196:199], v[100:103]
	v_mfma_f32_16x16x32_bf16 v[96:99], v[180:183], v[196:199], v[96:99]
	v_mfma_f32_16x16x32_bf16 v[84:87], v[172:175], v[204:207], v[84:87]
	v_mfma_f32_16x16x32_bf16 v[80:83], v[180:183], v[204:207], v[80:83]
	v_mfma_f32_16x16x32_bf16 v[68:71], v[172:175], v[212:215], v[68:71]
	v_mfma_f32_16x16x32_bf16 v[64:67], v[180:183], v[212:215], v[64:67]
	s_setprio 0
	s_barrier
; #define PG8_STAGE(bufoff, gbase, voff) do { _Pragma("unroll") for (int _i = 0; _i < 2; ++_i) \
;         __builtin_amdgcn_global_load_lds((const unsigned*)((const char*)(gbase) + (voff)[_i]), (PG8_LAS unsigned*)(lds + (bufoff) + ldsw + _i * 8192), 16, 0, 0); } while (0)
; #define PG8_LDA(dst, b, h) do { _Pragma("unroll") for (int m = 0; m < 4; ++m) _Pragma("unroll") for (int k = 0; k < 2; ++k) dst[m][k] = *(const PG8_LAS bf16x8*)(lds + PG8_SA(b, h) + aoff + m * 2048 + k * 1024); } while (0)
; #define PG8_MMA(ai, bj, At, Bt) do { __builtin_amdgcn_s_setprio(1); _Pragma("unroll") for (int m = 0; m < 4; ++m) _Pragma("unroll") for (int n = 0; n < 2; ++n) _Pragma("unroll") for (int k = 0; k < 2; ++k) \
;         acc[ai][bj][m][n] = __builtin_amdgcn_mfma_f32_16x16x32_bf16(Bt[n][k], At[m][k], acc[ai][bj][m][n], 0, 0, 0); __builtin_amdgcn_s_setprio(0); } while (0)
; #define PG8_WAIT_V(n) asm volatile("s_waitcnt vmcnt(" #n ")" ::: "memory")
; #define PG8_WAIT_L(n) asm volatile("s_waitcnt lgkmcnt(" #n ")" ::: "memory")
; #define PG8_BAR __builtin_amdgcn_s_barrier()
; #define PG8_SCHED __builtin_amdgcn_sched_barrier(0)
; template <class Epi, class Sched, bool ALIGN_EPI = false, bool SP2 = false>
; __device__ __forceinline__ void gemm_phase(PG8_LAS unsigned char* lds, const Gemm g, const Sched& S, const Epi& E) {
;     ...
;         for (int t = 0; t < nt; t += 2) {
;     ...
;             PG8_LDA(At, 1, 1); PG8_STAGE(PG8_SB(1, 0), b3, voffB); PG8_STAGE(PG8_SB(1, 1), b3 + hstep, voffB); PG8_STAGE(PG8_SA(1, 0), a3, voffA);
;             PG8_WAIT_V(8); PG8_WAIT_L(0); PG8_BAR; PG8_MMA(1, 0, At, B0); PG8_MMA(1, 1, At, B1); PG8_BAR; PG8_SCHED;
;     ...
;         if constexpr (ALIGN_EPI) { if (wr == 0) PG8_BAR; }
	s_add_u32 s98, s34, 0xfff00080
	s_addc_u32 s99, s35, -1
	s_add_u32 s100, s30, 0x80
	s_addc_u32 s101, s31, 0
	s_add_i32 s34, s59, s38
	s_mov_b32 m0, s34
	ds_read_b128 v[184:187], v155 offset:49152
	ds_read_b128 v[188:191], v155 offset:50176
	ds_read_b128 v[192:195], v155 offset:51200
	ds_read_b128 v[196:199], v155 offset:52224
	ds_read_b128 v[200:203], v155 offset:53248
	ds_read_b128 v[204:207], v155 offset:54272
	ds_read_b128 v[208:211], v155 offset:55296
	ds_read_b128 v[212:215], v155 offset:56320
	global_load_lds_dwordx4 v130, s[100:101]
	s_add_i32 m0, s34, 0x2000
	s_add_u32 s30, s30, 0x100080
	s_addc_u32 s31, s31, 0
	s_add_i32 s34, s60, s38
	global_load_lds_dwordx4 v134, s[100:101]
	s_mov_b32 m0, s34
	s_nop 0
	global_load_lds_dwordx4 v130, s[30:31]
	s_add_i32 m0, s34, 0x2000
	s_nop 0
	global_load_lds_dwordx4 v134, s[30:31]
	s_mov_b32 m0, s44
	s_nop 0
	global_load_lds_dwordx4 v128, s[98:99]
	s_mov_b32 m0, s45
	s_nop 0
	global_load_lds_dwordx4 v132, s[98:99]
	s_waitcnt vmcnt(8)
	s_waitcnt lgkmcnt(0)
	s_barrier
	s_setprio 1
	s_waitcnt lgkmcnt(0)
	v_mfma_f32_16x16x32_bf16 v[60:63], v[144:147], v[184:187], v[60:63]
	v_mfma_f32_16x16x32_bf16 v[56:59], v[160:163], v[184:187], v[56:59]
	v_mfma_f32_16x16x32_bf16 v[44:47], v[144:147], v[192:195], v[44:47]
	v_mfma_f32_16x16x32_bf16 v[40:43], v[160:163], v[192:195], v[40:43]
	v_mfma_f32_16x16x32_bf16 v[28:31], v[144:147], v[200:203], v[28:31]
	v_mfma_f32_16x16x32_bf16 v[24:27], v[160:163], v[200:203], v[24:27]
	v_mfma_f32_16x16x32_bf16 v[12:15], v[144:147], v[208:211], v[12:15]
	v_mfma_f32_16x16x32_bf16 v[8:11], v[160:163], v[208:211], v[8:11]
	v_mfma_f32_16x16x32_bf16 v[60:63], v[156:159], v[188:191], v[60:63]
	v_mfma_f32_16x16x32_bf16 v[56:59], v[164:167], v[188:191], v[56:59]
	v_mfma_f32_16x16x32_bf16 v[44:47], v[156:159], v[196:199], v[44:47]
	v_mfma_f32_16x16x32_bf16 v[40:43], v[164:167], v[196:199], v[40:43]
	v_mfma_f32_16x16x32_bf16 v[28:31], v[156:159], v[204:207], v[28:31]
	v_mfma_f32_16x16x32_bf16 v[24:27], v[164:167], v[204:207], v[24:27]
	v_mfma_f32_16x16x32_bf16 v[12:15], v[156:159], v[212:215], v[12:15]
	v_mfma_f32_16x16x32_bf16 v[8:11], v[164:167], v[212:215], v[8:11]
	s_setprio 0
	s_setprio 1
	v_mfma_f32_16x16x32_bf16 v[52:55], v[168:171], v[184:187], v[52:55]
	v_mfma_f32_16x16x32_bf16 v[48:51], v[176:179], v[184:187], v[48:51]
	v_mfma_f32_16x16x32_bf16 v[36:39], v[168:171], v[192:195], v[36:39]
	v_mfma_f32_16x16x32_bf16 v[32:35], v[176:179], v[192:195], v[32:35]
	v_mfma_f32_16x16x32_bf16 v[20:23], v[168:171], v[200:203], v[20:23]
	v_mfma_f32_16x16x32_bf16 v[16:19], v[176:179], v[200:203], v[16:19]
	v_mfma_f32_16x16x32_bf16 v[4:7], v[168:171], v[208:211], v[4:7]
	v_mfma_f32_16x16x32_bf16 v[0:3], v[176:179], v[208:211], v[0:3]
	v_mfma_f32_16x16x32_bf16 v[52:55], v[172:175], v[188:191], v[52:55]
	v_mfma_f32_16x16x32_bf16 v[48:51], v[180:183], v[188:191], v[48:51]
	v_mfma_f32_16x16x32_bf16 v[36:39], v[172:175], v[196:199], v[36:39]
	v_mfma_f32_16x16x32_bf16 v[32:35], v[180:183], v[196:199], v[32:35]
	v_mfma_f32_16x16x32_bf16 v[20:23], v[172:175], v[204:207], v[20:23]
	v_mfma_f32_16x16x32_bf16 v[16:19], v[180:183], v[204:207], v[16:19]
	v_mfma_f32_16x16x32_bf16 v[4:7], v[172:175], v[212:215], v[4:7]
	v_mfma_f32_16x16x32_bf16 v[0:3], v[180:183], v[212:215], v[0:3]
	s_setprio 0
	s_add_i32 s58, s58, 2
	s_add_u32 s28, s28, 0x100
	s_addc_u32 s29, s29, 0
	s_add_u32 s56, s56, 0x100
	s_addc_u32 s57, s57, 0
	s_cmp_gt_u32 s58, 61
	s_barrier
	s_cbranch_scc0 .LBB0_1641
	v_mbcnt_lo_u32_b32 v234, -1, 0
	v_mbcnt_hi_u32_b32 v234, -1, v234
	v_bfe_u32 v234, v234, 3, 1
	v_sub_u32_e32 v231, 0, v234
	v_and_b32_e32 v230, 0xffff8010, v231
	v_and_b32_e32 v235, 0x7ff0, v231
	v_sub_u32_e32 v244, 0x8000, v235
	v_mov_b32_e32 v245, 0
	s_mov_b32 s98, 0xff00ff
	s_mov_b32 s99, 0xff00ff
	s_and_b64 vcc, exec, s[8:9]
	s_cbranch_vccz .LBB0_1644
	s_barrier
